# hand-written attnC key-tile body (two query tiles interleaved, permlane max, lazy rescale), attnA merge loads batched, phase-0 loads batched
# speedup vs baseline: 1.1039x; 1.0169x over previous
; #define LAS __attribute__((address_space(3)))
; __device__ __forceinline__ void hy_filter(const Args& a, int L, int order, int c, LAS unsigned char* lds) {
;     ...
;     LAS float* tmp = (LAS float*)(lds + 66048);
;     LAS float* red = (LAS float*)(lds + 66048 + 16384);
;     const float* raw = (const float*)(a.ws + WS_HRAW) + (size_t)L * 2048 * 1024 + order * 512 + c;
;     float s = 0.f;
;     for (int i = tid; i < 4096; i += 512) {
;         float v;
;         if (i < 2048) v = raw[(size_t)i * 1024];
;         else if (i == 2048) v = 0.f;
;         else v = raw[(size_t)(4096 - i) * 1024 + 256];
;         tmp[i] = v; s += fabsf(v);
;     }
.LBB0_170:
	v_mov_b32_e32 v0, v225
	s_waitcnt lgkmcnt(0)
	s_barrier
	s_ashr_i32 s19, s18, 31
	v_cmp_gt_i32_e32 vcc, s52, v0
	v_mov_b32_e32 v1, 0
	s_and_saveexec_b64 s[0:1], vcc
	s_cbranch_execz .LBB0_180
	s_lshl_b64 s[2:3], s[18:19], 2
	s_add_u32 s2, s39, s2
	s_addc_u32 s3, s40, s3
	v_lshlrev_b32_e32 v2, 12, v0
	global_load_dword v8, v2, s[4:5]
	v_add_u32_e32 v3, 0x200000, v2
	global_load_dword v9, v3, s[4:5]
	v_add_u32_e32 v3, 0x400000, v2
	global_load_dword v10, v3, s[4:5]
	v_add_u32_e32 v3, 0x600000, v2
	global_load_dword v11, v3, s[4:5]
	v_sub_u32_e32 v3, 0x800400, v2
	global_load_dword v12, v3, s[2:3]
	v_sub_u32_e32 v3, 0x600400, v2
	global_load_dword v13, v3, s[2:3]
	v_sub_u32_e32 v3, 0x400400, v2
	global_load_dword v14, v3, s[2:3]
	v_sub_u32_e32 v3, 0x200400, v2
	global_load_dword v15, v3, s[2:3]
	v_cmp_eq_u32_e32 vcc, 0, v0
	v_lshl_add_u32 v4, v0, 2, s53
	v_mov_b32_e32 v1, 0
	s_waitcnt vmcnt(0)
	v_cndmask_b32_e64 v12, v12, 0, vcc
	ds_write_b32 v4, v8
	v_add_f32_e64 v1, v1, |v8|
	ds_write_b32 v4, v9 offset:2048
	v_add_f32_e64 v1, v1, |v9|
	ds_write_b32 v4, v10 offset:4096
	v_add_f32_e64 v1, v1, |v10|
	ds_write_b32 v4, v11 offset:6144
	v_add_f32_e64 v1, v1, |v11|
	ds_write_b32 v4, v12 offset:8192
	v_add_f32_e64 v1, v1, |v12|
	ds_write_b32 v4, v13 offset:10240
	v_add_f32_e64 v1, v1, |v13|
	ds_write_b32 v4, v14 offset:12288
	v_add_f32_e64 v1, v1, |v14|
	ds_write_b32 v4, v15 offset:14336
	v_add_f32_e64 v1, v1, |v15|
	s_mov_b64 s[20:21], exec

; #define LAS __attribute__((address_space(3)))
; __device__ __forceinline__ void hy_filter(const Args& a, int L, int order, int c, LAS unsigned char* lds) {
;     ...
;     LAS float* tmp = (LAS float*)(lds + 66048);
;     LAS float* red = (LAS float*)(lds + 66048 + 16384);
;     const float* raw = (const float*)(a.ws + WS_HRAW) + (size_t)L * 2048 * 1024 + order * 512 + c;
;     float s = 0.f;
;     for (int i = tid; i < 4096; i += 512) {
;         float v;
;         if (i < 2048) v = raw[(size_t)i * 1024];
;         else if (i == 2048) v = 0.f;
;         else v = raw[(size_t)(4096 - i) * 1024 + 256];
;         tmp[i] = v; s += fabsf(v);
;     }
.LBB0_191:
	v_mov_b32_e32 v0, v225
	s_barrier
	v_mov_b32_e32 v1, 0
	v_cmp_gt_i32_e32 vcc, s52, v0
	s_and_saveexec_b64 s[22:23], vcc
	s_cbranch_execz .LBB0_201
	s_lshl_b64 s[24:25], s[18:19], 2
	s_add_u32 s24, s43, s24
	s_addc_u32 s25, s44, s25
	v_lshlrev_b32_e32 v2, 12, v0
	global_load_dword v8, v2, s[12:13]
	v_add_u32_e32 v3, 0x200000, v2
	global_load_dword v9, v3, s[12:13]
	v_add_u32_e32 v3, 0x400000, v2
	global_load_dword v10, v3, s[12:13]
	v_add_u32_e32 v3, 0x600000, v2
	global_load_dword v11, v3, s[12:13]
	v_sub_u32_e32 v3, 0x800400, v2
	global_load_dword v12, v3, s[24:25]
	v_sub_u32_e32 v3, 0x600400, v2
	global_load_dword v13, v3, s[24:25]
	v_sub_u32_e32 v3, 0x400400, v2
	global_load_dword v14, v3, s[24:25]
	v_sub_u32_e32 v3, 0x200400, v2
	global_load_dword v15, v3, s[24:25]
	v_cmp_eq_u32_e32 vcc, 0, v0
	v_lshl_add_u32 v4, v0, 2, s53
	v_mov_b32_e32 v1, 0
	s_waitcnt vmcnt(0)
	v_cndmask_b32_e64 v12, v12, 0, vcc
	ds_write_b32 v4, v8
	v_add_f32_e64 v1, v1, |v8|
	ds_write_b32 v4, v9 offset:2048
	v_add_f32_e64 v1, v1, |v9|
	ds_write_b32 v4, v10 offset:4096
	v_add_f32_e64 v1, v1, |v10|
	ds_write_b32 v4, v11 offset:6144
	v_add_f32_e64 v1, v1, |v11|
	ds_write_b32 v4, v12 offset:8192
	v_add_f32_e64 v1, v1, |v12|
	ds_write_b32 v4, v13 offset:10240
	v_add_f32_e64 v1, v1, |v13|
	ds_write_b32 v4, v14 offset:12288
	v_add_f32_e64 v1, v1, |v14|
	ds_write_b32 v4, v15 offset:14336
	v_add_f32_e64 v1, v1, |v15|
	s_mov_b64 s[26:27], exec

; #define LAS __attribute__((address_space(3)))
; __device__ __forceinline__ float fexp2(float x) { return __builtin_amdgcn_exp2f(x); }
; template <bool KLDS>
; __device__ __forceinline__ void attn_step(const bf16x8 (&kf)[4], LAS const unsigned char* kb, const bf16x8 (&vf)[2][2], const bf16x8 (&qf)[4], f32x16& o0, f32x16& o1, float& m, float& l, int lane, int maskmode) {
;     const int ql = lane & 31, h = lane >> 5;
;     f32x16 S;
; #pragma unroll
;     for (int i = 0; i < 16; ++i) S[i] = 0.f;
; #pragma unroll
;     for (int s = 0; s < 4; ++s) {
;         if (KLDS) { const int pc = (2 * s + h) ^ ((ql >> 1) & 7); const bf16x8 k1 = *(const LAS bf16x8*)(kb + ql * 128 + pc * 16); S = __builtin_amdgcn_mfma_f32_32x32x16_bf16(k1, qf[s], S, 0, 0, 0); }
;         else S = __builtin_amdgcn_mfma_f32_32x32x16_bf16(kf[s], qf[s], S, 0, 0, 0);
;     }
;     if (maskmode) {
; #pragma unroll
;         for (int i = 0; i < 16; ++i) { const int kr = (i & 3) + 8 * (i >> 2) + 4 * h; const bool ok = (maskmode == 1) ? (kr >= ql) : (kr <= ql); S[i] = ok ? S[i] : -1e30f; }
;     }
;     float tm = S[0];
; #pragma unroll
;     for (int i = 1; i < 16; ++i) tm = fmaxf(tm, S[i]);
;     tm = fmaxf(tm, __shfl_xor(tm, 32));
;     const float mn = fmaxf(m, tm), al = fexp2(m - mn); m = mn;
;     float ps = 0.f;
; #pragma unroll
;     for (int i = 0; i < 16; ++i) { S[i] = fexp2(S[i] - mn); ps += S[i]; }
;     l = l * al + ps;
; #pragma unroll
;     for (int i = 0; i < 16; ++i) { o0[i] *= al; o1[i] *= al; }
; __device__ __forceinline__ void attnC_unit(const Args& a, int unit, LAS unsigned char* lds) {
;     ...
;             bf16x8 kf[4], vf[2][2];
;             load_kf(cur + j * 4096, kf, lane); load_vf(cur + 8192 + j * 4096, vf, lane);
; #pragma unroll
;             for (int e = 0; e < 2; ++e) attn_step<false>(kf, cur, vf, qf[e], o0[e], o1[e], m[e], l[e], lane, 0);
.LBB0_254:
	v_readfirstlane_b32 s5, v225
	s_add_i32 s4, s2, 0xffffc000
	s_and_b32 s4, s4, 0x4000
	v_add_u32_e32 v64, s4, v252
	v_add_u32_e32 v124, v64, v231
	v_add_u32_e32 v123, v64, v239
	v_add_u32_e32 v121, v64, v232
	v_add_u32_e32 v120, v64, v241
	v_add3_u32 v122, s4, v157, v156
	s_addk_i32 s2, 0x4000
	s_add_i32 s3, s3, 1
	v_lshl_add_u64 v[180:181], v[180:181], 0, s[18:19]
	s_mov_b32 s9, 0x41000000
	ds_read_b128 v[126:129], v124
	ds_read_b128 v[130:133], v123
	ds_read_b128 v[138:141], v121
	ds_read_b128 v[142:145], v120
	ds_read_b64_tr_b16 v[146:147], v122 offset:8192
	ds_read_b64_tr_b16 v[148:149], v122 offset:9216
	ds_read_b64_tr_b16 v[204:205], v122 offset:8256
	ds_read_b64_tr_b16 v[206:207], v122 offset:9280
	ds_read_b64_tr_b16 v[208:209], v122 offset:10240
	ds_read_b64_tr_b16 v[210:211], v122 offset:11264
	ds_read_b64_tr_b16 v[212:213], v122 offset:10304
	ds_read_b64_tr_b16 v[214:215], v122 offset:11328
	s_waitcnt lgkmcnt(11)
	v_mfma_f32_32x32x16_bf16 v[64:79], v[126:129], v[80:83], 0
	v_mfma_f32_32x32x16_bf16 v[158:173], v[126:129], v[96:99], 0
	s_waitcnt lgkmcnt(10)
	v_mfma_f32_32x32x16_bf16 v[64:79], v[130:133], v[84:87], v[64:79]
	v_mfma_f32_32x32x16_bf16 v[158:173], v[130:133], v[100:103], v[158:173]
	s_waitcnt lgkmcnt(9)
	v_mfma_f32_32x32x16_bf16 v[64:79], v[138:141], v[88:91], v[64:79]
	v_mfma_f32_32x32x16_bf16 v[158:173], v[138:141], v[104:107], v[158:173]
	s_waitcnt lgkmcnt(8)
	v_mfma_f32_32x32x16_bf16 v[64:79], v[142:145], v[92:95], v[64:79]
	v_mfma_f32_32x32x16_bf16 v[158:173], v[142:145], v[108:111], v[158:173]
	s_nop 10
	v_max3_f32 v152, v64, v65, v66
	v_max3_f32 v150, v158, v159, v160
	v_max3_f32 v152, v152, v67, v68
	v_max3_f32 v150, v150, v161, v162
	v_max3_f32 v152, v152, v69, v70
	v_max3_f32 v150, v150, v163, v164
	v_max3_f32 v152, v152, v71, v72
	v_max3_f32 v150, v150, v165, v166
	v_max3_f32 v152, v152, v73, v74
	v_max3_f32 v150, v150, v167, v168
	v_max3_f32 v152, v152, v75, v76
	v_max3_f32 v150, v150, v169, v170
	v_max3_f32 v152, v152, v77, v78
	v_max3_f32 v150, v150, v171, v172
	v_max_f32_e32 v152, v152, v79
	v_max_f32_e32 v150, v150, v173
	v_mov_b32_e32 v153, v152
	v_mov_b32_e32 v151, v150
	s_nop 1
	s_nop 1
	v_permlane32_swap_b32_e32 v153, v152
	v_permlane32_swap_b32_e32 v151, v150
	v_max_f32_e32 v152, v152, v153
	v_max_f32_e32 v150, v150, v151
	v_sub_f32_e32 v153, v152, v235
	v_sub_f32_e32 v151, v150, v136
	v_cmp_lt_f32_e64 s[10:11], s9, v153
	v_cmp_lt_f32_e64 s[4:5], s9, v151
	s_nop 0
	s_nop 0
	v_cndmask_b32_e64 v202, v235, v152, s[10:11]
	v_cndmask_b32_e64 v200, v136, v150, s[4:5]
	v_sub_f32_e32 v154, v235, v202
	v_sub_f32_e32 v174, v136, v200
	v_exp_f32_e32 v154, v154
	v_exp_f32_e32 v174, v174
	v_pk_add_f32 v[64:65], v[64:65], v[202:203] op_sel_hi:[1,0] neg_lo:[0,1] neg_hi:[0,1]
	v_pk_add_f32 v[158:159], v[158:159], v[200:201] op_sel_hi:[1,0] neg_lo:[0,1] neg_hi:[0,1]
	v_pk_add_f32 v[66:67], v[66:67], v[202:203] op_sel_hi:[1,0] neg_lo:[0,1] neg_hi:[0,1]
	v_pk_add_f32 v[160:161], v[160:161], v[200:201] op_sel_hi:[1,0] neg_lo:[0,1] neg_hi:[0,1]
	v_pk_add_f32 v[68:69], v[68:69], v[202:203] op_sel_hi:[1,0] neg_lo:[0,1] neg_hi:[0,1]
	v_pk_add_f32 v[162:163], v[162:163], v[200:201] op_sel_hi:[1,0] neg_lo:[0,1] neg_hi:[0,1]
	v_pk_add_f32 v[70:71], v[70:71], v[202:203] op_sel_hi:[1,0] neg_lo:[0,1] neg_hi:[0,1]
	v_pk_add_f32 v[164:165], v[164:165], v[200:201] op_sel_hi:[1,0] neg_lo:[0,1] neg_hi:[0,1]
	v_pk_add_f32 v[72:73], v[72:73], v[202:203] op_sel_hi:[1,0] neg_lo:[0,1] neg_hi:[0,1]
	v_pk_add_f32 v[166:167], v[166:167], v[200:201] op_sel_hi:[1,0] neg_lo:[0,1] neg_hi:[0,1]
	v_pk_add_f32 v[74:75], v[74:75], v[202:203] op_sel_hi:[1,0] neg_lo:[0,1] neg_hi:[0,1]
	v_pk_add_f32 v[168:169], v[168:169], v[200:201] op_sel_hi:[1,0] neg_lo:[0,1] neg_hi:[0,1]
	v_pk_add_f32 v[76:77], v[76:77], v[202:203] op_sel_hi:[1,0] neg_lo:[0,1] neg_hi:[0,1]
	v_pk_add_f32 v[170:171], v[170:171], v[200:201] op_sel_hi:[1,0] neg_lo:[0,1] neg_hi:[0,1]
	v_pk_add_f32 v[78:79], v[78:79], v[202:203] op_sel_hi:[1,0] neg_lo:[0,1] neg_hi:[0,1]
	v_pk_add_f32 v[172:173], v[172:173], v[200:201] op_sel_hi:[1,0] neg_lo:[0,1] neg_hi:[0,1]
	v_mov_b32_e32 v235, v202
	v_mov_b32_e32 v136, v200
	v_exp_f32_e32 v64, v64
	v_exp_f32_e32 v158, v158
	v_exp_f32_e32 v65, v65
	v_exp_f32_e32 v159, v159
	v_exp_f32_e32 v66, v66
	v_exp_f32_e32 v160, v160
	v_exp_f32_e32 v67, v67
	v_exp_f32_e32 v161, v161
	v_exp_f32_e32 v68, v68
	v_exp_f32_e32 v162, v162
	v_exp_f32_e32 v69, v69
	v_exp_f32_e32 v163, v163
	v_exp_f32_e32 v70, v70
	v_exp_f32_e32 v164, v164
	v_exp_f32_e32 v71, v71
	v_exp_f32_e32 v165, v165
	v_exp_f32_e32 v72, v72
	v_exp_f32_e32 v166, v166
	v_exp_f32_e32 v73, v73
	v_exp_f32_e32 v167, v167
	v_exp_f32_e32 v74, v74
	v_exp_f32_e32 v168, v168
	v_exp_f32_e32 v75, v75
	v_exp_f32_e32 v169, v169
	v_exp_f32_e32 v76, v76
	v_exp_f32_e32 v170, v170
	v_exp_f32_e32 v77, v77
	v_exp_f32_e32 v171, v171
	v_exp_f32_e32 v78, v78
	v_exp_f32_e32 v172, v172
	v_exp_f32_e32 v79, v79
	v_exp_f32_e32 v173, v173
	v_pk_add_f32 v[182:183], v[64:65], v[66:67]
	v_pk_add_f32 v[190:191], v[158:159], v[160:161]
	v_pk_add_f32 v[184:185], v[68:69], v[70:71]
	v_pk_add_f32 v[192:193], v[162:163], v[164:165]
	v_pk_add_f32 v[186:187], v[72:73], v[74:75]
	v_pk_add_f32 v[194:195], v[166:167], v[168:169]
	v_pk_add_f32 v[188:189], v[76:77], v[78:79]
	v_pk_add_f32 v[196:197], v[170:171], v[172:173]
	v_pk_add_f32 v[182:183], v[182:183], v[184:185]
	v_pk_add_f32 v[190:191], v[190:191], v[192:193]
	v_pk_add_f32 v[186:187], v[186:187], v[188:189]
	v_pk_add_f32 v[194:195], v[194:195], v[196:197]
	v_pk_add_f32 v[182:183], v[182:183], v[186:187]
	v_pk_add_f32 v[190:191], v[190:191], v[194:195]
	v_add_f32_e32 v182, v182, v183
	v_add_f32_e32 v190, v190, v191
	v_fma_f32 v179, v179, v154, v182
	v_fma_f32 v178, v178, v174, v190
	v_cmp_neq_f32_e32 vcc, 1.0, v154
	s_cbranch_vccz .LaC_nr00
	v_pk_mul_f32 v[48:49], v[48:49], v[154:155] op_sel_hi:[1,0]
	v_pk_mul_f32 v[50:51], v[50:51], v[154:155] op_sel_hi:[1,0]
	v_pk_mul_f32 v[52:53], v[52:53], v[154:155] op_sel_hi:[1,0]
	v_pk_mul_f32 v[54:55], v[54:55], v[154:155] op_sel_hi:[1,0]
	v_pk_mul_f32 v[56:57], v[56:57], v[154:155] op_sel_hi:[1,0]
	v_pk_mul_f32 v[58:59], v[58:59], v[154:155] op_sel_hi:[1,0]
	v_pk_mul_f32 v[60:61], v[60:61], v[154:155] op_sel_hi:[1,0]
	v_pk_mul_f32 v[62:63], v[62:63], v[154:155] op_sel_hi:[1,0]
	v_pk_mul_f32 v[32:33], v[32:33], v[154:155] op_sel_hi:[1,0]
	v_pk_mul_f32 v[34:35], v[34:35], v[154:155] op_sel_hi:[1,0]
	v_pk_mul_f32 v[36:37], v[36:37], v[154:155] op_sel_hi:[1,0]
	v_pk_mul_f32 v[38:39], v[38:39], v[154:155] op_sel_hi:[1,0]
	v_pk_mul_f32 v[40:41], v[40:41], v[154:155] op_sel_hi:[1,0]
	v_pk_mul_f32 v[42:43], v[42:43], v[154:155] op_sel_hi:[1,0]
	v_pk_mul_f32 v[44:45], v[44:45], v[154:155] op_sel_hi:[1,0]
	v_pk_mul_f32 v[46:47], v[46:47], v[154:155] op_sel_hi:[1,0]
; __device__ __forceinline__ unsigned pk2n(float lo, float hi) { const f32x2v v = {lo, hi}; const bf16v2 b = __builtin_convertvector(v, bf16v2); return __builtin_bit_cast(unsigned, b); }
; __device__ __forceinline__ float fexp2(float x) { return __builtin_amdgcn_exp2f(x); }
; template <bool KLDS>
; __device__ __forceinline__ void attn_step(const bf16x8 (&kf)[4], LAS const unsigned char* kb, const bf16x8 (&vf)[2][2], const bf16x8 (&qf)[4], f32x16& o0, f32x16& o1, float& m, float& l, int lane, int maskmode) {
;     ...
; #pragma unroll
;     for (int i = 0; i < 16; ++i) { S[i] = fexp2(S[i] - mn); ps += S[i]; }
;     l = l * al + ps;
; #pragma unroll
;     for (int i = 0; i < 16; ++i) { o0[i] *= al; o1[i] *= al; }
;     bf16x8 pf[2];
; #pragma unroll
;     for (int s2 = 0; s2 < 2; ++s2) {
;         u32x4 w; w.x = pk2n(S[8 * s2 + 0], S[8 * s2 + 1]); w.y = pk2n(S[8 * s2 + 2], S[8 * s2 + 3]); w.z = pk2n(S[8 * s2 + 4], S[8 * s2 + 5]); w.w = pk2n(S[8 * s2 + 6], S[8 * s2 + 7]);
;         pf[s2] = __builtin_bit_cast(bf16x8, w);
;     }
; #pragma unroll
;     for (int s2 = 0; s2 < 2; ++s2) {
;         o0 = __builtin_amdgcn_mfma_f32_32x32x16_bf16(vf[s2][0], pf[s2], o0, 0, 0, 0);
;         o1 = __builtin_amdgcn_mfma_f32_32x32x16_bf16(vf[s2][1], pf[s2], o1, 0, 0, 0);
;     }
; __device__ __forceinline__ void attnC_unit(const Args& a, int unit, LAS unsigned char* lds) {
;     ...
;             bf16x8 kf[4], vf[2][2];
;             load_kf(cur + j * 4096, kf, lane); load_vf(cur + 8192 + j * 4096, vf, lane);
; #pragma unroll
;             for (int e = 0; e < 2; ++e) attn_step<false>(kf, cur, vf, qf[e], o0[e], o1[e], m[e], l[e], lane, 0);
.LaC_nr00:
	v_cmp_neq_f32_e32 vcc, 1.0, v174
	s_cbranch_vccz .LaC_nr01
	v_pk_mul_f32 v[16:17], v[16:17], v[174:175] op_sel_hi:[1,0]
	v_pk_mul_f32 v[18:19], v[18:19], v[174:175] op_sel_hi:[1,0]
	v_pk_mul_f32 v[20:21], v[20:21], v[174:175] op_sel_hi:[1,0]
	v_pk_mul_f32 v[22:23], v[22:23], v[174:175] op_sel_hi:[1,0]
	v_pk_mul_f32 v[24:25], v[24:25], v[174:175] op_sel_hi:[1,0]
	v_pk_mul_f32 v[26:27], v[26:27], v[174:175] op_sel_hi:[1,0]
	v_pk_mul_f32 v[28:29], v[28:29], v[174:175] op_sel_hi:[1,0]
	v_pk_mul_f32 v[30:31], v[30:31], v[174:175] op_sel_hi:[1,0]
	v_pk_mul_f32 v[0:1], v[0:1], v[174:175] op_sel_hi:[1,0]
	v_pk_mul_f32 v[2:3], v[2:3], v[174:175] op_sel_hi:[1,0]
	v_pk_mul_f32 v[4:5], v[4:5], v[174:175] op_sel_hi:[1,0]
	v_pk_mul_f32 v[6:7], v[6:7], v[174:175] op_sel_hi:[1,0]
	v_pk_mul_f32 v[8:9], v[8:9], v[174:175] op_sel_hi:[1,0]
	v_pk_mul_f32 v[10:11], v[10:11], v[174:175] op_sel_hi:[1,0]
	v_pk_mul_f32 v[12:13], v[12:13], v[174:175] op_sel_hi:[1,0]
	v_pk_mul_f32 v[14:15], v[14:15], v[174:175] op_sel_hi:[1,0]
.LaC_nr01:
	v_cvt_pk_bf16_f32 v64, v64, v65
	v_cvt_pk_bf16_f32 v158, v158, v159
	v_cvt_pk_bf16_f32 v65, v66, v67
	v_cvt_pk_bf16_f32 v159, v160, v161
	v_cvt_pk_bf16_f32 v66, v68, v69
	v_cvt_pk_bf16_f32 v160, v162, v163
	v_cvt_pk_bf16_f32 v67, v70, v71
	v_cvt_pk_bf16_f32 v161, v164, v165
	v_cvt_pk_bf16_f32 v68, v72, v73
	v_cvt_pk_bf16_f32 v162, v166, v167
	v_cvt_pk_bf16_f32 v69, v74, v75
	v_cvt_pk_bf16_f32 v163, v168, v169
	v_cvt_pk_bf16_f32 v70, v76, v77
	v_cvt_pk_bf16_f32 v164, v170, v171
	v_cvt_pk_bf16_f32 v71, v78, v79
	v_cvt_pk_bf16_f32 v165, v172, v173
	s_waitcnt lgkmcnt(0)
	v_mfma_f32_32x32x16_bf16 v[48:63], v[146:149], v[64:67], v[48:63]
	v_mfma_f32_32x32x16_bf16 v[16:31], v[146:149], v[158:161], v[16:31]
	v_mfma_f32_32x32x16_bf16 v[32:47], v[204:207], v[64:67], v[32:47]
	v_mfma_f32_32x32x16_bf16 v[0:15], v[204:207], v[158:161], v[0:15]
	v_mfma_f32_32x32x16_bf16 v[48:63], v[208:211], v[68:71], v[48:63]
	v_mfma_f32_32x32x16_bf16 v[16:31], v[208:211], v[162:165], v[16:31]
	v_mfma_f32_32x32x16_bf16 v[32:47], v[212:215], v[68:71], v[32:47]
	v_mfma_f32_32x32x16_bf16 v[0:15], v[212:215], v[162:165], v[0:15]
	ds_read_b128 v[126:129], v124 offset:4096
	ds_read_b128 v[130:133], v123 offset:4096
	ds_read_b128 v[138:141], v121 offset:4096
	ds_read_b128 v[142:145], v120 offset:4096
	ds_read_b64_tr_b16 v[146:147], v122 offset:12288
	ds_read_b64_tr_b16 v[148:149], v122 offset:13312
	ds_read_b64_tr_b16 v[204:205], v122 offset:12352
	ds_read_b64_tr_b16 v[206:207], v122 offset:13376
	ds_read_b64_tr_b16 v[208:209], v122 offset:14336
	ds_read_b64_tr_b16 v[210:211], v122 offset:15360
	ds_read_b64_tr_b16 v[212:213], v122 offset:14400
	ds_read_b64_tr_b16 v[214:215], v122 offset:15424
	s_waitcnt lgkmcnt(11)
	v_mfma_f32_32x32x16_bf16 v[64:79], v[126:129], v[80:83], 0
	v_mfma_f32_32x32x16_bf16 v[158:173], v[126:129], v[96:99], 0
	s_waitcnt lgkmcnt(10)
	v_mfma_f32_32x32x16_bf16 v[64:79], v[130:133], v[84:87], v[64:79]
	v_mfma_f32_32x32x16_bf16 v[158:173], v[130:133], v[100:103], v[158:173]
	s_waitcnt lgkmcnt(9)
	v_mfma_f32_32x32x16_bf16 v[64:79], v[138:141], v[88:91], v[64:79]
	v_mfma_f32_32x32x16_bf16 v[158:173], v[138:141], v[104:107], v[158:173]
	s_waitcnt lgkmcnt(8)
; #define LAS __attribute__((address_space(3)))
; __device__ __forceinline__ float fexp2(float x) { return __builtin_amdgcn_exp2f(x); }
; template <bool KLDS>
; __device__ __forceinline__ void attn_step(const bf16x8 (&kf)[4], LAS const unsigned char* kb, const bf16x8 (&vf)[2][2], const bf16x8 (&qf)[4], f32x16& o0, f32x16& o1, float& m, float& l, int lane, int maskmode) {
;     const int ql = lane & 31, h = lane >> 5;
;     f32x16 S;
; #pragma unroll
;     for (int i = 0; i < 16; ++i) S[i] = 0.f;
; #pragma unroll
;     for (int s = 0; s < 4; ++s) {
;         if (KLDS) { const int pc = (2 * s + h) ^ ((ql >> 1) & 7); const bf16x8 k1 = *(const LAS bf16x8*)(kb + ql * 128 + pc * 16); S = __builtin_amdgcn_mfma_f32_32x32x16_bf16(k1, qf[s], S, 0, 0, 0); }
;         else S = __builtin_amdgcn_mfma_f32_32x32x16_bf16(kf[s], qf[s], S, 0, 0, 0);
;     }
;     if (maskmode) {
; #pragma unroll
;         for (int i = 0; i < 16; ++i) { const int kr = (i & 3) + 8 * (i >> 2) + 4 * h; const bool ok = (maskmode == 1) ? (kr >= ql) : (kr <= ql); S[i] = ok ? S[i] : -1e30f; }
;     }
;     float tm = S[0];
; #pragma unroll
;     for (int i = 1; i < 16; ++i) tm = fmaxf(tm, S[i]);
;     tm = fmaxf(tm, __shfl_xor(tm, 32));
;     const float mn = fmaxf(m, tm), al = fexp2(m - mn); m = mn;
;     float ps = 0.f;
; #pragma unroll
;     for (int i = 0; i < 16; ++i) { S[i] = fexp2(S[i] - mn); ps += S[i]; }
;     l = l * al + ps;
; #pragma unroll
;     for (int i = 0; i < 16; ++i) { o0[i] *= al; o1[i] *= al; }
	v_mfma_f32_32x32x16_bf16 v[64:79], v[142:145], v[92:95], v[64:79]
	v_mfma_f32_32x32x16_bf16 v[158:173], v[142:145], v[108:111], v[158:173]
	s_nop 10
	v_max3_f32 v152, v64, v65, v66
	v_max3_f32 v150, v158, v159, v160
	v_max3_f32 v152, v152, v67, v68
	v_max3_f32 v150, v150, v161, v162
	v_max3_f32 v152, v152, v69, v70
	v_max3_f32 v150, v150, v163, v164
	v_max3_f32 v152, v152, v71, v72
	v_max3_f32 v150, v150, v165, v166
	v_max3_f32 v152, v152, v73, v74
	v_max3_f32 v150, v150, v167, v168
	v_max3_f32 v152, v152, v75, v76
	v_max3_f32 v150, v150, v169, v170
	v_max3_f32 v152, v152, v77, v78
	v_max3_f32 v150, v150, v171, v172
	v_max_f32_e32 v152, v152, v79
	v_max_f32_e32 v150, v150, v173
	v_mov_b32_e32 v153, v152
	v_mov_b32_e32 v151, v150
	s_nop 1
	s_nop 1
	v_permlane32_swap_b32_e32 v153, v152
	v_permlane32_swap_b32_e32 v151, v150
	v_max_f32_e32 v152, v152, v153
	v_max_f32_e32 v150, v150, v151
	v_sub_f32_e32 v153, v152, v235
	v_sub_f32_e32 v151, v150, v136
	v_cmp_lt_f32_e64 s[10:11], s9, v153
	v_cmp_lt_f32_e64 s[4:5], s9, v151
	s_nop 0
	s_nop 0
	v_cndmask_b32_e64 v202, v235, v152, s[10:11]
	v_cndmask_b32_e64 v200, v136, v150, s[4:5]
	v_sub_f32_e32 v154, v235, v202
	v_sub_f32_e32 v174, v136, v200
	v_exp_f32_e32 v154, v154
	v_exp_f32_e32 v174, v174
	v_pk_add_f32 v[64:65], v[64:65], v[202:203] op_sel_hi:[1,0] neg_lo:[0,1] neg_hi:[0,1]
	v_pk_add_f32 v[158:159], v[158:159], v[200:201] op_sel_hi:[1,0] neg_lo:[0,1] neg_hi:[0,1]
	v_pk_add_f32 v[66:67], v[66:67], v[202:203] op_sel_hi:[1,0] neg_lo:[0,1] neg_hi:[0,1]
	v_pk_add_f32 v[160:161], v[160:161], v[200:201] op_sel_hi:[1,0] neg_lo:[0,1] neg_hi:[0,1]
	v_pk_add_f32 v[68:69], v[68:69], v[202:203] op_sel_hi:[1,0] neg_lo:[0,1] neg_hi:[0,1]
	v_pk_add_f32 v[162:163], v[162:163], v[200:201] op_sel_hi:[1,0] neg_lo:[0,1] neg_hi:[0,1]
	v_pk_add_f32 v[70:71], v[70:71], v[202:203] op_sel_hi:[1,0] neg_lo:[0,1] neg_hi:[0,1]
	v_pk_add_f32 v[164:165], v[164:165], v[200:201] op_sel_hi:[1,0] neg_lo:[0,1] neg_hi:[0,1]
	v_pk_add_f32 v[72:73], v[72:73], v[202:203] op_sel_hi:[1,0] neg_lo:[0,1] neg_hi:[0,1]
	v_pk_add_f32 v[166:167], v[166:167], v[200:201] op_sel_hi:[1,0] neg_lo:[0,1] neg_hi:[0,1]
	v_pk_add_f32 v[74:75], v[74:75], v[202:203] op_sel_hi:[1,0] neg_lo:[0,1] neg_hi:[0,1]
	v_pk_add_f32 v[168:169], v[168:169], v[200:201] op_sel_hi:[1,0] neg_lo:[0,1] neg_hi:[0,1]
	v_pk_add_f32 v[76:77], v[76:77], v[202:203] op_sel_hi:[1,0] neg_lo:[0,1] neg_hi:[0,1]
	v_pk_add_f32 v[170:171], v[170:171], v[200:201] op_sel_hi:[1,0] neg_lo:[0,1] neg_hi:[0,1]
	v_pk_add_f32 v[78:79], v[78:79], v[202:203] op_sel_hi:[1,0] neg_lo:[0,1] neg_hi:[0,1]
	v_pk_add_f32 v[172:173], v[172:173], v[200:201] op_sel_hi:[1,0] neg_lo:[0,1] neg_hi:[0,1]
	v_mov_b32_e32 v235, v202
	v_mov_b32_e32 v136, v200
	v_exp_f32_e32 v64, v64
	v_exp_f32_e32 v158, v158
	v_exp_f32_e32 v65, v65
	v_exp_f32_e32 v159, v159
	v_exp_f32_e32 v66, v66
	v_exp_f32_e32 v160, v160
	v_exp_f32_e32 v67, v67
	v_exp_f32_e32 v161, v161
	v_exp_f32_e32 v68, v68
	v_exp_f32_e32 v162, v162
	v_exp_f32_e32 v69, v69
	v_exp_f32_e32 v163, v163
	v_exp_f32_e32 v70, v70
	v_exp_f32_e32 v164, v164
	v_exp_f32_e32 v71, v71
	v_exp_f32_e32 v165, v165
	v_exp_f32_e32 v72, v72
	v_exp_f32_e32 v166, v166
	v_exp_f32_e32 v73, v73
	v_exp_f32_e32 v167, v167
	v_exp_f32_e32 v74, v74
	v_exp_f32_e32 v168, v168
	v_exp_f32_e32 v75, v75
	v_exp_f32_e32 v169, v169
	v_exp_f32_e32 v76, v76
	v_exp_f32_e32 v170, v170
	v_exp_f32_e32 v77, v77
	v_exp_f32_e32 v171, v171
	v_exp_f32_e32 v78, v78
	v_exp_f32_e32 v172, v172
	v_exp_f32_e32 v79, v79
	v_exp_f32_e32 v173, v173
	v_pk_add_f32 v[182:183], v[64:65], v[66:67]
	v_pk_add_f32 v[190:191], v[158:159], v[160:161]
	v_pk_add_f32 v[184:185], v[68:69], v[70:71]
	v_pk_add_f32 v[192:193], v[162:163], v[164:165]
	v_pk_add_f32 v[186:187], v[72:73], v[74:75]
	v_pk_add_f32 v[194:195], v[166:167], v[168:169]
	v_pk_add_f32 v[188:189], v[76:77], v[78:79]
	v_pk_add_f32 v[196:197], v[170:171], v[172:173]
	v_pk_add_f32 v[182:183], v[182:183], v[184:185]
	v_pk_add_f32 v[190:191], v[190:191], v[192:193]
	v_pk_add_f32 v[186:187], v[186:187], v[188:189]
	v_pk_add_f32 v[194:195], v[194:195], v[196:197]
	v_pk_add_f32 v[182:183], v[182:183], v[186:187]
	v_pk_add_f32 v[190:191], v[190:191], v[194:195]
	v_add_f32_e32 v182, v182, v183
	v_add_f32_e32 v190, v190, v191
	v_fma_f32 v179, v179, v154, v182
	v_fma_f32 v178, v178, v174, v190
	v_cmp_neq_f32_e32 vcc, 1.0, v154
	s_cbranch_vccz .LaC_nr10
	v_pk_mul_f32 v[48:49], v[48:49], v[154:155] op_sel_hi:[1,0]
	v_pk_mul_f32 v[50:51], v[50:51], v[154:155] op_sel_hi:[1,0]
	v_pk_mul_f32 v[52:53], v[52:53], v[154:155] op_sel_hi:[1,0]
	v_pk_mul_f32 v[54:55], v[54:55], v[154:155] op_sel_hi:[1,0]
	v_pk_mul_f32 v[56:57], v[56:57], v[154:155] op_sel_hi:[1,0]
	v_pk_mul_f32 v[58:59], v[58:59], v[154:155] op_sel_hi:[1,0]
	v_pk_mul_f32 v[60:61], v[60:61], v[154:155] op_sel_hi:[1,0]
	v_pk_mul_f32 v[62:63], v[62:63], v[154:155] op_sel_hi:[1,0]
	v_pk_mul_f32 v[32:33], v[32:33], v[154:155] op_sel_hi:[1,0]
	v_pk_mul_f32 v[34:35], v[34:35], v[154:155] op_sel_hi:[1,0]
	v_pk_mul_f32 v[36:37], v[36:37], v[154:155] op_sel_hi:[1,0]
	v_pk_mul_f32 v[38:39], v[38:39], v[154:155] op_sel_hi:[1,0]
	v_pk_mul_f32 v[40:41], v[40:41], v[154:155] op_sel_hi:[1,0]
	v_pk_mul_f32 v[42:43], v[42:43], v[154:155] op_sel_hi:[1,0]
	v_pk_mul_f32 v[44:45], v[44:45], v[154:155] op_sel_hi:[1,0]
	v_pk_mul_f32 v[46:47], v[46:47], v[154:155] op_sel_hi:[1,0]

; __device__ __forceinline__ unsigned pk2n(float lo, float hi) { const f32x2v v = {lo, hi}; const bf16v2 b = __builtin_convertvector(v, bf16v2); return __builtin_bit_cast(unsigned, b); }
; template <bool KLDS>
; __device__ __forceinline__ void attn_step(const bf16x8 (&kf)[4], LAS const unsigned char* kb, const bf16x8 (&vf)[2][2], const bf16x8 (&qf)[4], f32x16& o0, f32x16& o1, float& m, float& l, int lane, int maskmode) {
;     ...
;     bf16x8 pf[2];
; #pragma unroll
;     for (int s2 = 0; s2 < 2; ++s2) {
;         u32x4 w; w.x = pk2n(S[8 * s2 + 0], S[8 * s2 + 1]); w.y = pk2n(S[8 * s2 + 2], S[8 * s2 + 3]); w.z = pk2n(S[8 * s2 + 4], S[8 * s2 + 5]); w.w = pk2n(S[8 * s2 + 6], S[8 * s2 + 7]);
;         pf[s2] = __builtin_bit_cast(bf16x8, w);
;     }
; #pragma unroll
;     for (int s2 = 0; s2 < 2; ++s2) {
;         o0 = __builtin_amdgcn_mfma_f32_32x32x16_bf16(vf[s2][0], pf[s2], o0, 0, 0, 0);
;         o1 = __builtin_amdgcn_mfma_f32_32x32x16_bf16(vf[s2][1], pf[s2], o1, 0, 0, 0);
;     }
.LaC_nr11:
	v_cvt_pk_bf16_f32 v64, v64, v65
	v_cvt_pk_bf16_f32 v158, v158, v159
	v_cvt_pk_bf16_f32 v65, v66, v67
	v_cvt_pk_bf16_f32 v159, v160, v161
	v_cvt_pk_bf16_f32 v66, v68, v69
	v_cvt_pk_bf16_f32 v160, v162, v163
	v_cvt_pk_bf16_f32 v67, v70, v71
	v_cvt_pk_bf16_f32 v161, v164, v165
	v_cvt_pk_bf16_f32 v68, v72, v73
	v_cvt_pk_bf16_f32 v162, v166, v167
	v_cvt_pk_bf16_f32 v69, v74, v75
	v_cvt_pk_bf16_f32 v163, v168, v169
	v_cvt_pk_bf16_f32 v70, v76, v77
	v_cvt_pk_bf16_f32 v164, v170, v171
	v_cvt_pk_bf16_f32 v71, v78, v79
	v_cvt_pk_bf16_f32 v165, v172, v173
	s_waitcnt lgkmcnt(0)
	s_barrier
	v_mfma_f32_32x32x16_bf16 v[48:63], v[146:149], v[64:67], v[48:63]
	v_mfma_f32_32x32x16_bf16 v[16:31], v[146:149], v[158:161], v[16:31]
	v_mfma_f32_32x32x16_bf16 v[32:47], v[204:207], v[64:67], v[32:47]
	v_mfma_f32_32x32x16_bf16 v[0:15], v[204:207], v[158:161], v[0:15]
	v_mfma_f32_32x32x16_bf16 v[48:63], v[208:211], v[68:71], v[48:63]
	v_mfma_f32_32x32x16_bf16 v[16:31], v[208:211], v[162:165], v[16:31]
	v_mfma_f32_32x32x16_bf16 v[32:47], v[212:215], v[68:71], v[32:47]
	v_mfma_f32_32x32x16_bf16 v[0:15], v[212:215], v[162:165], v[0:15]
	s_cmp_lg_u32 s2, 0x84000
	s_cbranch_scc0 .LBB0_252

; __device__ __forceinline__ unsigned pk2(float lo, float hi) { unsigned r; asm("v_cvt_pk_bf16_f32 %0, %1, %2" : "=v"(r) : "v"(lo), "v"(hi)); return r; }
; __device__ __forceinline__ float bflo(unsigned w) { return __uint_as_float(w << 16); }
; __device__ __forceinline__ float bfhi(unsigned w) { return __uint_as_float(w & 0xffff0000u); }
; __device__ __forceinline__ float fexp2(float x) { return __builtin_amdgcn_exp2f(x); }
; __device__ __forceinline__ void attnA_unit(const Args& a, int unit, LAS unsigned char* lds) {
;     ...
;                 const float l1 = LSE[tokg * 6 + hh], l2 = LSE[((size_t)MTOK + tokg) * 6 + hh];
;                 const float mx = fmaxf(lse, fmaxf(l1, l2));
;                 const float w1 = fexp2(l1 - mx), w2 = fexp2(l2 - mx), w3 = fexp2(lse - mx);
;                 const float wi = 1.0f / (w1 + w2 + w3);
;                 const float c1 = w1 * wi, c2 = w2 * wi, c3 = w3 * wi * inv;
;                 const bf16_t* p1 = OA + tokg * 384 + 64 * hh; const bf16_t* p2 = OA + ((size_t)MTOK + tokg) * 384 + 64 * hh;
;                 bf16_t* op = MIX + tokg * DM + 64 * hh;
; #pragma unroll
;                 for (int dt = 0; dt < 2; ++dt)
; #pragma unroll
;                     for (int g = 0; g < 4; ++g) {
;                         const f32x16& o = dt ? o1 : o0;
;                         const int d = 32 * dt + 8 * g + 4 * h;
;                         const u32x2 a1 = *(const u32x2*)(p1 + d), a2 = *(const u32x2*)(p2 + d);
;                         const float r0 = c1 * bflo(a1.x) + c2 * bflo(a2.x) + c3 * o[4 * g], r1 = c1 * bfhi(a1.x) + c2 * bfhi(a2.x) + c3 * o[4 * g + 1];
;                         const float r2 = c1 * bflo(a1.y) + c2 * bflo(a2.y) + c3 * o[4 * g + 2], r3 = c1 * bfhi(a1.y) + c2 * bfhi(a2.y) + c3 * o[4 * g + 3];
;                         u32x2 w; w.x = pk2(r0, r1); w.y = pk2(r2, r3);
;                         *(u32x2*)(op + d) = w;
;                     }
.LBB0_283:
	v_mad_u64_u32 v[34:35], s[0:1], v122, 24, s[88:89]
	v_mad_i32_i24 v35, v123, 24, v35
	global_load_dword v32, v[34:35], off
	v_add_co_u32_e32 v34, vcc, 0x180000, v34
	s_movk_i32 s74, 0x300
	s_nop 0
	v_addc_co_u32_e32 v35, vcc, 0, v35, vcc
	global_load_dword v34, v[34:35], off
	v_mov_b64_e32 v[160:161], s[94:95]
	v_mad_u64_u32 v[160:161], s[0:1], v122, s74, v[160:161]
	v_mad_i32_i24 v161, v123, s74, v161
	v_lshl_add_u64 v[160:161], v[160:161], 0, v[154:155]
	s_mov_b64 s[0:1], 0x3000000
	v_lshl_add_u64 v[162:163], v[160:161], 0, s[0:1]
	global_load_dwordx2 v[164:165], v[160:161], off
	global_load_dwordx2 v[166:167], v[160:161], off offset:16
	global_load_dwordx2 v[168:169], v[160:161], off offset:32
	global_load_dwordx2 v[170:171], v[160:161], off offset:48
	global_load_dwordx2 v[172:173], v[160:161], off offset:64
	global_load_dwordx2 v[174:175], v[160:161], off offset:80
	global_load_dwordx2 v[176:177], v[160:161], off offset:96
	global_load_dwordx2 v[178:179], v[160:161], off offset:112
	global_load_dwordx2 v[180:181], v[162:163], off
	global_load_dwordx2 v[182:183], v[162:163], off offset:16
	global_load_dwordx2 v[184:185], v[162:163], off offset:32
	global_load_dwordx2 v[186:187], v[162:163], off offset:48
	global_load_dwordx2 v[188:189], v[162:163], off offset:64
	global_load_dwordx2 v[190:191], v[162:163], off offset:80
	global_load_dwordx2 v[192:193], v[162:163], off offset:96
	global_load_dwordx2 v[194:195], v[162:163], off offset:112
	v_lshlrev_b64 v[40:41], 11, v[122:123]
	s_waitcnt vmcnt(0)
	v_max3_f32 v35, v36, v32, v34
	v_sub_f32_e32 v32, v32, v35
	v_sub_f32_e32 v34, v34, v35
	v_exp_f32_e32 v32, v32
	v_exp_f32_e32 v45, v34
	v_sub_f32_e32 v34, v36, v35
	v_exp_f32_e32 v47, v34
	v_add_f32_e32 v34, v32, v45
	v_add_f32_e32 v49, v47, v34
	v_mov_b64_e32 v[34:35], s[94:95]
	v_mad_u64_u32 v[34:35], s[0:1], v122, s74, v[34:35]
	v_mad_i32_i24 v35, v123, s74, v35
	v_lshl_add_u64 v[36:37], v[34:35], 0, v[154:155]
	v_mov_b32_e32 v38, v164
	v_mov_b32_e32 v39, v165
	s_mov_b64 s[0:1], 0x3000000
	v_lshl_add_u64 v[34:35], v[36:37], 0, s[0:1]
	s_mov_b32 s0, 0x3000000
	v_add_co_u32_e32 v42, vcc, s0, v36
	s_nop 1
	v_addc_co_u32_e32 v43, vcc, 0, v37, vcc
	v_mov_b32_e32 v42, v180
	v_mov_b32_e32 v43, v181
	v_lshlrev_b32_e32 v44, 16, v38
	v_and_b32_e32 v46, 0xffff0000, v38
	v_div_scale_f32 v38, s[0:1], v49, v49, 1.0
	v_rcp_f32_e32 v50, v38
	v_lshlrev_b32_e32 v48, 16, v39
	v_fma_f32 v51, -v38, v50, 1.0
	v_fmac_f32_e32 v50, v51, v50
	v_div_scale_f32 v51, vcc, 1.0, v49, 1.0
	v_mul_f32_e32 v54, v51, v50
	v_fma_f32 v55, -v38, v54, v51
	v_fmac_f32_e32 v54, v55, v50
	v_fma_f32 v38, -v38, v54, v51
	v_div_fmas_f32 v38, v38, v50, v54
	v_div_fixup_f32 v50, v38, v49, 1.0
	v_mul_f32_e32 v51, v47, v50
	v_mul_f32_e32 v38, v45, v50
	v_pk_mul_f32 v[32:33], v[32:33], v[50:51]
	v_mov_b32_e32 v45, v16
	v_lshlrev_b32_e32 v52, 16, v42
	v_pk_mul_f32 v[44:45], v[32:33], v[44:45]
	v_mov_b32_e32 v47, v17
	v_fma_f32 v16, v38, v52, v44
	v_and_b32_e32 v42, 0xffff0000, v42
	v_add_f32_e32 v44, v16, v45
	v_pk_mul_f32 v[16:17], v[32:33], v[46:47]
	v_mov_b32_e32 v49, v18
	v_fma_f32 v16, v38, v42, v16
	v_lshlrev_b32_e32 v53, 16, v43
	v_add_f32_e32 v42, v16, v17
	v_pk_mul_f32 v[16:17], v[32:33], v[48:49]
	v_and_b32_e32 v18, 0xffff0000, v39
	v_fma_f32 v16, v38, v53, v16
	v_add_f32_e32 v45, v16, v17
	v_and_b32_e32 v39, 0xffff0000, v43
	v_pk_mul_f32 v[16:17], v[32:33], v[18:19]
	v_cvt_pk_bf16_f32 v18, v44, v42
	v_mov_b32_e32 v43, v20
	v_fma_f32 v16, v38, v39, v16
	v_add_f32_e32 v16, v16, v17
	v_cvt_pk_bf16_f32 v19, v45, v16
	v_lshl_add_u64 v[16:17], v[118:119], 0, v[40:41]
	global_store_dwordx2 v[16:17], v[18:19], off
	v_mov_b32_e32 v18, v166
	v_mov_b32_e32 v19, v167
	s_nop 0
	v_mov_b32_e32 v40, v182
	v_mov_b32_e32 v41, v183
	v_lshlrev_b32_e32 v42, 16, v18
	v_lshlrev_b32_e32 v39, 16, v40
	v_pk_mul_f32 v[42:43], v[32:33], v[42:43]
	s_nop 0
	v_fma_f32 v20, v38, v39, v42
	v_add_f32_e32 v39, v43, v20
	v_and_b32_e32 v20, 0xffff0000, v18
	v_and_b32_e32 v18, 0xffff0000, v40
	v_pk_mul_f32 v[20:21], v[32:33], v[20:21]
	s_nop 0
	v_fma_f32 v18, v38, v18, v20
	v_add_f32_e32 v40, v21, v18
	v_lshlrev_b32_e32 v20, 16, v19
	v_mov_b32_e32 v21, v22
	v_lshlrev_b32_e32 v18, 16, v41
	v_pk_mul_f32 v[20:21], v[32:33], v[20:21]
	v_and_b32_e32 v22, 0xffff0000, v19
	v_fma_f32 v18, v38, v18, v20
	v_add_f32_e32 v20, v21, v18
	v_and_b32_e32 v21, 0xffff0000, v41
	v_pk_mul_f32 v[18:19], v[32:33], v[22:23]
	v_mov_b32_e32 v23, v24
	v_fma_f32 v18, v38, v21, v18
	v_add_f32_e32 v19, v19, v18
	v_cvt_pk_bf16_f32 v18, v39, v40
	v_cvt_pk_bf16_f32 v19, v20, v19
	global_store_dwordx2 v[16:17], v[18:19], off offset:16
	v_mov_b32_e32 v18, v168
	v_mov_b32_e32 v19, v169
	s_nop 0
	v_mov_b32_e32 v20, v184
	v_mov_b32_e32 v21, v185
	v_lshlrev_b32_e32 v22, 16, v18
	v_lshlrev_b32_e32 v39, 16, v20
	v_pk_mul_f32 v[22:23], v[32:33], v[22:23]
	v_and_b32_e32 v24, 0xffff0000, v18
	v_fma_f32 v22, v38, v39, v22
	v_add_f32_e32 v39, v23, v22
	v_and_b32_e32 v18, 0xffff0000, v20
	v_pk_mul_f32 v[22:23], v[32:33], v[24:25]
	s_nop 0
	v_fma_f32 v18, v38, v18, v22
	v_add_f32_e32 v20, v23, v18
	v_lshlrev_b32_e32 v22, 16, v19
; __device__ __forceinline__ unsigned pk2(float lo, float hi) { unsigned r; asm("v_cvt_pk_bf16_f32 %0, %1, %2" : "=v"(r) : "v"(lo), "v"(hi)); return r; }
; __device__ __forceinline__ float bflo(unsigned w) { return __uint_as_float(w << 16); }
; __device__ __forceinline__ float bfhi(unsigned w) { return __uint_as_float(w & 0xffff0000u); }
; __device__ __forceinline__ void attnA_unit(const Args& a, int unit, LAS unsigned char* lds) {
;     ...
;                         const int d = 32 * dt + 8 * g + 4 * h;
;                         const u32x2 a1 = *(const u32x2*)(p1 + d), a2 = *(const u32x2*)(p2 + d);
;                         const float r0 = c1 * bflo(a1.x) + c2 * bflo(a2.x) + c3 * o[4 * g], r1 = c1 * bfhi(a1.x) + c2 * bfhi(a2.x) + c3 * o[4 * g + 1];
;                         const float r2 = c1 * bflo(a1.y) + c2 * bflo(a2.y) + c3 * o[4 * g + 2], r3 = c1 * bfhi(a1.y) + c2 * bfhi(a2.y) + c3 * o[4 * g + 3];
;                         u32x2 w; w.x = pk2(r0, r1); w.y = pk2(r2, r3);
;                         *(u32x2*)(op + d) = w;
;                     }
	v_mov_b32_e32 v23, v26
	v_lshlrev_b32_e32 v18, 16, v21
	v_pk_mul_f32 v[22:23], v[32:33], v[22:23]
	v_and_b32_e32 v26, 0xffff0000, v19
	v_fma_f32 v18, v38, v18, v22
	v_add_f32_e32 v22, v23, v18
	v_and_b32_e32 v21, 0xffff0000, v21
	v_pk_mul_f32 v[18:19], v[32:33], v[26:27]
	v_mov_b32_e32 v23, v28
	v_fma_f32 v18, v38, v21, v18
	v_add_f32_e32 v19, v19, v18
	v_cvt_pk_bf16_f32 v18, v39, v20
	v_cvt_pk_bf16_f32 v19, v22, v19
	global_store_dwordx2 v[16:17], v[18:19], off offset:32
	v_mov_b32_e32 v18, v170
	v_mov_b32_e32 v19, v171
	s_nop 0
	v_mov_b32_e32 v20, v186
	v_mov_b32_e32 v21, v187
	v_lshlrev_b32_e32 v22, 16, v18
	v_lshlrev_b32_e32 v24, 16, v20
	v_pk_mul_f32 v[22:23], v[32:33], v[22:23]
	v_and_b32_e32 v28, 0xffff0000, v18
	v_fma_f32 v22, v38, v24, v22
	v_add_f32_e32 v24, v23, v22
	v_and_b32_e32 v18, 0xffff0000, v20
	v_pk_mul_f32 v[22:23], v[32:33], v[28:29]
	s_nop 0
	v_fma_f32 v18, v38, v18, v22
	v_add_f32_e32 v20, v23, v18
	v_lshlrev_b32_e32 v22, 16, v19
	v_mov_b32_e32 v23, v30
	v_lshlrev_b32_e32 v18, 16, v21
	v_pk_mul_f32 v[22:23], v[32:33], v[22:23]
	v_and_b32_e32 v30, 0xffff0000, v19
	v_fma_f32 v18, v38, v18, v22
	v_add_f32_e32 v22, v23, v18
	v_and_b32_e32 v21, 0xffff0000, v21
	v_pk_mul_f32 v[18:19], v[32:33], v[30:31]
	v_mov_b32_e32 v23, v0
	v_fma_f32 v18, v38, v21, v18
	v_add_f32_e32 v19, v19, v18
	v_cvt_pk_bf16_f32 v18, v24, v20
	v_cvt_pk_bf16_f32 v19, v22, v19
	global_store_dwordx2 v[16:17], v[18:19], off offset:48
	v_mov_b32_e32 v18, v172
	v_mov_b32_e32 v19, v173
	s_nop 0
	v_mov_b32_e32 v20, v188
	v_mov_b32_e32 v21, v189
	v_lshlrev_b32_e32 v22, 16, v18
	v_lshlrev_b32_e32 v24, 16, v20
	v_pk_mul_f32 v[22:23], v[32:33], v[22:23]
	s_nop 0
	v_fma_f32 v0, v38, v24, v22
	v_add_f32_e32 v22, v23, v0
	v_and_b32_e32 v0, 0xffff0000, v18
	v_and_b32_e32 v18, 0xffff0000, v20
	v_pk_mul_f32 v[0:1], v[32:33], v[0:1]
	v_lshlrev_b32_e32 v20, 16, v21
	v_fma_f32 v0, v38, v18, v0
	v_add_f32_e32 v18, v1, v0
	v_lshlrev_b32_e32 v0, 16, v19
	v_mov_b32_e32 v1, v2
	v_pk_mul_f32 v[0:1], v[32:33], v[0:1]
	v_and_b32_e32 v2, 0xffff0000, v19
	v_fma_f32 v0, v38, v20, v0
	v_add_f32_e32 v20, v1, v0
	v_and_b32_e32 v19, 0xffff0000, v21
	v_pk_mul_f32 v[0:1], v[32:33], v[2:3]
	s_nop 0
	v_fma_f32 v0, v38, v19, v0
	v_add_f32_e32 v1, v1, v0
	v_cvt_pk_bf16_f32 v0, v22, v18
	v_cvt_pk_bf16_f32 v1, v20, v1
	global_store_dwordx2 v[16:17], v[0:1], off offset:64
	v_mov_b32_e32 v0, v174
	v_mov_b32_e32 v1, v175
	s_nop 0
	v_mov_b32_e32 v2, v190
	v_mov_b32_e32 v3, v191
	v_mov_b32_e32 v19, v4
	v_lshlrev_b32_e32 v18, 16, v0
	v_lshlrev_b32_e32 v20, 16, v2
	v_pk_mul_f32 v[18:19], v[32:33], v[18:19]
	s_nop 0
	v_fma_f32 v4, v38, v20, v18
	v_add_f32_e32 v18, v19, v4
	v_and_b32_e32 v4, 0xffff0000, v0
	v_and_b32_e32 v0, 0xffff0000, v2
	v_pk_mul_f32 v[4:5], v[32:33], v[4:5]
	s_nop 0
	v_fma_f32 v0, v38, v0, v4
	v_add_f32_e32 v2, v5, v0
	v_lshlrev_b32_e32 v4, 16, v1
	v_mov_b32_e32 v5, v6
	v_lshlrev_b32_e32 v0, 16, v3
	v_pk_mul_f32 v[4:5], v[32:33], v[4:5]
	v_and_b32_e32 v6, 0xffff0000, v1
	v_fma_f32 v0, v38, v0, v4
	v_add_f32_e32 v4, v5, v0
	v_and_b32_e32 v3, 0xffff0000, v3
	v_pk_mul_f32 v[0:1], v[32:33], v[6:7]
	v_mov_b32_e32 v5, v8
	v_fma_f32 v0, v38, v3, v0
	v_add_f32_e32 v1, v1, v0
	v_cvt_pk_bf16_f32 v0, v18, v2
	v_cvt_pk_bf16_f32 v1, v4, v1
	global_store_dwordx2 v[16:17], v[0:1], off offset:80
	v_mov_b32_e32 v0, v176
	v_mov_b32_e32 v1, v177
	s_nop 0
	v_mov_b32_e32 v2, v192
	v_mov_b32_e32 v3, v193
	v_lshlrev_b32_e32 v4, 16, v0
	v_lshlrev_b32_e32 v6, 16, v2
	v_pk_mul_f32 v[4:5], v[32:33], v[4:5]
	v_and_b32_e32 v8, 0xffff0000, v0
	v_fma_f32 v4, v38, v6, v4
	v_add_f32_e32 v6, v5, v4
	v_and_b32_e32 v0, 0xffff0000, v2
	v_pk_mul_f32 v[4:5], v[32:33], v[8:9]
	s_nop 0
	v_fma_f32 v0, v38, v0, v4
	v_add_f32_e32 v2, v5, v0
	v_lshlrev_b32_e32 v4, 16, v1
	v_mov_b32_e32 v5, v10
	v_lshlrev_b32_e32 v0, 16, v3
	v_pk_mul_f32 v[4:5], v[32:33], v[4:5]
	v_and_b32_e32 v10, 0xffff0000, v1
	v_fma_f32 v0, v38, v0, v4
	v_add_f32_e32 v4, v5, v0
	v_and_b32_e32 v3, 0xffff0000, v3
	v_pk_mul_f32 v[0:1], v[32:33], v[10:11]
	v_mov_b32_e32 v5, v12
	v_fma_f32 v0, v38, v3, v0
	v_add_f32_e32 v1, v1, v0
	v_cvt_pk_bf16_f32 v0, v6, v2
	v_cvt_pk_bf16_f32 v1, v4, v1
	global_store_dwordx2 v[16:17], v[0:1], off offset:96
	v_mov_b32_e32 v0, v178
	v_mov_b32_e32 v1, v179
	s_nop 0
	v_mov_b32_e32 v2, v194
	v_mov_b32_e32 v3, v195
	v_lshlrev_b32_e32 v4, 16, v0
	v_lshlrev_b32_e32 v6, 16, v2
	v_pk_mul_f32 v[4:5], v[32:33], v[4:5]
	v_and_b32_e32 v12, 0xffff0000, v0
	v_fma_f32 v4, v38, v6, v4
	v_add_f32_e32 v6, v5, v4
	v_and_b32_e32 v0, 0xffff0000, v2
	v_pk_mul_f32 v[4:5], v[32:33], v[12:13]
	s_nop 0
	v_fma_f32 v0, v38, v0, v4
	v_add_f32_e32 v2, v5, v0
	v_lshlrev_b32_e32 v4, 16, v1
	v_mov_b32_e32 v5, v14
	v_lshlrev_b32_e32 v0, 16, v3
	v_pk_mul_f32 v[4:5], v[32:33], v[4:5]
	v_and_b32_e32 v14, 0xffff0000, v1
	v_fma_f32 v0, v38, v0, v4
	v_add_f32_e32 v4, v5, v0
	v_and_b32_e32 v3, 0xffff0000, v3
	v_pk_mul_f32 v[0:1], v[32:33], v[14:15]
	s_nop 0
	v_fma_f32 v0, v38, v3, v0
	v_add_f32_e32 v1, v1, v0
	v_cvt_pk_bf16_f32 v0, v6, v2
	v_cvt_pk_bf16_f32 v1, v4, v1
	global_store_dwordx2 v[16:17], v[0:1], off offset:112
	s_branch .LBB0_266

; template <int MODE>
; __device__ __forceinline__ void transpose_item(const Args& a, int layer, int item, LAS float* scr, int lane) {
;     ...
; #pragma unroll 8
;     for (int i = 0; i < 32; ++i) { const int kk = 2 * i + (lane >> 5); scr[kk * 33 + (lane & 31)] = src[(size_t)(k0 + kk) * N + col]; }
.LBB0_367:
	s_lshl_b32 s22, s19, 1
	s_lshl_b32 s21, s18, 1
	v_or_b32_e32 v35, s22, v2
	v_or_b32_e32 v11, s21, v1
	v_add_lshl_u32 v17, v35, v10, 10
	v_add_lshl_u32 v16, v11, v3, 10
	v_or_b32_e32 v154, v14, v17
	v_or_b32_e32 v16, v5, v16
	v_lshl_add_u64 v[18:19], v[154:155], 2, v[12:13]
	v_mov_b32_e32 v17, v155
	v_lshl_add_u64 v[16:17], v[16:17], 2, v[12:13]
	global_load_dword v64, v[18:19], off
	global_load_dword v65, v[16:17], off
	v_mad_u64_u32 v[16:17], s[24:25], v35, s38, v[4:5]
	v_mad_u64_u32 v[18:19], s[24:25], v11, s38, v[4:5]
	s_add_i32 s24, s22, 4
	s_add_i32 s23, s21, 4
	v_or_b32_e32 v35, s24, v2
	v_or_b32_e32 v11, s23, v1
	v_add_lshl_u32 v17, v35, v10, 10
	v_or_b32_e32 v154, v14, v17
	v_mov_b32_e32 v17, v155
	s_add_i32 s23, s21, 8
	s_add_i32 s19, s19, 16
	s_add_i32 s18, s18, 16
	s_add_i32 s20, s20, -16
	v_mov_b32_e32 v80, v16
	v_mov_b32_e32 v81, v18
	v_add_lshl_u32 v16, v11, v3, 10
	v_or_b32_e32 v16, v5, v16
	v_lshl_add_u64 v[18:19], v[154:155], 2, v[12:13]
	v_lshl_add_u64 v[16:17], v[16:17], 2, v[12:13]
	global_load_dword v66, v[18:19], off
	global_load_dword v67, v[16:17], off
	v_mad_u64_u32 v[16:17], s[24:25], v35, s38, v[4:5]
	v_mad_u64_u32 v[18:19], s[24:25], v11, s38, v[4:5]
	s_add_i32 s24, s22, 8
	s_nop 0
	v_or_b32_e32 v35, s24, v2
	v_or_b32_e32 v11, s23, v1
	v_add_lshl_u32 v17, v35, v10, 10
	v_or_b32_e32 v154, v14, v17
	v_mov_b32_e32 v17, v155
	s_add_i32 s23, s21, 12
	v_mov_b32_e32 v82, v16
	v_mov_b32_e32 v83, v18
	v_add_lshl_u32 v16, v11, v3, 10
	v_or_b32_e32 v16, v5, v16
	v_lshl_add_u64 v[18:19], v[154:155], 2, v[12:13]
	v_lshl_add_u64 v[16:17], v[16:17], 2, v[12:13]
	global_load_dword v68, v[18:19], off
	global_load_dword v69, v[16:17], off
	v_mad_u64_u32 v[16:17], s[24:25], v35, s38, v[4:5]
	v_mad_u64_u32 v[18:19], s[24:25], v11, s38, v[4:5]
	s_add_i32 s24, s22, 12
	s_nop 0
	v_or_b32_e32 v35, s24, v2
	v_or_b32_e32 v11, s23, v1
	v_add_lshl_u32 v17, v35, v10, 10
	v_or_b32_e32 v154, v14, v17
	v_mov_b32_e32 v17, v155
	s_add_i32 s23, s21, 16
	v_mov_b32_e32 v84, v16
	v_mov_b32_e32 v85, v18
	v_add_lshl_u32 v16, v11, v3, 10
	v_or_b32_e32 v16, v5, v16
	v_lshl_add_u64 v[18:19], v[154:155], 2, v[12:13]
	v_lshl_add_u64 v[16:17], v[16:17], 2, v[12:13]
	global_load_dword v70, v[18:19], off
	global_load_dword v71, v[16:17], off
	v_mad_u64_u32 v[16:17], s[24:25], v35, s38, v[4:5]
	v_mad_u64_u32 v[18:19], s[24:25], v11, s38, v[4:5]
	s_add_i32 s24, s22, 16
	s_nop 0
	v_or_b32_e32 v35, s24, v2
	v_or_b32_e32 v11, s23, v1
	v_add_lshl_u32 v17, v35, v10, 10
	v_or_b32_e32 v154, v14, v17
	v_mov_b32_e32 v17, v155
	s_add_i32 s23, s21, 20
	v_mov_b32_e32 v86, v16
	v_mov_b32_e32 v87, v18
	v_add_lshl_u32 v16, v11, v3, 10
	v_or_b32_e32 v16, v5, v16
	v_lshl_add_u64 v[18:19], v[154:155], 2, v[12:13]
	v_lshl_add_u64 v[16:17], v[16:17], 2, v[12:13]
	global_load_dword v72, v[18:19], off
	global_load_dword v73, v[16:17], off
	v_mad_u64_u32 v[16:17], s[24:25], v35, s38, v[4:5]
	v_mad_u64_u32 v[18:19], s[24:25], v11, s38, v[4:5]
	s_add_i32 s24, s22, 20
	s_nop 0
	v_or_b32_e32 v35, s24, v2
	v_or_b32_e32 v11, s23, v1
	v_add_lshl_u32 v17, v35, v10, 10
	v_or_b32_e32 v154, v14, v17
	v_mov_b32_e32 v17, v155
	s_add_i32 s23, s21, 24
	s_add_i32 s21, s21, 28
	v_mov_b32_e32 v88, v16
	v_mov_b32_e32 v89, v18
	v_add_lshl_u32 v16, v11, v3, 10
	v_or_b32_e32 v16, v5, v16
	v_lshl_add_u64 v[18:19], v[154:155], 2, v[12:13]
	v_lshl_add_u64 v[16:17], v[16:17], 2, v[12:13]
	global_load_dword v74, v[18:19], off
	global_load_dword v75, v[16:17], off
	v_mad_u64_u32 v[16:17], s[24:25], v35, s38, v[4:5]
	v_mad_u64_u32 v[18:19], s[24:25], v11, s38, v[4:5]
	s_add_i32 s24, s22, 24
	s_nop 0
	v_or_b32_e32 v35, s24, v2
	v_or_b32_e32 v11, s23, v1
	v_add_lshl_u32 v17, v35, v10, 10
	v_or_b32_e32 v154, v14, v17
	v_mov_b32_e32 v17, v155
	s_add_i32 s22, s22, 28
	s_cmp_lg_u32 s20, 0
	v_mov_b32_e32 v90, v16
	v_mov_b32_e32 v91, v18
	v_add_lshl_u32 v16, v11, v3, 10
	v_or_b32_e32 v16, v5, v16
	v_lshl_add_u64 v[18:19], v[154:155], 2, v[12:13]
	v_lshl_add_u64 v[16:17], v[16:17], 2, v[12:13]
	global_load_dword v76, v[18:19], off
	global_load_dword v77, v[16:17], off
	v_mad_u64_u32 v[16:17], s[24:25], v35, s38, v[4:5]
	v_or_b32_e32 v35, s22, v2
	v_mad_u64_u32 v[18:19], s[24:25], v11, s38, v[4:5]
	v_or_b32_e32 v11, s21, v1
	v_add_lshl_u32 v17, v35, v10, 10
	v_or_b32_e32 v154, v14, v17
	v_mov_b32_e32 v19, v155
	v_mov_b32_e32 v92, v16
	v_mov_b32_e32 v93, v18
	v_add_lshl_u32 v16, v11, v3, 10
	v_or_b32_e32 v18, v5, v16
	v_lshl_add_u64 v[16:17], v[154:155], 2, v[12:13]
	v_lshl_add_u64 v[18:19], v[18:19], 2, v[12:13]
	global_load_dword v78, v[16:17], off
	global_load_dword v79, v[18:19], off
	v_mad_u64_u32 v[16:17], s[22:23], v35, s38, v[4:5]
	v_mad_u64_u32 v[18:19], s[22:23], v11, s38, v[4:5]
	v_mov_b32_e32 v94, v16
	v_mov_b32_e32 v95, v18
	s_waitcnt vmcnt(0)
	ds_write_b32 v80, v64
	ds_write_b32 v81, v65
	ds_write_b32 v82, v66
	ds_write_b32 v83, v67
	ds_write_b32 v84, v68
	ds_write_b32 v85, v69
	ds_write_b32 v86, v70
	ds_write_b32 v87, v71
	ds_write_b32 v88, v72
	ds_write_b32 v89, v73
	ds_write_b32 v90, v74
	ds_write_b32 v91, v75
	ds_write_b32 v92, v76
	ds_write_b32 v93, v77
	ds_write_b32 v94, v78
	ds_write_b32 v95, v79
	s_cbranch_scc1 .LBB0_367
; #define LAS __attribute__((address_space(3)))
; __device__ __forceinline__ unsigned pk2(float lo, float hi) { unsigned r; asm("v_cvt_pk_bf16_f32 %0, %1, %2" : "=v"(r) : "v"(lo), "v"(hi)); return r; }
; template <int MODE>
; __device__ __forceinline__ void transpose_item(const Args& a, int layer, int item, LAS float* scr, int lane) {
;     ...
;     asm volatile("s_waitcnt lgkmcnt(0)" ::: "memory");
;     const int c = lane & 7;
; #pragma unroll
;     for (int j = 0; j < 4; ++j) {
;         const int n = (lane >> 3) + 8 * j; const LAS float* s = scr + (8 * c) * 33 + n;
;         u32x4 o; o.x = pk2(s[0 * 33], s[1 * 33]); o.y = pk2(s[2 * 33], s[3 * 33]); o.z = pk2(s[4 * 33], s[5 * 33]); o.w = pk2(s[6 * 33], s[7 * 33]);
;         *(u32x4*)(WT + (size_t)(n0 + n) * K + k0 + 8 * c) = o;
;     }
;     asm volatile("s_waitcnt lgkmcnt(0)" ::: "memory");
	s_waitcnt lgkmcnt(0)
	v_mul_hi_i32_i24_e32 v13, 0x580000, v8
	v_mul_i32_i24_e32 v12, 0x580000, v8
	ds_read2_b32 v[16:17], v24 offset0:33 offset1:41
	ds_read2_b32 v[18:19], v24 offset1:8
	ds_read2_b32 v[36:37], v24 offset0:66 offset1:74
	ds_read2_b32 v[38:39], v24 offset0:99 offset1:107
	ds_read2_b32 v[40:41], v24 offset0:132 offset1:140
	ds_read2_b32 v[42:43], v24 offset0:165 offset1:173
	ds_read2_b32 v[44:45], v24 offset0:198 offset1:206
	ds_read2_b32 v[46:47], v24 offset0:231 offset1:239
	v_lshl_add_u64 v[12:13], s[2:3], 0, v[12:13]
	v_lshlrev_b32_e32 v154, 1, v10
	v_or_b32_e32 v3, v9, v23
	v_lshl_add_u64 v[10:11], v[12:13], 0, v[154:155]
	v_lshlrev_b32_e32 v154, 1, v6
	v_mul_u32_u24_e32 v3, 0xb00, v3
	v_lshl_add_u64 v[48:49], v[10:11], 0, v[154:155]
	v_lshlrev_b32_e32 v154, 1, v3
	v_lshl_add_u64 v[50:51], v[48:49], 0, v[154:155]
	v_or_b32_e32 v3, v9, v25
	s_waitcnt lgkmcnt(0)
	v_cvt_pk_bf16_f32 v10, v18, v16
	v_cvt_pk_bf16_f32 v11, v36, v38
	v_cvt_pk_bf16_f32 v12, v40, v42
	v_cvt_pk_bf16_f32 v13, v44, v46
	global_store_dwordx4 v[50:51], v[10:13], off
	v_mul_u32_u24_e32 v3, 0xb00, v3
	v_lshlrev_b32_e32 v154, 1, v3
	v_cvt_pk_bf16_f32 v10, v19, v17
	v_cvt_pk_bf16_f32 v11, v37, v39
	v_cvt_pk_bf16_f32 v12, v41, v43
	v_cvt_pk_bf16_f32 v13, v45, v47
	ds_read2_b32 v[18:19], v24 offset0:16 offset1:24
	ds_read2_b32 v[36:37], v24 offset0:49 offset1:57
	ds_read2_b32 v[38:39], v24 offset0:82 offset1:90
	ds_read2_b32 v[40:41], v24 offset0:115 offset1:123
	ds_read2_b32 v[42:43], v24 offset0:148 offset1:156
	ds_read2_b32 v[44:45], v24 offset0:181 offset1:189
	ds_read2_b32 v[46:47], v24 offset0:214 offset1:222
	ds_read2_b32 v[50:51], v24 offset0:247 offset1:255
	v_or_b32_e32 v3, v9, v26
	v_mul_u32_u24_e32 v3, 0xb00, v3
	v_lshl_add_u64 v[16:17], v[48:49], 0, v[154:155]
	v_lshlrev_b32_e32 v154, 1, v3
	v_or_b32_e32 v3, v9, v27
	v_mul_u32_u24_e32 v3, 0xb00, v3
	global_store_dwordx4 v[16:17], v[10:13], off
	v_lshl_add_u64 v[16:17], v[48:49], 0, v[154:155]
	v_lshlrev_b32_e32 v154, 1, v3
	s_waitcnt lgkmcnt(6)
	v_cvt_pk_bf16_f32 v10, v18, v36
	s_waitcnt lgkmcnt(4)
	v_cvt_pk_bf16_f32 v11, v38, v40
	s_waitcnt lgkmcnt(2)
	v_cvt_pk_bf16_f32 v12, v42, v44
	s_waitcnt lgkmcnt(0)
	v_cvt_pk_bf16_f32 v13, v46, v50
	v_lshl_add_u64 v[8:9], v[48:49], 0, v[154:155]
	global_store_dwordx4 v[16:17], v[10:13], off
	s_nop 1
	v_cvt_pk_bf16_f32 v10, v19, v37
	v_cvt_pk_bf16_f32 v11, v39, v41
	v_cvt_pk_bf16_f32 v12, v43, v45
	v_cvt_pk_bf16_f32 v13, v47, v51
	global_store_dwordx4 v[8:9], v[10:13], off
	s_waitcnt lgkmcnt(0)

; template <int MODE>
; __device__ __forceinline__ void transpose_item(const Args& a, int layer, int item, LAS float* scr, int lane) {
;     ...
; #pragma unroll 8
;     for (int i = 0; i < 32; ++i) { const int kk = 2 * i + (lane >> 5); scr[kk * 33 + (lane & 31)] = src[(size_t)(k0 + kk) * N + col]; }
.LBB0_371:
	s_lshl_b32 s22, s18, 1
	s_lshl_b32 s21, s19, 1
	v_or_b32_e32 v35, s22, v2
	v_or_b32_e32 v11, s21, v1
	v_add_u32_e32 v18, v35, v10
	v_add_u32_e32 v16, v11, v3
	v_mad_u64_u32 v[18:19], s[24:25], v18, s61, v[14:15]
	v_mad_u64_u32 v[16:17], s[24:25], v16, s61, v[14:15]
	v_mov_b32_e32 v19, v155
	v_lshl_add_u64 v[18:19], v[18:19], 2, v[8:9]
	v_mov_b32_e32 v17, v155
	v_lshl_add_u64 v[16:17], v[16:17], 2, v[8:9]
	global_load_dword v64, v[18:19], off
	global_load_dword v65, v[16:17], off
	v_mad_u64_u32 v[16:17], s[24:25], v35, s38, v[4:5]
	v_mad_u64_u32 v[18:19], s[24:25], v11, s38, v[4:5]
	s_add_i32 s24, s22, 4
	s_add_i32 s23, s21, 4
	v_or_b32_e32 v35, s24, v2
	v_or_b32_e32 v11, s23, v1
	s_add_i32 s23, s21, 8
	s_add_i32 s18, s18, 16
	s_add_i32 s19, s19, 16
	s_add_i32 s20, s20, -16
	v_mov_b32_e32 v80, v16
	v_mov_b32_e32 v81, v18
	v_add_u32_e32 v18, v35, v10
	v_add_u32_e32 v16, v11, v3
	v_mad_u64_u32 v[18:19], s[24:25], v18, s61, v[14:15]
	v_mad_u64_u32 v[16:17], s[24:25], v16, s61, v[14:15]
	v_mov_b32_e32 v19, v155
	v_lshl_add_u64 v[18:19], v[18:19], 2, v[8:9]
	v_mov_b32_e32 v17, v155
	v_lshl_add_u64 v[16:17], v[16:17], 2, v[8:9]
	global_load_dword v66, v[18:19], off
	global_load_dword v67, v[16:17], off
	v_mad_u64_u32 v[16:17], s[24:25], v35, s38, v[4:5]
	v_mad_u64_u32 v[18:19], s[24:25], v11, s38, v[4:5]
	s_add_i32 s24, s22, 8
	s_nop 0
	v_or_b32_e32 v35, s24, v2
	v_or_b32_e32 v11, s23, v1
	s_add_i32 s23, s21, 12
	v_mov_b32_e32 v82, v16
	v_mov_b32_e32 v83, v18
	v_add_u32_e32 v18, v35, v10
	v_add_u32_e32 v16, v11, v3
	v_mad_u64_u32 v[18:19], s[24:25], v18, s61, v[14:15]
	v_mad_u64_u32 v[16:17], s[24:25], v16, s61, v[14:15]
	v_mov_b32_e32 v19, v155
	v_lshl_add_u64 v[18:19], v[18:19], 2, v[8:9]
	v_mov_b32_e32 v17, v155
	v_lshl_add_u64 v[16:17], v[16:17], 2, v[8:9]
	global_load_dword v68, v[18:19], off
	global_load_dword v69, v[16:17], off
	v_mad_u64_u32 v[16:17], s[24:25], v35, s38, v[4:5]
	v_mad_u64_u32 v[18:19], s[24:25], v11, s38, v[4:5]
	s_add_i32 s24, s22, 12
	s_nop 0
	v_or_b32_e32 v35, s24, v2
	v_or_b32_e32 v11, s23, v1
	s_add_i32 s23, s21, 16
	v_mov_b32_e32 v84, v16
	v_mov_b32_e32 v85, v18
	v_add_u32_e32 v18, v35, v10
	v_add_u32_e32 v16, v11, v3
	v_mad_u64_u32 v[18:19], s[24:25], v18, s61, v[14:15]
	v_mad_u64_u32 v[16:17], s[24:25], v16, s61, v[14:15]
	v_mov_b32_e32 v19, v155
	v_lshl_add_u64 v[18:19], v[18:19], 2, v[8:9]
	v_mov_b32_e32 v17, v155
	v_lshl_add_u64 v[16:17], v[16:17], 2, v[8:9]
	global_load_dword v70, v[18:19], off
	global_load_dword v71, v[16:17], off
	v_mad_u64_u32 v[16:17], s[24:25], v35, s38, v[4:5]
	v_mad_u64_u32 v[18:19], s[24:25], v11, s38, v[4:5]
	s_add_i32 s24, s22, 16
	s_nop 0
	v_or_b32_e32 v35, s24, v2
	v_or_b32_e32 v11, s23, v1
	s_add_i32 s23, s21, 20
	v_mov_b32_e32 v86, v16
	v_mov_b32_e32 v87, v18
	v_add_u32_e32 v18, v35, v10
	v_add_u32_e32 v16, v11, v3
	v_mad_u64_u32 v[18:19], s[24:25], v18, s61, v[14:15]
	v_mad_u64_u32 v[16:17], s[24:25], v16, s61, v[14:15]
	v_mov_b32_e32 v19, v155
	v_lshl_add_u64 v[18:19], v[18:19], 2, v[8:9]
	v_mov_b32_e32 v17, v155
	v_lshl_add_u64 v[16:17], v[16:17], 2, v[8:9]
	global_load_dword v72, v[18:19], off
	global_load_dword v73, v[16:17], off
	v_mad_u64_u32 v[16:17], s[24:25], v35, s38, v[4:5]
	v_mad_u64_u32 v[18:19], s[24:25], v11, s38, v[4:5]
	s_add_i32 s24, s22, 20
	s_nop 0
	v_or_b32_e32 v35, s24, v2
	v_or_b32_e32 v11, s23, v1
	s_add_i32 s23, s21, 24
	s_add_i32 s21, s21, 28
	v_mov_b32_e32 v88, v16
	v_mov_b32_e32 v89, v18
	v_add_u32_e32 v18, v35, v10
	v_add_u32_e32 v16, v11, v3
	v_mad_u64_u32 v[18:19], s[24:25], v18, s61, v[14:15]
	v_mad_u64_u32 v[16:17], s[24:25], v16, s61, v[14:15]
	v_mov_b32_e32 v19, v155
	v_lshl_add_u64 v[18:19], v[18:19], 2, v[8:9]
	v_mov_b32_e32 v17, v155
	v_lshl_add_u64 v[16:17], v[16:17], 2, v[8:9]
	global_load_dword v74, v[18:19], off
	global_load_dword v75, v[16:17], off
	v_mad_u64_u32 v[16:17], s[24:25], v35, s38, v[4:5]
	v_mad_u64_u32 v[18:19], s[24:25], v11, s38, v[4:5]
	s_add_i32 s24, s22, 24
	s_nop 0
	v_or_b32_e32 v35, s24, v2
	v_or_b32_e32 v11, s23, v1
	s_add_i32 s22, s22, 28
	s_cmp_lg_u32 s20, 0
	v_mov_b32_e32 v90, v16
	v_mov_b32_e32 v91, v18
	v_add_u32_e32 v18, v35, v10
	v_add_u32_e32 v16, v11, v3
	v_mad_u64_u32 v[18:19], s[24:25], v18, s61, v[14:15]
	v_mad_u64_u32 v[16:17], s[24:25], v16, s61, v[14:15]
	v_mov_b32_e32 v19, v155
	v_lshl_add_u64 v[18:19], v[18:19], 2, v[8:9]
	v_mov_b32_e32 v17, v155
	v_lshl_add_u64 v[16:17], v[16:17], 2, v[8:9]
	global_load_dword v76, v[18:19], off
	global_load_dword v77, v[16:17], off
	v_mad_u64_u32 v[16:17], s[24:25], v35, s38, v[4:5]
	v_mad_u64_u32 v[18:19], s[24:25], v11, s38, v[4:5]
	v_or_b32_e32 v35, s22, v2
	v_or_b32_e32 v11, s21, v1
	v_mov_b32_e32 v92, v16
	v_mov_b32_e32 v93, v18
	v_add_u32_e32 v18, v35, v10
	v_add_u32_e32 v16, v11, v3
	v_mad_u64_u32 v[18:19], s[22:23], v18, s61, v[14:15]
	v_mad_u64_u32 v[16:17], s[22:23], v16, s61, v[14:15]
	v_mov_b32_e32 v19, v155
	v_lshl_add_u64 v[18:19], v[18:19], 2, v[8:9]
	v_mov_b32_e32 v17, v155
	v_lshl_add_u64 v[16:17], v[16:17], 2, v[8:9]
	global_load_dword v78, v[18:19], off
	global_load_dword v79, v[16:17], off
	v_mad_u64_u32 v[16:17], s[22:23], v35, s38, v[4:5]
	v_mad_u64_u32 v[18:19], s[22:23], v11, s38, v[4:5]
	v_mov_b32_e32 v94, v16
	v_mov_b32_e32 v95, v18
	s_waitcnt vmcnt(0)
	ds_write_b32 v80, v64
	ds_write_b32 v81, v65
	ds_write_b32 v82, v66
	ds_write_b32 v83, v67
	ds_write_b32 v84, v68
	ds_write_b32 v85, v69
	ds_write_b32 v86, v70
	ds_write_b32 v87, v71
	ds_write_b32 v88, v72
	ds_write_b32 v89, v73
	ds_write_b32 v90, v74
	ds_write_b32 v91, v75
	ds_write_b32 v92, v76
	ds_write_b32 v93, v77
	ds_write_b32 v94, v78
	ds_write_b32 v95, v79
	s_cbranch_scc1 .LBB0_371
; #define LAS __attribute__((address_space(3)))
; __device__ __forceinline__ unsigned pk2(float lo, float hi) { unsigned r; asm("v_cvt_pk_bf16_f32 %0, %1, %2" : "=v"(r) : "v"(lo), "v"(hi)); return r; }
; template <int MODE>
; __device__ __forceinline__ void transpose_item(const Args& a, int layer, int item, LAS float* scr, int lane) {
;     ...
;     asm volatile("s_waitcnt lgkmcnt(0)" ::: "memory");
;     const int c = lane & 7;
; #pragma unroll
;     for (int j = 0; j < 4; ++j) {
;         const int n = (lane >> 3) + 8 * j; const LAS float* s = scr + (8 * c) * 33 + n;
;         u32x4 o; o.x = pk2(s[0 * 33], s[1 * 33]); o.y = pk2(s[2 * 33], s[3 * 33]); o.z = pk2(s[4 * 33], s[5 * 33]); o.w = pk2(s[6 * 33], s[7 * 33]);
;         *(u32x4*)(WT + (size_t)(n0 + n) * K + k0 + 8 * c) = o;
;     }
;     asm volatile("s_waitcnt lgkmcnt(0)" ::: "memory");
	s_waitcnt lgkmcnt(0)
	v_lshl_add_u64 v[8:9], s[4:5], 0, v[12:13]
	ds_read2_b32 v[12:13], v24 offset0:33 offset1:41
	ds_read2_b32 v[16:17], v24 offset1:8
	ds_read2_b32 v[18:19], v24 offset0:66 offset1:74
	ds_read2_b32 v[36:37], v24 offset0:99 offset1:107
	ds_read2_b32 v[38:39], v24 offset0:132 offset1:140
	ds_read2_b32 v[40:41], v24 offset0:165 offset1:173
	ds_read2_b32 v[42:43], v24 offset0:198 offset1:206
	ds_read2_b32 v[44:45], v24 offset0:231 offset1:239
	v_lshlrev_b32_e32 v3, 15, v5
	v_lshlrev_b32_e32 v154, 1, v10
	v_lshl_add_u64 v[8:9], v[8:9], 0, v[154:155]
	v_lshlrev_b32_e32 v154, 1, v6
	v_or_b32_e32 v5, v3, v28
	v_lshl_add_u64 v[46:47], v[8:9], 0, v[154:155]
	v_lshlrev_b32_e32 v154, 1, v5
	v_lshl_add_u64 v[48:49], v[46:47], 0, v[154:155]
	s_waitcnt lgkmcnt(0)
	v_cvt_pk_bf16_f32 v8, v16, v12
	v_cvt_pk_bf16_f32 v9, v18, v36
	v_cvt_pk_bf16_f32 v10, v38, v40
	v_cvt_pk_bf16_f32 v11, v42, v44
	global_store_dwordx4 v[48:49], v[8:11], off
	v_or_b32_e32 v5, v3, v29
	v_lshlrev_b32_e32 v154, 1, v5
	v_cvt_pk_bf16_f32 v8, v17, v13
	v_cvt_pk_bf16_f32 v9, v19, v37
	v_cvt_pk_bf16_f32 v10, v39, v41
	v_cvt_pk_bf16_f32 v11, v43, v45
	ds_read2_b32 v[16:17], v24 offset0:16 offset1:24
	ds_read2_b32 v[18:19], v24 offset0:49 offset1:57
	ds_read2_b32 v[36:37], v24 offset0:82 offset1:90
	ds_read2_b32 v[38:39], v24 offset0:115 offset1:123
	ds_read2_b32 v[40:41], v24 offset0:148 offset1:156
	ds_read2_b32 v[42:43], v24 offset0:181 offset1:189
	ds_read2_b32 v[44:45], v24 offset0:214 offset1:222
	ds_read2_b32 v[48:49], v24 offset0:247 offset1:255
	v_or_b32_e32 v5, v3, v30
	v_lshl_add_u64 v[12:13], v[46:47], 0, v[154:155]
	v_lshlrev_b32_e32 v154, 1, v5
	v_or_b32_e32 v3, v3, v31
	global_store_dwordx4 v[12:13], v[8:11], off
	v_lshl_add_u64 v[12:13], v[46:47], 0, v[154:155]
	v_lshlrev_b32_e32 v154, 1, v3
	s_waitcnt lgkmcnt(6)
	v_cvt_pk_bf16_f32 v8, v16, v18
	s_waitcnt lgkmcnt(4)
	v_cvt_pk_bf16_f32 v9, v36, v38
	s_waitcnt lgkmcnt(2)
	v_cvt_pk_bf16_f32 v10, v40, v42
	s_waitcnt lgkmcnt(0)
	v_cvt_pk_bf16_f32 v11, v44, v48
	global_store_dwordx4 v[12:13], v[8:11], off
	v_lshl_add_u64 v[12:13], v[46:47], 0, v[154:155]
	s_nop 0
	v_cvt_pk_bf16_f32 v8, v17, v19
	v_cvt_pk_bf16_f32 v9, v37, v39
	v_cvt_pk_bf16_f32 v10, v41, v43
	v_cvt_pk_bf16_f32 v11, v45, v49
	global_store_dwordx4 v[12:13], v[8:11], off
	s_waitcnt lgkmcnt(0)

; template <int MODE>
; __device__ __forceinline__ void transpose_item(const Args& a, int layer, int item, LAS float* scr, int lane) {
;     ...
; #pragma unroll 8
;     for (int i = 0; i < 32; ++i) { const int kk = 2 * i + (lane >> 5); scr[kk * 33 + (lane & 31)] = src[(size_t)(k0 + kk) * N + col]; }
.LBB0_376:
	s_lshl_b32 s20, s17, 1
	s_lshl_b32 s19, s16, 1
	v_or_b32_e32 v36, s20, v2
	v_or_b32_e32 v35, s19, v1
	v_add_lshl_u32 v17, v36, v10, 10
	v_add_lshl_u32 v16, v35, v3, 10
	v_or_b32_e32 v154, v14, v17
	v_or_b32_e32 v16, v5, v16
	v_lshl_add_u64 v[18:19], v[154:155], 2, v[8:9]
	v_mov_b32_e32 v17, v155
	v_lshl_add_u64 v[16:17], v[16:17], 2, v[8:9]
	global_load_dword v64, v[18:19], off
	global_load_dword v65, v[16:17], off
	v_mad_u64_u32 v[16:17], s[22:23], v36, s38, v[4:5]
	v_mad_u64_u32 v[18:19], s[22:23], v35, s38, v[4:5]
	s_add_i32 s22, s20, 4
	s_add_i32 s21, s19, 4
	v_or_b32_e32 v36, s22, v2
	v_or_b32_e32 v35, s21, v1
	v_add_lshl_u32 v17, v36, v10, 10
	v_or_b32_e32 v154, v14, v17
	v_mov_b32_e32 v17, v155
	s_add_i32 s21, s19, 8
	s_add_i32 s17, s17, 16
	s_add_i32 s16, s16, 16
	s_add_i32 s18, s18, -16
	v_mov_b32_e32 v80, v16
	v_mov_b32_e32 v81, v18
	v_add_lshl_u32 v16, v35, v3, 10
	v_or_b32_e32 v16, v5, v16
	v_lshl_add_u64 v[18:19], v[154:155], 2, v[8:9]
	v_lshl_add_u64 v[16:17], v[16:17], 2, v[8:9]
	global_load_dword v66, v[18:19], off
	global_load_dword v67, v[16:17], off
	v_mad_u64_u32 v[16:17], s[22:23], v36, s38, v[4:5]
	v_mad_u64_u32 v[18:19], s[22:23], v35, s38, v[4:5]
	s_add_i32 s22, s20, 8
	s_nop 0
	v_or_b32_e32 v36, s22, v2
	v_or_b32_e32 v35, s21, v1
	v_add_lshl_u32 v17, v36, v10, 10
	v_or_b32_e32 v154, v14, v17
	v_mov_b32_e32 v17, v155
	s_add_i32 s21, s19, 12
	v_mov_b32_e32 v82, v16
	v_mov_b32_e32 v83, v18
	v_add_lshl_u32 v16, v35, v3, 10
	v_or_b32_e32 v16, v5, v16
	v_lshl_add_u64 v[18:19], v[154:155], 2, v[8:9]
	v_lshl_add_u64 v[16:17], v[16:17], 2, v[8:9]
	global_load_dword v68, v[18:19], off
	global_load_dword v69, v[16:17], off
	v_mad_u64_u32 v[16:17], s[22:23], v36, s38, v[4:5]
	v_mad_u64_u32 v[18:19], s[22:23], v35, s38, v[4:5]
	s_add_i32 s22, s20, 12
	s_nop 0
	v_or_b32_e32 v36, s22, v2
	v_or_b32_e32 v35, s21, v1
	v_add_lshl_u32 v17, v36, v10, 10
	v_or_b32_e32 v154, v14, v17
	v_mov_b32_e32 v17, v155
	s_add_i32 s21, s19, 16
	v_mov_b32_e32 v84, v16
	v_mov_b32_e32 v85, v18
	v_add_lshl_u32 v16, v35, v3, 10
	v_or_b32_e32 v16, v5, v16
	v_lshl_add_u64 v[18:19], v[154:155], 2, v[8:9]
	v_lshl_add_u64 v[16:17], v[16:17], 2, v[8:9]
	global_load_dword v70, v[18:19], off
	global_load_dword v71, v[16:17], off
	v_mad_u64_u32 v[16:17], s[22:23], v36, s38, v[4:5]
	v_mad_u64_u32 v[18:19], s[22:23], v35, s38, v[4:5]
	s_add_i32 s22, s20, 16
	s_nop 0
	v_or_b32_e32 v36, s22, v2
	v_or_b32_e32 v35, s21, v1
	v_add_lshl_u32 v17, v36, v10, 10
	v_or_b32_e32 v154, v14, v17
	v_mov_b32_e32 v17, v155
	s_add_i32 s21, s19, 20
	v_mov_b32_e32 v86, v16
	v_mov_b32_e32 v87, v18
	v_add_lshl_u32 v16, v35, v3, 10
	v_or_b32_e32 v16, v5, v16
	v_lshl_add_u64 v[18:19], v[154:155], 2, v[8:9]
	v_lshl_add_u64 v[16:17], v[16:17], 2, v[8:9]
	global_load_dword v72, v[18:19], off
	global_load_dword v73, v[16:17], off
	v_mad_u64_u32 v[16:17], s[22:23], v36, s38, v[4:5]
	v_mad_u64_u32 v[18:19], s[22:23], v35, s38, v[4:5]
	s_add_i32 s22, s20, 20
	s_nop 0
	v_or_b32_e32 v36, s22, v2
	v_or_b32_e32 v35, s21, v1
	v_add_lshl_u32 v17, v36, v10, 10
	v_or_b32_e32 v154, v14, v17
	v_mov_b32_e32 v17, v155
	s_add_i32 s21, s19, 24
	s_add_i32 s19, s19, 28
	v_mov_b32_e32 v88, v16
	v_mov_b32_e32 v89, v18
	v_add_lshl_u32 v16, v35, v3, 10
	v_or_b32_e32 v16, v5, v16
	v_lshl_add_u64 v[18:19], v[154:155], 2, v[8:9]
	v_lshl_add_u64 v[16:17], v[16:17], 2, v[8:9]
	global_load_dword v74, v[18:19], off
	global_load_dword v75, v[16:17], off
	v_mad_u64_u32 v[16:17], s[22:23], v36, s38, v[4:5]
	v_mad_u64_u32 v[18:19], s[22:23], v35, s38, v[4:5]
	s_add_i32 s22, s20, 24
	s_nop 0
	v_or_b32_e32 v36, s22, v2
	v_or_b32_e32 v35, s21, v1
	v_add_lshl_u32 v17, v36, v10, 10
	v_or_b32_e32 v154, v14, v17
	v_mov_b32_e32 v17, v155
	s_add_i32 s20, s20, 28
	s_cmp_lg_u32 s18, 0
	v_mov_b32_e32 v90, v16
	v_mov_b32_e32 v91, v18
	v_add_lshl_u32 v16, v35, v3, 10
	v_or_b32_e32 v16, v5, v16
	v_lshl_add_u64 v[18:19], v[154:155], 2, v[8:9]
	v_lshl_add_u64 v[16:17], v[16:17], 2, v[8:9]
	global_load_dword v76, v[18:19], off
	global_load_dword v77, v[16:17], off
	v_mad_u64_u32 v[16:17], s[22:23], v36, s38, v[4:5]
	v_or_b32_e32 v36, s20, v2
	v_mad_u64_u32 v[18:19], s[22:23], v35, s38, v[4:5]
	v_or_b32_e32 v35, s19, v1
	v_add_lshl_u32 v17, v36, v10, 10
	v_or_b32_e32 v154, v14, v17
	v_mov_b32_e32 v19, v155
	v_mov_b32_e32 v92, v16
	v_mov_b32_e32 v93, v18
	v_add_lshl_u32 v16, v35, v3, 10
	v_or_b32_e32 v18, v5, v16
	v_lshl_add_u64 v[16:17], v[154:155], 2, v[8:9]
	v_lshl_add_u64 v[18:19], v[18:19], 2, v[8:9]
	global_load_dword v78, v[16:17], off
	global_load_dword v79, v[18:19], off
	v_mad_u64_u32 v[16:17], s[20:21], v36, s38, v[4:5]
	v_mad_u64_u32 v[18:19], s[20:21], v35, s38, v[4:5]
	v_mov_b32_e32 v94, v16
	v_mov_b32_e32 v95, v18
	s_waitcnt vmcnt(0)
	ds_write_b32 v80, v64
	ds_write_b32 v81, v65
	ds_write_b32 v82, v66
	ds_write_b32 v83, v67
	ds_write_b32 v84, v68
	ds_write_b32 v85, v69
	ds_write_b32 v86, v70
	ds_write_b32 v87, v71
	ds_write_b32 v88, v72
	ds_write_b32 v89, v73
	ds_write_b32 v90, v74
	ds_write_b32 v91, v75
	ds_write_b32 v92, v76
	ds_write_b32 v93, v77
	ds_write_b32 v94, v78
	ds_write_b32 v95, v79
	s_cbranch_scc1 .LBB0_376
; #define LAS __attribute__((address_space(3)))
; __device__ __forceinline__ unsigned pk2(float lo, float hi) { unsigned r; asm("v_cvt_pk_bf16_f32 %0, %1, %2" : "=v"(r) : "v"(lo), "v"(hi)); return r; }
; template <int MODE>
; __device__ __forceinline__ void transpose_item(const Args& a, int layer, int item, LAS float* scr, int lane) {
;     ...
;     asm volatile("s_waitcnt lgkmcnt(0)" ::: "memory");
;     const int c = lane & 7;
; #pragma unroll
;     for (int j = 0; j < 4; ++j) {
;         const int n = (lane >> 3) + 8 * j; const LAS float* s = scr + (8 * c) * 33 + n;
;         u32x4 o; o.x = pk2(s[0 * 33], s[1 * 33]); o.y = pk2(s[2 * 33], s[3 * 33]); o.z = pk2(s[4 * 33], s[5 * 33]); o.w = pk2(s[6 * 33], s[7 * 33]);
;         *(u32x4*)(WT + (size_t)(n0 + n) * K + k0 + 8 * c) = o;
;     }
;     asm volatile("s_waitcnt lgkmcnt(0)" ::: "memory");
	s_waitcnt lgkmcnt(0)
	v_lshl_add_u64 v[8:9], v[12:13], 1, s[6:7]
	ds_read2_b32 v[12:13], v24 offset0:33 offset1:41
	ds_read2_b32 v[36:37], v24 offset1:8
	ds_read2_b32 v[38:39], v24 offset0:66 offset1:74
	ds_read2_b32 v[40:41], v24 offset0:99 offset1:107
	ds_read2_b32 v[42:43], v24 offset0:132 offset1:140
	ds_read2_b32 v[44:45], v24 offset0:165 offset1:173
	ds_read2_b32 v[46:47], v24 offset0:198 offset1:206
	ds_read2_b32 v[48:49], v24 offset0:231 offset1:239
	v_lshlrev_b32_e32 v154, 1, v10
	v_lshl_add_u64 v[8:9], v[8:9], 0, v[154:155]
	v_lshlrev_b32_e32 v154, 1, v6
	v_or_b32_e32 v3, v11, v23
	v_lshl_add_u64 v[8:9], v[8:9], 0, v[154:155]
	v_lshlrev_b32_e32 v154, 11, v3
	v_lshl_add_u64 v[50:51], v[8:9], 0, v[154:155]
	s_waitcnt lgkmcnt(0)
	v_cvt_pk_bf16_f32 v16, v36, v12
	v_cvt_pk_bf16_f32 v17, v38, v40
	v_cvt_pk_bf16_f32 v18, v42, v44
	v_cvt_pk_bf16_f32 v19, v46, v48
	global_store_dwordx4 v[50:51], v[16:19], off
	v_or_b32_e32 v3, v11, v25
	v_lshlrev_b32_e32 v154, 11, v3
	v_cvt_pk_bf16_f32 v16, v37, v13
	v_cvt_pk_bf16_f32 v17, v39, v41
	v_cvt_pk_bf16_f32 v18, v43, v45
	v_cvt_pk_bf16_f32 v19, v47, v49
	ds_read2_b32 v[36:37], v24 offset0:16 offset1:24
	ds_read2_b32 v[38:39], v24 offset0:49 offset1:57
	ds_read2_b32 v[40:41], v24 offset0:82 offset1:90
	ds_read2_b32 v[42:43], v24 offset0:115 offset1:123
	ds_read2_b32 v[44:45], v24 offset0:148 offset1:156
	ds_read2_b32 v[46:47], v24 offset0:181 offset1:189
	ds_read2_b32 v[48:49], v24 offset0:214 offset1:222
	ds_read2_b32 v[50:51], v24 offset0:247 offset1:255
	v_or_b32_e32 v3, v11, v26
	v_lshl_add_u64 v[12:13], v[8:9], 0, v[154:155]
	v_lshlrev_b32_e32 v154, 11, v3
	v_or_b32_e32 v3, v11, v27
	global_store_dwordx4 v[12:13], v[16:19], off
	v_lshl_add_u64 v[12:13], v[8:9], 0, v[154:155]
	v_lshlrev_b32_e32 v154, 11, v3
	s_waitcnt lgkmcnt(6)
	v_cvt_pk_bf16_f32 v16, v36, v38
	s_waitcnt lgkmcnt(4)
	v_cvt_pk_bf16_f32 v17, v40, v42
	s_waitcnt lgkmcnt(2)
	v_cvt_pk_bf16_f32 v18, v44, v46
	s_waitcnt lgkmcnt(0)
	v_cvt_pk_bf16_f32 v19, v48, v50
	v_lshl_add_u64 v[8:9], v[8:9], 0, v[154:155]
	global_store_dwordx4 v[12:13], v[16:19], off
	s_nop 1
	v_cvt_pk_bf16_f32 v16, v37, v39
	v_cvt_pk_bf16_f32 v17, v41, v43
	v_cvt_pk_bf16_f32 v18, v45, v47
	v_cvt_pk_bf16_f32 v19, v49, v51
	global_store_dwordx4 v[8:9], v[16:19], off
	s_waitcnt lgkmcnt(0)

; template <int MODE>
; __device__ __forceinline__ void transpose_item(const Args& a, int layer, int item, LAS float* scr, int lane) {
;     ...
;     if (MODE == 0) { src = a.in[5] + (size_t)layer * DM * PW; col = colmap_in(R); }
;     ...
; #pragma unroll 8
;     for (int i = 0; i < 32; ++i) { const int kk = 2 * i + (lane >> 5); scr[kk * 33 + (lane & 31)] = src[(size_t)(k0 + kk) * N + col]; }
.LBB0_381:
	s_lshl_b32 s18, s16, 1
	s_lshl_b32 s17, s14, 1
	v_or_b32_e32 v11, s18, v2
	v_or_b32_e32 v9, s17, v1
	v_add_u32_e32 v16, v11, v10
	v_add_u32_e32 v14, v9, v3
	v_mul_lo_u32 v16, v16, s39
	v_mul_lo_u32 v18, v14, s39
	v_ashrrev_i32_e32 v17, 31, v16
	v_ashrrev_i32_e32 v19, 31, v18
	v_lshl_add_u64 v[16:17], v[12:13], 0, v[16:17]
	v_lshl_add_u64 v[18:19], v[12:13], 0, v[18:19]
	global_load_dword v64, v[16:17], off
	global_load_dword v65, v[18:19], off
	v_mad_u64_u32 v[16:17], s[20:21], v11, s38, v[4:5]
	v_mad_u64_u32 v[18:19], s[20:21], v9, s38, v[4:5]
	s_add_i32 s20, s18, 4
	s_add_i32 s19, s17, 4
	v_or_b32_e32 v11, s20, v2
	v_or_b32_e32 v9, s19, v1
	s_add_i32 s19, s17, 8
	s_add_i32 s16, s16, 16
	s_add_i32 s14, s14, 16
	s_add_i32 s15, s15, -16
	v_mov_b32_e32 v80, v16
	v_mov_b32_e32 v81, v18
	v_add_u32_e32 v16, v11, v10
	v_add_u32_e32 v14, v9, v3
	v_mul_lo_u32 v16, v16, s39
	v_mul_lo_u32 v18, v14, s39
	v_ashrrev_i32_e32 v17, 31, v16
	v_ashrrev_i32_e32 v19, 31, v18
	v_lshl_add_u64 v[16:17], v[12:13], 0, v[16:17]
	v_lshl_add_u64 v[18:19], v[12:13], 0, v[18:19]
	global_load_dword v66, v[16:17], off
	global_load_dword v67, v[18:19], off
	v_mad_u64_u32 v[16:17], s[20:21], v11, s38, v[4:5]
	v_mad_u64_u32 v[18:19], s[20:21], v9, s38, v[4:5]
	s_add_i32 s20, s18, 8
	s_nop 0
	v_or_b32_e32 v11, s20, v2
	v_or_b32_e32 v9, s19, v1
	s_add_i32 s19, s17, 12
	v_mov_b32_e32 v82, v16
	v_mov_b32_e32 v83, v18
	v_add_u32_e32 v16, v11, v10
	v_add_u32_e32 v14, v9, v3
	v_mul_lo_u32 v16, v16, s39
	v_mul_lo_u32 v18, v14, s39
	v_ashrrev_i32_e32 v17, 31, v16
	v_ashrrev_i32_e32 v19, 31, v18
	v_lshl_add_u64 v[16:17], v[12:13], 0, v[16:17]
	v_lshl_add_u64 v[18:19], v[12:13], 0, v[18:19]
	global_load_dword v68, v[16:17], off
	global_load_dword v69, v[18:19], off
	v_mad_u64_u32 v[16:17], s[20:21], v11, s38, v[4:5]
	v_mad_u64_u32 v[18:19], s[20:21], v9, s38, v[4:5]
	s_add_i32 s20, s18, 12
	s_nop 0
	v_or_b32_e32 v11, s20, v2
	v_or_b32_e32 v9, s19, v1
	s_add_i32 s19, s17, 16
	v_mov_b32_e32 v84, v16
	v_mov_b32_e32 v85, v18
	v_add_u32_e32 v16, v11, v10
	v_add_u32_e32 v14, v9, v3
	v_mul_lo_u32 v16, v16, s39
	v_mul_lo_u32 v18, v14, s39
	v_ashrrev_i32_e32 v17, 31, v16
	v_ashrrev_i32_e32 v19, 31, v18
	v_lshl_add_u64 v[16:17], v[12:13], 0, v[16:17]
	v_lshl_add_u64 v[18:19], v[12:13], 0, v[18:19]
	global_load_dword v70, v[16:17], off
	global_load_dword v71, v[18:19], off
	v_mad_u64_u32 v[16:17], s[20:21], v11, s38, v[4:5]
	v_mad_u64_u32 v[18:19], s[20:21], v9, s38, v[4:5]
	s_add_i32 s20, s18, 16
	s_nop 0
	v_or_b32_e32 v11, s20, v2
	v_or_b32_e32 v9, s19, v1
	s_add_i32 s19, s17, 20
	v_mov_b32_e32 v86, v16
	v_mov_b32_e32 v87, v18
	v_add_u32_e32 v16, v11, v10
	v_add_u32_e32 v14, v9, v3
	v_mul_lo_u32 v16, v16, s39
	v_mul_lo_u32 v18, v14, s39
	v_ashrrev_i32_e32 v17, 31, v16
	v_ashrrev_i32_e32 v19, 31, v18
	v_lshl_add_u64 v[16:17], v[12:13], 0, v[16:17]
	v_lshl_add_u64 v[18:19], v[12:13], 0, v[18:19]
	global_load_dword v72, v[16:17], off
	global_load_dword v73, v[18:19], off
	v_mad_u64_u32 v[16:17], s[20:21], v11, s38, v[4:5]
	v_mad_u64_u32 v[18:19], s[20:21], v9, s38, v[4:5]
	s_add_i32 s20, s18, 20
	s_nop 0
	v_or_b32_e32 v11, s20, v2
	v_or_b32_e32 v9, s19, v1
	s_add_i32 s19, s17, 24
	s_add_i32 s17, s17, 28
	v_mov_b32_e32 v88, v16
	v_mov_b32_e32 v89, v18
	v_add_u32_e32 v16, v11, v10
	v_add_u32_e32 v14, v9, v3
	v_mul_lo_u32 v16, v16, s39
	v_mul_lo_u32 v18, v14, s39
	v_ashrrev_i32_e32 v17, 31, v16
	v_ashrrev_i32_e32 v19, 31, v18
	v_lshl_add_u64 v[16:17], v[12:13], 0, v[16:17]
	v_lshl_add_u64 v[18:19], v[12:13], 0, v[18:19]
	global_load_dword v74, v[16:17], off
	global_load_dword v75, v[18:19], off
	v_mad_u64_u32 v[16:17], s[20:21], v11, s38, v[4:5]
	v_mad_u64_u32 v[18:19], s[20:21], v9, s38, v[4:5]
	s_add_i32 s20, s18, 24
	s_nop 0
	v_or_b32_e32 v11, s20, v2
	v_or_b32_e32 v9, s19, v1
	s_add_i32 s18, s18, 28
	s_cmp_lg_u32 s15, 0
	v_mov_b32_e32 v90, v16
	v_mov_b32_e32 v91, v18
	v_add_u32_e32 v16, v11, v10
	v_add_u32_e32 v14, v9, v3
	v_mul_lo_u32 v16, v16, s39
	v_mul_lo_u32 v18, v14, s39
	v_ashrrev_i32_e32 v17, 31, v16
	v_ashrrev_i32_e32 v19, 31, v18
	v_lshl_add_u64 v[16:17], v[12:13], 0, v[16:17]
	v_lshl_add_u64 v[18:19], v[12:13], 0, v[18:19]
	global_load_dword v76, v[16:17], off
	global_load_dword v77, v[18:19], off
	v_mad_u64_u32 v[16:17], s[20:21], v11, s38, v[4:5]
	v_or_b32_e32 v11, s18, v2
	v_mad_u64_u32 v[18:19], s[20:21], v9, s38, v[4:5]
	v_or_b32_e32 v9, s17, v1
	v_mov_b32_e32 v92, v16
	v_mov_b32_e32 v93, v18
	v_add_u32_e32 v16, v11, v10
	v_add_u32_e32 v14, v9, v3
	v_mul_lo_u32 v16, v16, s39
	v_mul_lo_u32 v18, v14, s39
	v_ashrrev_i32_e32 v17, 31, v16
	v_ashrrev_i32_e32 v19, 31, v18
	v_lshl_add_u64 v[16:17], v[12:13], 0, v[16:17]
	v_lshl_add_u64 v[18:19], v[12:13], 0, v[18:19]
	global_load_dword v78, v[16:17], off
	global_load_dword v79, v[18:19], off
	v_mad_u64_u32 v[16:17], s[18:19], v11, s38, v[4:5]
	v_mad_u64_u32 v[18:19], s[18:19], v9, s38, v[4:5]
	v_mov_b32_e32 v94, v16
	v_mov_b32_e32 v95, v18
	s_waitcnt vmcnt(0)
	ds_write_b32 v80, v64
	ds_write_b32 v81, v65
	ds_write_b32 v82, v66
	ds_write_b32 v83, v67
	ds_write_b32 v84, v68
	ds_write_b32 v85, v69
	ds_write_b32 v86, v70
	ds_write_b32 v87, v71
	ds_write_b32 v88, v72
	ds_write_b32 v89, v73
	ds_write_b32 v90, v74
	ds_write_b32 v91, v75
	ds_write_b32 v92, v76
	ds_write_b32 v93, v77
	ds_write_b32 v94, v78
	ds_write_b32 v95, v79
	s_cbranch_scc1 .LBB0_381
; #define LAS __attribute__((address_space(3)))
; __device__ __forceinline__ unsigned pk2(float lo, float hi) { unsigned r; asm("v_cvt_pk_bf16_f32 %0, %1, %2" : "=v"(r) : "v"(lo), "v"(hi)); return r; }
; template <int MODE>
; __device__ __forceinline__ void transpose_item(const Args& a, int layer, int item, LAS float* scr, int lane) {
;     ...
;     bf16_t* WT = (bf16_t*)(a.ws + (MODE == 0 ? WS_WIN : MODE == 1 ? WS_WOUT : MODE == 2 ? WS_WGU : WS_WDN)) + (size_t)layer * NP * K;
;     ...
;     asm volatile("s_waitcnt lgkmcnt(0)" ::: "memory");
;     const int c = lane & 7;
; #pragma unroll
;     for (int j = 0; j < 4; ++j) {
;         const int n = (lane >> 3) + 8 * j; const LAS float* s = scr + (8 * c) * 33 + n;
;         u32x4 o; o.x = pk2(s[0 * 33], s[1 * 33]); o.y = pk2(s[2 * 33], s[3 * 33]); o.z = pk2(s[4 * 33], s[5 * 33]); o.w = pk2(s[6 * 33], s[7 * 33]);
;         *(u32x4*)(WT + (size_t)(n0 + n) * K + k0 + 8 * c) = o;
;     }
;     asm volatile("s_waitcnt lgkmcnt(0)" ::: "memory");
	s_waitcnt lgkmcnt(0)
	v_mul_hi_i32_i24_e32 v9, 0x500000, v8
	v_mul_i32_i24_e32 v8, 0x500000, v8
	ds_read2_b32 v[12:13], v24 offset0:33 offset1:41
	ds_read2_b32 v[16:17], v24 offset1:8
	ds_read2_b32 v[18:19], v24 offset0:66 offset1:74
	ds_read2_b32 v[36:37], v24 offset0:99 offset1:107
	ds_read2_b32 v[38:39], v24 offset0:132 offset1:140
	ds_read2_b32 v[40:41], v24 offset0:165 offset1:173
	ds_read2_b32 v[42:43], v24 offset0:198 offset1:206
	ds_read2_b32 v[44:45], v24 offset0:231 offset1:239
	v_lshl_add_u64 v[8:9], s[8:9], 0, v[8:9]
	v_ashrrev_i32_e32 v11, 31, v10
	v_or_b32_e32 v48, v5, v23
	v_lshl_add_u64 v[8:9], v[10:11], 1, v[8:9]
	v_lshlrev_b32_e32 v154, 1, v6
	v_ashrrev_i32_e32 v49, 31, v48
	v_lshl_add_u64 v[46:47], v[8:9], 0, v[154:155]
	v_lshlrev_b64 v[48:49], 11, v[48:49]
	s_waitcnt lgkmcnt(0)
	v_cvt_pk_bf16_f32 v8, v16, v12
	v_lshl_add_u64 v[48:49], v[46:47], 0, v[48:49]
	v_or_b32_e32 v12, v5, v25
	v_cvt_pk_bf16_f32 v9, v18, v36
	v_cvt_pk_bf16_f32 v10, v38, v40
	v_cvt_pk_bf16_f32 v11, v42, v44
	global_store_dwordx4 v[48:49], v[8:11], off
	s_nop 1
	v_cvt_pk_bf16_f32 v8, v17, v13
	v_ashrrev_i32_e32 v13, 31, v12
	v_lshlrev_b64 v[12:13], 11, v[12:13]
	v_cvt_pk_bf16_f32 v9, v19, v37
	v_cvt_pk_bf16_f32 v10, v39, v41
	v_cvt_pk_bf16_f32 v11, v43, v45
	v_lshl_add_u64 v[12:13], v[46:47], 0, v[12:13]
	ds_read2_b32 v[16:17], v24 offset0:16 offset1:24
	ds_read2_b32 v[18:19], v24 offset0:49 offset1:57
	ds_read2_b32 v[36:37], v24 offset0:82 offset1:90
	ds_read2_b32 v[38:39], v24 offset0:115 offset1:123
	ds_read2_b32 v[40:41], v24 offset0:148 offset1:156
	ds_read2_b32 v[42:43], v24 offset0:181 offset1:189
	ds_read2_b32 v[44:45], v24 offset0:214 offset1:222
	ds_read2_b32 v[48:49], v24 offset0:247 offset1:255
	global_store_dwordx4 v[12:13], v[8:11], off
	v_or_b32_e32 v12, v5, v26
	v_ashrrev_i32_e32 v13, 31, v12
	v_lshlrev_b64 v[12:13], 11, v[12:13]
	v_lshl_add_u64 v[12:13], v[46:47], 0, v[12:13]
	s_waitcnt lgkmcnt(6)
	v_cvt_pk_bf16_f32 v8, v16, v18
	s_waitcnt lgkmcnt(4)
	v_cvt_pk_bf16_f32 v9, v36, v38
	s_waitcnt lgkmcnt(2)
	v_cvt_pk_bf16_f32 v10, v40, v42
	s_waitcnt lgkmcnt(0)
	v_cvt_pk_bf16_f32 v11, v44, v48
	global_store_dwordx4 v[12:13], v[8:11], off
	v_or_b32_e32 v12, v5, v27
	v_ashrrev_i32_e32 v13, 31, v12
	v_lshlrev_b64 v[12:13], 11, v[12:13]
	v_lshl_add_u64 v[12:13], v[46:47], 0, v[12:13]
	v_cvt_pk_bf16_f32 v8, v17, v19
	v_cvt_pk_bf16_f32 v9, v37, v39
	v_cvt_pk_bf16_f32 v10, v41, v43
	v_cvt_pk_bf16_f32 v11, v45, v49
	global_store_dwordx4 v[12:13], v[8:11], off
	s_waitcnt lgkmcnt(0)
	s_branch .LBB0_362

; __device__ __forceinline__ void hyena_raw4(const Args& a, int L, int t0, LAS float* scr, int lane) {
;     ...
; #pragma unroll 1
;     for (int k0 = 0; k0 < 64; k0 += 4) {
;         float wv[4][16];
; #pragma unroll
;         for (int k = 0; k < 4; ++k)
; #pragma unroll
;             for (int mth = 0; mth < 16; ++mth) wv[k][mth] = w3[(k0 + k) * 1024 + lane + 64 * mth];
; #pragma unroll
;         for (int p = 0; p < 4; ++p)
; #pragma unroll
;             for (int k = 0; k < 4; ++k) { const float hk = scr[192 * p + 128 + k0 + k];
; #pragma unroll
;                 for (int mth = 0; mth < 16; ++mth) o[p][mth] += hk * wv[k][mth]; }
.LBB0_414:
	s_movk_i32 s1, 0xd000
	v_add_co_u32_e32 v114, vcc, s1, v86
	s_movk_i32 s1, 0xe000
	s_nop 0
	v_addc_co_u32_e32 v115, vcc, -1, v87, vcc
	v_add_co_u32_e32 v146, vcc, s1, v86
	global_load_dword v128, v[114:115], off offset:-3840
	global_load_dword v129, v[114:115], off offset:-3584
	global_load_dword v126, v[114:115], off offset:-3328
	global_load_dword v127, v[114:115], off offset:-3072
	global_load_dword v124, v[114:115], off offset:-2816
	global_load_dword v125, v[114:115], off offset:-2560
	global_load_dword v122, v[114:115], off offset:-2304
	global_load_dword v123, v[114:115], off offset:-2048
	global_load_dword v120, v[114:115], off offset:-1792
	global_load_dword v121, v[114:115], off offset:-1536
	global_load_dword v118, v[114:115], off offset:-1280
	global_load_dword v119, v[114:115], off offset:-1024
	global_load_dword v116, v[114:115], off offset:-768
	global_load_dword v117, v[114:115], off offset:-512
	s_nop 0
	global_load_dword v114, v[114:115], off offset:-256
	v_addc_co_u32_e32 v147, vcc, -1, v87, vcc
	global_load_dword v115, v[146:147], off offset:-4096
	global_load_dword v144, v[146:147], off offset:-3840
	global_load_dword v145, v[146:147], off offset:-3584
	global_load_dword v142, v[146:147], off offset:-3328
	global_load_dword v143, v[146:147], off offset:-3072
	global_load_dword v140, v[146:147], off offset:-2816
	global_load_dword v141, v[146:147], off offset:-2560
	global_load_dword v138, v[146:147], off offset:-2304
	global_load_dword v139, v[146:147], off offset:-2048
	global_load_dword v136, v[146:147], off offset:-1792
	global_load_dword v137, v[146:147], off offset:-1536
	global_load_dword v134, v[146:147], off offset:-1280
	global_load_dword v135, v[146:147], off offset:-1024
	global_load_dword v132, v[146:147], off offset:-768
	global_load_dword v133, v[146:147], off offset:-512
	global_load_dword v130, v[146:147], off offset:-256
	global_load_dword v131, v[146:147], off
	s_movk_i32 s1, 0xf000
	v_add_co_u32_e32 v146, vcc, s1, v86
	s_add_i32 s0, s0, 4
	s_nop 0
	v_addc_co_u32_e32 v147, vcc, -1, v87, vcc
	global_load_dword v184, v[146:147], off offset:-3840
	global_load_dword v185, v[146:147], off offset:-3584
	global_load_dword v182, v[146:147], off offset:-3328
	global_load_dword v183, v[146:147], off offset:-3072
	global_load_dword v180, v[146:147], off offset:-2816
	global_load_dword v181, v[146:147], off offset:-2560
	global_load_dword v178, v[146:147], off offset:-2304
	global_load_dword v179, v[146:147], off offset:-2048
	global_load_dword v176, v[146:147], off offset:-1792
	global_load_dword v177, v[146:147], off offset:-1536
	global_load_dword v150, v[146:147], off offset:-1280
	global_load_dword v151, v[146:147], off offset:-1024
	global_load_dword v148, v[146:147], off offset:-768
	global_load_dword v149, v[146:147], off offset:-512
	s_nop 0
	global_load_dword v146, v[146:147], off offset:-256
	s_nop 0
	global_load_dword v147, v[86:87], off offset:-4096
	global_load_dword v200, v[86:87], off offset:-3840
	global_load_dword v201, v[86:87], off offset:-3584
	global_load_dword v198, v[86:87], off offset:-3328
	global_load_dword v199, v[86:87], off offset:-3072
	global_load_dword v196, v[86:87], off offset:-2816
	global_load_dword v197, v[86:87], off offset:-2560
	global_load_dword v194, v[86:87], off offset:-2304
	global_load_dword v195, v[86:87], off offset:-2048
	global_load_dword v192, v[86:87], off offset:-1792
	global_load_dword v193, v[86:87], off offset:-1536
	global_load_dword v190, v[86:87], off offset:-1280
	global_load_dword v191, v[86:87], off offset:-1024
	global_load_dword v188, v[86:87], off offset:-768
	global_load_dword v189, v[86:87], off offset:-512
	global_load_dword v186, v[86:87], off offset:-256
	global_load_dword v187, v[86:87], off
	ds_read_b128 v[208:211], v15
	v_lshl_add_u64 v[86:87], v[86:87], 0, s[2:3]
	s_cmp_lt_u32 s0, 60
	s_waitcnt lgkmcnt(0)
	v_mov_b32_e32 v154, v211
	s_waitcnt vmcnt(62)
	v_pk_fma_f32 v[112:113], v[128:129], v[208:209], v[112:113] op_sel_hi:[1,0,1]
	s_waitcnt vmcnt(60)
	v_pk_fma_f32 v[110:111], v[126:127], v[208:209], v[110:111] op_sel_hi:[1,0,1]
	s_waitcnt vmcnt(46)
	v_pk_fma_f32 v[112:113], v[144:145], v[208:209], v[112:113] op_sel:[0,1,0]
	v_pk_fma_f32 v[108:109], v[124:125], v[208:209], v[108:109] op_sel_hi:[1,0,1]
	s_waitcnt vmcnt(44)
	v_pk_fma_f32 v[110:111], v[142:143], v[208:209], v[110:111] op_sel:[0,1,0]
	v_pk_fma_f32 v[106:107], v[122:123], v[208:209], v[106:107] op_sel_hi:[1,0,1]
	s_waitcnt vmcnt(42)
	v_pk_fma_f32 v[108:109], v[140:141], v[208:209], v[108:109] op_sel:[0,1,0]
	v_pk_fma_f32 v[104:105], v[120:121], v[208:209], v[104:105] op_sel_hi:[1,0,1]
	s_waitcnt vmcnt(40)
	v_pk_fma_f32 v[106:107], v[138:139], v[208:209], v[106:107] op_sel:[0,1,0]
	v_pk_fma_f32 v[102:103], v[118:119], v[208:209], v[102:103] op_sel_hi:[1,0,1]
	s_waitcnt vmcnt(38)
	v_pk_fma_f32 v[104:105], v[136:137], v[208:209], v[104:105] op_sel:[0,1,0]
	v_pk_fma_f32 v[100:101], v[116:117], v[208:209], v[100:101] op_sel_hi:[1,0,1]
	v_pk_fma_f32 v[98:99], v[114:115], v[208:209], v[98:99] op_sel_hi:[1,0,1]
	s_waitcnt vmcnt(36)
	v_pk_fma_f32 v[102:103], v[134:135], v[208:209], v[102:103] op_sel:[0,1,0]
	s_waitcnt vmcnt(34)
	v_pk_fma_f32 v[100:101], v[132:133], v[208:209], v[100:101] op_sel:[0,1,0]
	s_waitcnt vmcnt(32)
	v_pk_fma_f32 v[98:99], v[130:131], v[208:209], v[98:99] op_sel:[0,1,0]
	s_waitcnt vmcnt(30)
	v_pk_fma_f32 v[112:113], v[184:185], v[210:211], v[112:113] op_sel_hi:[1,0,1]
	s_waitcnt vmcnt(28)
	v_pk_fma_f32 v[110:111], v[182:183], v[210:211], v[110:111] op_sel_hi:[1,0,1]
	s_waitcnt vmcnt(26)
	v_pk_fma_f32 v[108:109], v[180:181], v[210:211], v[108:109] op_sel_hi:[1,0,1]
	s_waitcnt vmcnt(24)
; __device__ __forceinline__ void hyena_raw4(const Args& a, int L, int t0, LAS float* scr, int lane) {
;     ...
; #pragma unroll
;         for (int p = 0; p < 4; ++p)
; #pragma unroll
;             for (int k = 0; k < 4; ++k) { const float hk = scr[192 * p + 128 + k0 + k];
; #pragma unroll
;                 for (int mth = 0; mth < 16; ++mth) o[p][mth] += hk * wv[k][mth]; }
	v_pk_fma_f32 v[106:107], v[178:179], v[210:211], v[106:107] op_sel_hi:[1,0,1]
	s_waitcnt vmcnt(22)
	v_pk_fma_f32 v[104:105], v[176:177], v[210:211], v[104:105] op_sel_hi:[1,0,1]
	s_waitcnt vmcnt(20)
	v_pk_fma_f32 v[102:103], v[150:151], v[210:211], v[102:103] op_sel_hi:[1,0,1]
	s_waitcnt vmcnt(18)
	v_pk_fma_f32 v[100:101], v[148:149], v[210:211], v[100:101] op_sel_hi:[1,0,1]
	s_waitcnt vmcnt(16)
	v_pk_fma_f32 v[98:99], v[146:147], v[210:211], v[98:99] op_sel_hi:[1,0,1]
	ds_read_b128 v[208:211], v15 offset:768
	s_waitcnt vmcnt(14)
	v_pk_fma_f32 v[112:113], v[200:201], v[154:155], v[112:113] op_sel_hi:[1,0,1]
	s_waitcnt vmcnt(12)
	v_pk_fma_f32 v[110:111], v[198:199], v[154:155], v[110:111] op_sel_hi:[1,0,1]
	s_waitcnt vmcnt(10)
	v_pk_fma_f32 v[108:109], v[196:197], v[154:155], v[108:109] op_sel_hi:[1,0,1]
	s_waitcnt vmcnt(8)
	v_pk_fma_f32 v[106:107], v[194:195], v[154:155], v[106:107] op_sel_hi:[1,0,1]
	s_waitcnt lgkmcnt(0)
	v_pk_fma_f32 v[96:97], v[128:129], v[208:209], v[96:97] op_sel_hi:[1,0,1]
	v_pk_fma_f32 v[94:95], v[126:127], v[208:209], v[94:95] op_sel_hi:[1,0,1]
	v_pk_fma_f32 v[92:93], v[124:125], v[208:209], v[92:93] op_sel_hi:[1,0,1]
	v_pk_fma_f32 v[90:91], v[122:123], v[208:209], v[90:91] op_sel_hi:[1,0,1]
	v_pk_fma_f32 v[88:89], v[120:121], v[208:209], v[88:89] op_sel_hi:[1,0,1]
	v_pk_fma_f32 v[84:85], v[118:119], v[208:209], v[84:85] op_sel_hi:[1,0,1]
	v_pk_fma_f32 v[82:83], v[116:117], v[208:209], v[82:83] op_sel_hi:[1,0,1]
	v_pk_fma_f32 v[80:81], v[114:115], v[208:209], v[80:81] op_sel_hi:[1,0,1]
	v_pk_fma_f32 v[96:97], v[144:145], v[208:209], v[96:97] op_sel:[0,1,0]
	v_pk_fma_f32 v[94:95], v[142:143], v[208:209], v[94:95] op_sel:[0,1,0]
	v_pk_fma_f32 v[92:93], v[140:141], v[208:209], v[92:93] op_sel:[0,1,0]
	v_pk_fma_f32 v[90:91], v[138:139], v[208:209], v[90:91] op_sel:[0,1,0]
	v_pk_fma_f32 v[88:89], v[136:137], v[208:209], v[88:89] op_sel:[0,1,0]
	v_pk_fma_f32 v[84:85], v[134:135], v[208:209], v[84:85] op_sel:[0,1,0]
	v_pk_fma_f32 v[82:83], v[132:133], v[208:209], v[82:83] op_sel:[0,1,0]
	v_pk_fma_f32 v[80:81], v[130:131], v[208:209], v[80:81] op_sel:[0,1,0]
	s_waitcnt vmcnt(6)
	v_pk_fma_f32 v[104:105], v[192:193], v[154:155], v[104:105] op_sel_hi:[1,0,1]
	s_waitcnt vmcnt(4)
	v_pk_fma_f32 v[102:103], v[190:191], v[154:155], v[102:103] op_sel_hi:[1,0,1]
	s_waitcnt vmcnt(2)
	v_pk_fma_f32 v[100:101], v[188:189], v[154:155], v[100:101] op_sel_hi:[1,0,1]
	s_waitcnt vmcnt(0)
	v_pk_fma_f32 v[98:99], v[186:187], v[154:155], v[98:99] op_sel_hi:[1,0,1]
	v_pk_fma_f32 v[96:97], v[184:185], v[210:211], v[96:97] op_sel_hi:[1,0,1]
	v_mov_b32_e32 v154, v211
	v_pk_fma_f32 v[94:95], v[182:183], v[210:211], v[94:95] op_sel_hi:[1,0,1]
	v_pk_fma_f32 v[92:93], v[180:181], v[210:211], v[92:93] op_sel_hi:[1,0,1]
	v_pk_fma_f32 v[90:91], v[178:179], v[210:211], v[90:91] op_sel_hi:[1,0,1]
	v_pk_fma_f32 v[88:89], v[176:177], v[210:211], v[88:89] op_sel_hi:[1,0,1]
	v_pk_fma_f32 v[84:85], v[150:151], v[210:211], v[84:85] op_sel_hi:[1,0,1]
	v_pk_fma_f32 v[82:83], v[148:149], v[210:211], v[82:83] op_sel_hi:[1,0,1]
	v_pk_fma_f32 v[80:81], v[146:147], v[210:211], v[80:81] op_sel_hi:[1,0,1]
	ds_read_b128 v[208:211], v15 offset:1536
	v_pk_fma_f32 v[96:97], v[200:201], v[154:155], v[96:97] op_sel_hi:[1,0,1]
	v_pk_fma_f32 v[94:95], v[198:199], v[154:155], v[94:95] op_sel_hi:[1,0,1]
	v_pk_fma_f32 v[92:93], v[196:197], v[154:155], v[92:93] op_sel_hi:[1,0,1]
	v_pk_fma_f32 v[90:91], v[194:195], v[154:155], v[90:91] op_sel_hi:[1,0,1]
	s_waitcnt lgkmcnt(0)
	v_pk_fma_f32 v[78:79], v[128:129], v[208:209], v[78:79] op_sel_hi:[1,0,1]
	v_pk_fma_f32 v[76:77], v[126:127], v[208:209], v[76:77] op_sel_hi:[1,0,1]
	v_pk_fma_f32 v[74:75], v[124:125], v[208:209], v[74:75] op_sel_hi:[1,0,1]
	v_pk_fma_f32 v[72:73], v[122:123], v[208:209], v[72:73] op_sel_hi:[1,0,1]
	v_pk_fma_f32 v[68:69], v[120:121], v[208:209], v[68:69] op_sel_hi:[1,0,1]
	v_pk_fma_f32 v[66:67], v[118:119], v[208:209], v[66:67] op_sel_hi:[1,0,1]
	v_pk_fma_f32 v[64:65], v[116:117], v[208:209], v[64:65] op_sel_hi:[1,0,1]
	v_pk_fma_f32 v[62:63], v[114:115], v[208:209], v[62:63] op_sel_hi:[1,0,1]
	v_pk_fma_f32 v[78:79], v[144:145], v[208:209], v[78:79] op_sel:[0,1,0]
	v_pk_fma_f32 v[76:77], v[142:143], v[208:209], v[76:77] op_sel:[0,1,0]
	v_pk_fma_f32 v[74:75], v[140:141], v[208:209], v[74:75] op_sel:[0,1,0]
	v_pk_fma_f32 v[72:73], v[138:139], v[208:209], v[72:73] op_sel:[0,1,0]
	v_pk_fma_f32 v[68:69], v[136:137], v[208:209], v[68:69] op_sel:[0,1,0]
	v_pk_fma_f32 v[66:67], v[134:135], v[208:209], v[66:67] op_sel:[0,1,0]
	v_pk_fma_f32 v[64:65], v[132:133], v[208:209], v[64:65] op_sel:[0,1,0]
	v_pk_fma_f32 v[62:63], v[130:131], v[208:209], v[62:63] op_sel:[0,1,0]
	v_pk_fma_f32 v[88:89], v[192:193], v[154:155], v[88:89] op_sel_hi:[1,0,1]
	v_pk_fma_f32 v[84:85], v[190:191], v[154:155], v[84:85] op_sel_hi:[1,0,1]
	v_pk_fma_f32 v[82:83], v[188:189], v[154:155], v[82:83] op_sel_hi:[1,0,1]
	v_pk_fma_f32 v[80:81], v[186:187], v[154:155], v[80:81] op_sel_hi:[1,0,1]
	v_pk_fma_f32 v[78:79], v[184:185], v[210:211], v[78:79] op_sel_hi:[1,0,1]
	v_mov_b32_e32 v154, v211
	v_pk_fma_f32 v[76:77], v[182:183], v[210:211], v[76:77] op_sel_hi:[1,0,1]
	v_pk_fma_f32 v[74:75], v[180:181], v[210:211], v[74:75] op_sel_hi:[1,0,1]
	v_pk_fma_f32 v[72:73], v[178:179], v[210:211], v[72:73] op_sel_hi:[1,0,1]
	v_pk_fma_f32 v[68:69], v[176:177], v[210:211], v[68:69] op_sel_hi:[1,0,1]
	v_pk_fma_f32 v[66:67], v[150:151], v[210:211], v[66:67] op_sel_hi:[1,0,1]
	v_pk_fma_f32 v[64:65], v[148:149], v[210:211], v[64:65] op_sel_hi:[1,0,1]
	v_pk_fma_f32 v[62:63], v[146:147], v[210:211], v[62:63] op_sel_hi:[1,0,1]
	ds_read_b128 v[208:211], v15 offset:2304
	v_pk_fma_f32 v[78:79], v[200:201], v[154:155], v[78:79] op_sel_hi:[1,0,1]
	v_pk_fma_f32 v[76:77], v[198:199], v[154:155], v[76:77] op_sel_hi:[1,0,1]
	v_pk_fma_f32 v[74:75], v[196:197], v[154:155], v[74:75] op_sel_hi:[1,0,1]
	v_pk_fma_f32 v[72:73], v[194:195], v[154:155], v[72:73] op_sel_hi:[1,0,1]
	s_waitcnt lgkmcnt(0)
; __device__ __forceinline__ void hyena_raw4(const Args& a, int L, int t0, LAS float* scr, int lane) {
;     ...
;             for (int k = 0; k < 4; ++k) { const float hk = scr[192 * p + 128 + k0 + k];
; #pragma unroll
;                 for (int mth = 0; mth < 16; ++mth) o[p][mth] += hk * wv[k][mth]; }
;     }
; #pragma unroll
;     for (int p = 0; p < 4; ++p) {
;         const float tl = (float)(t0 + p) * (1.0f / 2047.0f);
;         float* raw = (float*)(a.ws + WS_HRAW) + ((size_t)L * 2048 + t0 + p) * 1024;
; #pragma unroll
;         for (int mth = 0; mth < 16; ++mth) { const int idx = lane + 64 * mth; raw[idx] = o[p][mth] * expf(-tl * dec[idx]); }
;     }
	v_pk_fma_f32 v[60:61], v[128:129], v[208:209], v[60:61] op_sel_hi:[1,0,1]
	v_pk_fma_f32 v[58:59], v[126:127], v[208:209], v[58:59] op_sel_hi:[1,0,1]
	v_pk_fma_f32 v[56:57], v[124:125], v[208:209], v[56:57] op_sel_hi:[1,0,1]
	v_pk_fma_f32 v[54:55], v[122:123], v[208:209], v[54:55] op_sel_hi:[1,0,1]
	v_pk_fma_f32 v[52:53], v[120:121], v[208:209], v[52:53] op_sel_hi:[1,0,1]
	v_pk_fma_f32 v[50:51], v[118:119], v[208:209], v[50:51] op_sel_hi:[1,0,1]
	v_pk_fma_f32 v[48:49], v[116:117], v[208:209], v[48:49] op_sel_hi:[1,0,1]
	v_pk_fma_f32 v[46:47], v[114:115], v[208:209], v[46:47] op_sel_hi:[1,0,1]
	v_pk_fma_f32 v[60:61], v[144:145], v[208:209], v[60:61] op_sel:[0,1,0]
	v_pk_fma_f32 v[58:59], v[142:143], v[208:209], v[58:59] op_sel:[0,1,0]
	v_pk_fma_f32 v[56:57], v[140:141], v[208:209], v[56:57] op_sel:[0,1,0]
	v_pk_fma_f32 v[54:55], v[138:139], v[208:209], v[54:55] op_sel:[0,1,0]
	v_pk_fma_f32 v[52:53], v[136:137], v[208:209], v[52:53] op_sel:[0,1,0]
	v_pk_fma_f32 v[50:51], v[134:135], v[208:209], v[50:51] op_sel:[0,1,0]
	v_pk_fma_f32 v[48:49], v[132:133], v[208:209], v[48:49] op_sel:[0,1,0]
	v_pk_fma_f32 v[46:47], v[130:131], v[208:209], v[46:47] op_sel:[0,1,0]
	v_pk_fma_f32 v[60:61], v[184:185], v[210:211], v[60:61] op_sel_hi:[1,0,1]
	v_mov_b32_e32 v128, v211
	v_pk_fma_f32 v[58:59], v[182:183], v[210:211], v[58:59] op_sel_hi:[1,0,1]
	v_pk_fma_f32 v[56:57], v[180:181], v[210:211], v[56:57] op_sel_hi:[1,0,1]
	v_pk_fma_f32 v[54:55], v[178:179], v[210:211], v[54:55] op_sel_hi:[1,0,1]
	v_pk_fma_f32 v[52:53], v[176:177], v[210:211], v[52:53] op_sel_hi:[1,0,1]
	v_pk_fma_f32 v[50:51], v[150:151], v[210:211], v[50:51] op_sel_hi:[1,0,1]
	v_pk_fma_f32 v[48:49], v[148:149], v[210:211], v[48:49] op_sel_hi:[1,0,1]
	v_pk_fma_f32 v[46:47], v[146:147], v[210:211], v[46:47] op_sel_hi:[1,0,1]
	v_pk_fma_f32 v[68:69], v[192:193], v[154:155], v[68:69] op_sel_hi:[1,0,1]
	v_pk_fma_f32 v[66:67], v[190:191], v[154:155], v[66:67] op_sel_hi:[1,0,1]
	v_pk_fma_f32 v[64:65], v[188:189], v[154:155], v[64:65] op_sel_hi:[1,0,1]
	v_pk_fma_f32 v[62:63], v[186:187], v[154:155], v[62:63] op_sel_hi:[1,0,1]
	v_pk_fma_f32 v[60:61], v[200:201], v[128:129], v[60:61] op_sel_hi:[1,0,1]
	v_pk_fma_f32 v[58:59], v[198:199], v[128:129], v[58:59] op_sel_hi:[1,0,1]
	v_pk_fma_f32 v[56:57], v[196:197], v[128:129], v[56:57] op_sel_hi:[1,0,1]
	v_pk_fma_f32 v[54:55], v[194:195], v[128:129], v[54:55] op_sel_hi:[1,0,1]
	v_pk_fma_f32 v[52:53], v[192:193], v[128:129], v[52:53] op_sel_hi:[1,0,1]
	v_pk_fma_f32 v[50:51], v[190:191], v[128:129], v[50:51] op_sel_hi:[1,0,1]
	v_pk_fma_f32 v[48:49], v[188:189], v[128:129], v[48:49] op_sel_hi:[1,0,1]
	v_pk_fma_f32 v[46:47], v[186:187], v[128:129], v[46:47] op_sel_hi:[1,0,1]
	v_add_u32_e32 v15, 16, v15
	s_cbranch_scc1 .LBB0_414
	v_cvt_f32_u32_e32 v15, v206
	v_lshlrev_b32_e32 v114, 10, v70
	v_lshlrev_b64 v[70:71], 23, v[70:71]
	v_ashrrev_i32_e32 v115, 31, v114
	v_lshlrev_b32_e32 v154, 12, v206
	v_lshl_add_u64 v[70:71], s[16:17], 0, v[70:71]
	v_lshl_add_u64 v[86:87], v[70:71], 0, v[154:155]
	v_lshl_add_u64 v[70:71], v[114:115], 2, v[10:11]
	global_load_dword v116, v[70:71], off
	global_load_dword v117, v[70:71], off offset:256
	global_load_dword v118, v[70:71], off offset:512
	global_load_dword v119, v[70:71], off offset:768
	global_load_dword v120, v[70:71], off offset:1024
	global_load_dword v121, v[70:71], off offset:1280
	global_load_dword v122, v[70:71], off offset:1536
	global_load_dword v123, v[70:71], off offset:1792
	global_load_dword v124, v[70:71], off offset:2048
	global_load_dword v125, v[70:71], off offset:2304
	global_load_dword v126, v[70:71], off offset:2560
	global_load_dword v127, v[70:71], off offset:2816
	global_load_dword v128, v[70:71], off offset:3072
	global_load_dword v129, v[70:71], off offset:3328
	global_load_dword v130, v[70:71], off offset:3584
	global_load_dword v131, v[70:71], off offset:3840
	s_waitcnt vmcnt(0)
	v_mul_f32_e32 v17, 0xba001002, v15
	v_mov_b32_e32 v15, v116
	s_mov_b32 s2, 0x3fb8aa3b
	s_mov_b32 s3, 0xc2ce8ed0
	s_mov_b32 s10, 0x42b17218
	s_mov_b64 s[12:13], 0x1000
	s_mov_b64 s[20:21], 0x2000
	s_mov_b64 s[0:1], 0x3000
	v_add_u32_e32 v205, s28, v205
	v_mul_f32_e32 v15, v17, v15
	v_mul_f32_e32 v19, 0x3fb8aa3b, v15
	v_fma_f32 v21, v15, s2, -v19
	v_rndne_f32_e32 v23, v19
	v_fmac_f32_e32 v21, 0x32a5705f, v15
	v_sub_f32_e32 v19, v19, v23
	v_add_f32_e32 v19, v19, v21
	v_exp_f32_e32 v19, v19
	v_cvt_i32_f32_e32 v21, v23
	v_cmp_ngt_f32_e32 vcc, s3, v15
	v_ldexp_f32 v19, v19, v21
	s_nop 0
	v_cndmask_b32_e32 v19, 0, v19, vcc
	v_cmp_nlt_f32_e32 vcc, s10, v15
	s_nop 1
	v_cndmask_b32_e32 v15, v247, v19, vcc
	v_mul_f32_e32 v19, v112, v15
	v_mov_b32_e32 v15, v155
	v_lshl_add_u64 v[114:115], v[86:87], 0, v[14:15]
	global_store_dword v[114:115], v19, off
	v_mov_b32_e32 v19, v117
	v_mul_f32_e32 v19, v17, v19
	v_mul_f32_e32 v21, 0x3fb8aa3b, v19
	v_fma_f32 v23, v19, s2, -v21
	v_rndne_f32_e32 v25, v21
	v_fmac_f32_e32 v23, 0x32a5705f, v19
	v_sub_f32_e32 v21, v21, v25
	v_add_f32_e32 v21, v21, v23
	v_exp_f32_e32 v21, v21
	v_cvt_i32_f32_e32 v23, v25
	v_cmp_ngt_f32_e32 vcc, s3, v19
	v_ldexp_f32 v21, v21, v23
	s_nop 0
	v_cndmask_b32_e32 v21, 0, v21, vcc
	v_cmp_nlt_f32_e32 vcc, s10, v19
	s_nop 1
	v_cndmask_b32_e32 v19, v247, v21, vcc
	v_mul_f32_e32 v19, v113, v19
	global_store_dword v[114:115], v19, off offset:256
	v_mov_b32_e32 v19, v118
	v_mul_f32_e32 v19, v17, v19
	v_mul_f32_e32 v21, 0x3fb8aa3b, v19
	v_fma_f32 v23, v19, s2, -v21
	v_rndne_f32_e32 v25, v21
	v_fmac_f32_e32 v23, 0x32a5705f, v19
	v_sub_f32_e32 v21, v21, v25
	v_add_f32_e32 v21, v21, v23
	v_exp_f32_e32 v21, v21
	v_cvt_i32_f32_e32 v23, v25
	v_cmp_ngt_f32_e32 vcc, s3, v19
; __device__ __forceinline__ void hyena_raw4(const Args& a, int L, int t0, LAS float* scr, int lane) {
;     ...
;         for (int mth = 0; mth < 16; ++mth) { const int idx = lane + 64 * mth; raw[idx] = o[p][mth] * expf(-tl * dec[idx]); }
	v_ldexp_f32 v21, v21, v23
	s_nop 0
	v_cndmask_b32_e32 v21, 0, v21, vcc
	v_cmp_nlt_f32_e32 vcc, s10, v19
	s_nop 1
	v_cndmask_b32_e32 v19, v247, v21, vcc
	v_mul_f32_e32 v19, v110, v19
	global_store_dword v[114:115], v19, off offset:512
	v_mov_b32_e32 v19, v119
	v_mul_f32_e32 v19, v17, v19
	v_mul_f32_e32 v21, 0x3fb8aa3b, v19
	v_fma_f32 v23, v19, s2, -v21
	v_rndne_f32_e32 v25, v21
	v_fmac_f32_e32 v23, 0x32a5705f, v19
	v_sub_f32_e32 v21, v21, v25
	v_add_f32_e32 v21, v21, v23
	v_exp_f32_e32 v21, v21
	v_cvt_i32_f32_e32 v23, v25
	v_cmp_ngt_f32_e32 vcc, s3, v19
	v_ldexp_f32 v21, v21, v23
	s_nop 0
	v_cndmask_b32_e32 v21, 0, v21, vcc
	v_cmp_nlt_f32_e32 vcc, s10, v19
	s_nop 1
	v_cndmask_b32_e32 v19, v247, v21, vcc
	v_mul_f32_e32 v19, v111, v19
	global_store_dword v[114:115], v19, off offset:768
	v_mov_b32_e32 v19, v120
	v_mul_f32_e32 v19, v17, v19
	v_mul_f32_e32 v21, 0x3fb8aa3b, v19
	v_fma_f32 v23, v19, s2, -v21
	v_rndne_f32_e32 v25, v21
	v_fmac_f32_e32 v23, 0x32a5705f, v19
	v_sub_f32_e32 v21, v21, v25
	v_add_f32_e32 v21, v21, v23
	v_exp_f32_e32 v21, v21
	v_cvt_i32_f32_e32 v23, v25
	v_cmp_ngt_f32_e32 vcc, s3, v19
	v_ldexp_f32 v21, v21, v23
	s_nop 0
	v_cndmask_b32_e32 v21, 0, v21, vcc
	v_cmp_nlt_f32_e32 vcc, s10, v19
	s_nop 1
	v_cndmask_b32_e32 v19, v247, v21, vcc
	v_mul_f32_e32 v19, v108, v19
	global_store_dword v[114:115], v19, off offset:1024
	v_mov_b32_e32 v19, v121
	v_mul_f32_e32 v19, v17, v19
	v_mul_f32_e32 v21, 0x3fb8aa3b, v19
	v_fma_f32 v23, v19, s2, -v21
	v_rndne_f32_e32 v25, v21
	v_fmac_f32_e32 v23, 0x32a5705f, v19
	v_sub_f32_e32 v21, v21, v25
	v_add_f32_e32 v21, v21, v23
	v_exp_f32_e32 v21, v21
	v_cvt_i32_f32_e32 v23, v25
	v_cmp_ngt_f32_e32 vcc, s3, v19
	v_ldexp_f32 v21, v21, v23
	s_nop 0
	v_cndmask_b32_e32 v21, 0, v21, vcc
	v_cmp_nlt_f32_e32 vcc, s10, v19
	s_nop 1
	v_cndmask_b32_e32 v19, v247, v21, vcc
	v_mul_f32_e32 v19, v109, v19
	global_store_dword v[114:115], v19, off offset:1280
	v_mov_b32_e32 v19, v122
	v_mul_f32_e32 v19, v17, v19
	v_mul_f32_e32 v21, 0x3fb8aa3b, v19
	v_fma_f32 v23, v19, s2, -v21
	v_rndne_f32_e32 v25, v21
	v_fmac_f32_e32 v23, 0x32a5705f, v19
	v_sub_f32_e32 v21, v21, v25
	v_add_f32_e32 v21, v21, v23
	v_exp_f32_e32 v21, v21
	v_cvt_i32_f32_e32 v23, v25
	v_cmp_ngt_f32_e32 vcc, s3, v19
	v_ldexp_f32 v21, v21, v23
	s_nop 0
	v_cndmask_b32_e32 v21, 0, v21, vcc
	v_cmp_nlt_f32_e32 vcc, s10, v19
	s_nop 1
	v_cndmask_b32_e32 v19, v247, v21, vcc
	v_mul_f32_e32 v19, v106, v19
	global_store_dword v[114:115], v19, off offset:1536
	v_mov_b32_e32 v19, v123
	v_mul_f32_e32 v19, v17, v19
	v_mul_f32_e32 v21, 0x3fb8aa3b, v19
	v_fma_f32 v23, v19, s2, -v21
	v_rndne_f32_e32 v25, v21
	v_fmac_f32_e32 v23, 0x32a5705f, v19
	v_sub_f32_e32 v21, v21, v25
	v_add_f32_e32 v21, v21, v23
	v_exp_f32_e32 v21, v21
	v_cvt_i32_f32_e32 v23, v25
	v_cmp_ngt_f32_e32 vcc, s3, v19
	v_ldexp_f32 v21, v21, v23
	s_nop 0
	v_cndmask_b32_e32 v21, 0, v21, vcc
	v_cmp_nlt_f32_e32 vcc, s10, v19
	s_nop 1
	v_cndmask_b32_e32 v19, v247, v21, vcc
	v_mul_f32_e32 v19, v107, v19
	global_store_dword v[114:115], v19, off offset:1792
	v_mov_b32_e32 v19, v124
	v_mul_f32_e32 v19, v17, v19
	v_mul_f32_e32 v21, 0x3fb8aa3b, v19
	v_fma_f32 v23, v19, s2, -v21
	v_rndne_f32_e32 v25, v21
	v_fmac_f32_e32 v23, 0x32a5705f, v19
	v_sub_f32_e32 v21, v21, v25
	v_add_f32_e32 v21, v21, v23
	v_exp_f32_e32 v21, v21
	v_cvt_i32_f32_e32 v23, v25
	v_cmp_ngt_f32_e32 vcc, s3, v19
	v_ldexp_f32 v21, v21, v23
	s_nop 0
	v_cndmask_b32_e32 v21, 0, v21, vcc
	v_cmp_nlt_f32_e32 vcc, s10, v19
	s_nop 1
	v_cndmask_b32_e32 v19, v247, v21, vcc
	v_mul_f32_e32 v19, v104, v19
	global_store_dword v[114:115], v19, off offset:2048
	v_mov_b32_e32 v19, v125
	v_mul_f32_e32 v19, v17, v19
	v_mul_f32_e32 v21, 0x3fb8aa3b, v19
	v_fma_f32 v23, v19, s2, -v21
	v_rndne_f32_e32 v25, v21
	v_fmac_f32_e32 v23, 0x32a5705f, v19
	v_sub_f32_e32 v21, v21, v25
	v_add_f32_e32 v21, v21, v23
	v_exp_f32_e32 v21, v21
	v_cvt_i32_f32_e32 v23, v25
	v_cmp_ngt_f32_e32 vcc, s3, v19
	v_ldexp_f32 v21, v21, v23
	s_nop 0
	v_cndmask_b32_e32 v21, 0, v21, vcc
	v_cmp_nlt_f32_e32 vcc, s10, v19
	s_nop 1
	v_cndmask_b32_e32 v19, v247, v21, vcc
	v_mul_f32_e32 v19, v105, v19
	global_store_dword v[114:115], v19, off offset:2304
	v_mov_b32_e32 v19, v126
	v_mul_f32_e32 v19, v17, v19
	v_mul_f32_e32 v21, 0x3fb8aa3b, v19
	v_fma_f32 v23, v19, s2, -v21
	v_rndne_f32_e32 v25, v21
	v_fmac_f32_e32 v23, 0x32a5705f, v19
	v_sub_f32_e32 v21, v21, v25
	v_add_f32_e32 v21, v21, v23
	v_exp_f32_e32 v21, v21
	v_cvt_i32_f32_e32 v23, v25
	v_cmp_ngt_f32_e32 vcc, s3, v19
	v_ldexp_f32 v21, v21, v23
	s_nop 0
	v_cndmask_b32_e32 v21, 0, v21, vcc
	v_cmp_nlt_f32_e32 vcc, s10, v19
	s_nop 1
	v_cndmask_b32_e32 v19, v247, v21, vcc
	v_mul_f32_e32 v19, v102, v19
	global_store_dword v[114:115], v19, off offset:2560
	v_mov_b32_e32 v19, v127
	v_mul_f32_e32 v19, v17, v19
	v_mul_f32_e32 v21, 0x3fb8aa3b, v19
	v_fma_f32 v23, v19, s2, -v21
	v_rndne_f32_e32 v25, v21
	v_fmac_f32_e32 v23, 0x32a5705f, v19
	v_sub_f32_e32 v21, v21, v25
	v_add_f32_e32 v21, v21, v23
	v_exp_f32_e32 v21, v21
	v_cvt_i32_f32_e32 v23, v25
	v_cmp_ngt_f32_e32 vcc, s3, v19
	v_ldexp_f32 v21, v21, v23
	s_nop 0
	v_cndmask_b32_e32 v21, 0, v21, vcc
	v_cmp_nlt_f32_e32 vcc, s10, v19
	s_nop 1
	v_cndmask_b32_e32 v19, v247, v21, vcc
	v_mul_f32_e32 v19, v103, v19
	global_store_dword v[114:115], v19, off offset:2816
	v_mov_b32_e32 v19, v128
	v_mul_f32_e32 v19, v17, v19
	v_mul_f32_e32 v21, 0x3fb8aa3b, v19
	v_fma_f32 v23, v19, s2, -v21
	v_rndne_f32_e32 v25, v21
	v_fmac_f32_e32 v23, 0x32a5705f, v19
	v_sub_f32_e32 v21, v21, v25
	v_add_f32_e32 v21, v21, v23
	v_exp_f32_e32 v21, v21
	v_cvt_i32_f32_e32 v23, v25
	v_cmp_ngt_f32_e32 vcc, s3, v19
	v_ldexp_f32 v21, v21, v23
	s_nop 0
; __device__ __forceinline__ void hyena_raw4(const Args& a, int L, int t0, LAS float* scr, int lane) {
;     ...
;     for (int p = 0; p < 4; ++p) {
;         const float tl = (float)(t0 + p) * (1.0f / 2047.0f);
;         float* raw = (float*)(a.ws + WS_HRAW) + ((size_t)L * 2048 + t0 + p) * 1024;
; #pragma unroll
;         for (int mth = 0; mth < 16; ++mth) { const int idx = lane + 64 * mth; raw[idx] = o[p][mth] * expf(-tl * dec[idx]); }
	v_cndmask_b32_e32 v21, 0, v21, vcc
	v_cmp_nlt_f32_e32 vcc, s10, v19
	s_nop 1
	v_cndmask_b32_e32 v19, v247, v21, vcc
	v_mul_f32_e32 v19, v100, v19
	global_store_dword v[114:115], v19, off offset:3072
	v_mov_b32_e32 v19, v129
	v_mul_f32_e32 v19, v17, v19
	v_mul_f32_e32 v21, 0x3fb8aa3b, v19
	v_fma_f32 v23, v19, s2, -v21
	v_rndne_f32_e32 v25, v21
	v_fmac_f32_e32 v23, 0x32a5705f, v19
	v_sub_f32_e32 v21, v21, v25
	v_add_f32_e32 v21, v21, v23
	v_exp_f32_e32 v21, v21
	v_cvt_i32_f32_e32 v23, v25
	v_cmp_ngt_f32_e32 vcc, s3, v19
	v_ldexp_f32 v21, v21, v23
	s_nop 0
	v_cndmask_b32_e32 v21, 0, v21, vcc
	v_cmp_nlt_f32_e32 vcc, s10, v19
	s_nop 1
	v_cndmask_b32_e32 v19, v247, v21, vcc
	v_mul_f32_e32 v19, v101, v19
	global_store_dword v[114:115], v19, off offset:3328
	v_mov_b32_e32 v19, v130
	v_mul_f32_e32 v19, v17, v19
	v_mul_f32_e32 v21, 0x3fb8aa3b, v19
	v_fma_f32 v23, v19, s2, -v21
	v_rndne_f32_e32 v25, v21
	v_fmac_f32_e32 v23, 0x32a5705f, v19
	v_sub_f32_e32 v21, v21, v25
	v_add_f32_e32 v21, v21, v23
	v_exp_f32_e32 v21, v21
	v_cvt_i32_f32_e32 v23, v25
	v_cmp_ngt_f32_e32 vcc, s3, v19
	v_ldexp_f32 v21, v21, v23
	s_nop 0
	v_cndmask_b32_e32 v21, 0, v21, vcc
	v_cmp_nlt_f32_e32 vcc, s10, v19
	s_nop 1
	v_cndmask_b32_e32 v19, v247, v21, vcc
	v_mul_f32_e32 v19, v98, v19
	global_store_dword v[114:115], v19, off offset:3584
	v_mov_b32_e32 v19, v131
	v_mul_f32_e32 v17, v17, v19
	v_mul_f32_e32 v19, 0x3fb8aa3b, v17
	v_fma_f32 v21, v17, s2, -v19
	v_rndne_f32_e32 v23, v19
	v_fmac_f32_e32 v21, 0x32a5705f, v17
	v_sub_f32_e32 v19, v19, v23
	v_add_f32_e32 v19, v19, v21
	v_exp_f32_e32 v19, v19
	v_cvt_i32_f32_e32 v21, v23
	v_cmp_ngt_f32_e32 vcc, s3, v17
	v_ldexp_f32 v19, v19, v21
	s_nop 0
	v_cndmask_b32_e32 v19, 0, v19, vcc
	v_cmp_nlt_f32_e32 vcc, s10, v17
	s_nop 1
	v_cndmask_b32_e32 v17, v247, v19, vcc
	v_mul_f32_e32 v17, v99, v17
	global_store_dword v[114:115], v17, off offset:3840
	v_or_b32_e32 v17, 1, v206
	v_cvt_f32_u32_e32 v17, v17
	v_lshl_add_u64 v[98:99], v[86:87], 0, s[12:13]
	v_lshl_add_u64 v[100:101], v[98:99], 0, v[14:15]
	v_mul_f32_e32 v45, 0xba001002, v17
	v_mov_b32_e32 v17, v116
	v_mul_f32_e32 v17, v45, v17
	v_mul_f32_e32 v19, 0x3fb8aa3b, v17
	v_fma_f32 v21, v17, s2, -v19
	v_rndne_f32_e32 v23, v19
	v_fmac_f32_e32 v21, 0x32a5705f, v17
	v_sub_f32_e32 v19, v19, v23
	v_add_f32_e32 v19, v19, v21
	v_exp_f32_e32 v19, v19
	v_cvt_i32_f32_e32 v21, v23
	v_cmp_ngt_f32_e32 vcc, s3, v17
	v_ldexp_f32 v19, v19, v21
	s_nop 0
	v_cndmask_b32_e32 v19, 0, v19, vcc
	v_cmp_nlt_f32_e32 vcc, s10, v17
	s_nop 1
	v_cndmask_b32_e32 v17, v247, v19, vcc
	v_mul_f32_e32 v17, v96, v17
	global_store_dword v[100:101], v17, off
	v_mov_b32_e32 v17, v117
	v_mul_f32_e32 v17, v45, v17
	v_mul_f32_e32 v19, 0x3fb8aa3b, v17
	v_fma_f32 v21, v17, s2, -v19
	v_rndne_f32_e32 v23, v19
	v_fmac_f32_e32 v21, 0x32a5705f, v17
	v_sub_f32_e32 v19, v19, v23
	v_add_f32_e32 v19, v19, v21
	v_exp_f32_e32 v19, v19
	v_cvt_i32_f32_e32 v21, v23
	v_cmp_ngt_f32_e32 vcc, s3, v17
	v_ldexp_f32 v19, v19, v21
	s_nop 0
	v_cndmask_b32_e32 v19, 0, v19, vcc
	v_cmp_nlt_f32_e32 vcc, s10, v17
	s_nop 1
	v_cndmask_b32_e32 v17, v247, v19, vcc
	v_mul_f32_e32 v19, v97, v17
	v_mov_b32_e32 v17, v155
	v_lshl_add_u64 v[96:97], v[98:99], 0, v[16:17]
	global_store_dword v[96:97], v19, off
	v_mov_b32_e32 v19, v118
	v_mul_f32_e32 v19, v45, v19
	v_mul_f32_e32 v21, 0x3fb8aa3b, v19
	v_fma_f32 v23, v19, s2, -v21
	v_rndne_f32_e32 v25, v21
	v_fmac_f32_e32 v23, 0x32a5705f, v19
	v_sub_f32_e32 v21, v21, v25
	v_add_f32_e32 v21, v21, v23
	v_exp_f32_e32 v21, v21
	v_cvt_i32_f32_e32 v23, v25
	v_cmp_ngt_f32_e32 vcc, s3, v19
	v_ldexp_f32 v21, v21, v23
	s_nop 0
	v_cndmask_b32_e32 v21, 0, v21, vcc
	v_cmp_nlt_f32_e32 vcc, s10, v19
	s_nop 1
	v_cndmask_b32_e32 v19, v247, v21, vcc
	v_mul_f32_e32 v21, v94, v19
	v_mov_b32_e32 v19, v155
	v_lshl_add_u64 v[96:97], v[98:99], 0, v[18:19]
	global_store_dword v[96:97], v21, off
	v_mov_b32_e32 v21, v119
	v_mul_f32_e32 v21, v45, v21
	v_mul_f32_e32 v23, 0x3fb8aa3b, v21
	v_fma_f32 v25, v21, s2, -v23
	v_rndne_f32_e32 v27, v23
	v_fmac_f32_e32 v25, 0x32a5705f, v21
	v_sub_f32_e32 v23, v23, v27
	v_add_f32_e32 v23, v23, v25
	v_exp_f32_e32 v23, v23
	v_cvt_i32_f32_e32 v25, v27
	v_cmp_ngt_f32_e32 vcc, s3, v21
	v_ldexp_f32 v23, v23, v25
	s_nop 0
	v_cndmask_b32_e32 v23, 0, v23, vcc
	v_cmp_nlt_f32_e32 vcc, s10, v21
	s_nop 1
	v_cndmask_b32_e32 v21, v247, v23, vcc
	v_mul_f32_e32 v23, v95, v21
	v_mov_b32_e32 v21, v155
	v_lshl_add_u64 v[94:95], v[98:99], 0, v[20:21]
	global_store_dword v[94:95], v23, off
	v_mov_b32_e32 v23, v120
	v_mul_f32_e32 v23, v45, v23
	v_mul_f32_e32 v25, 0x3fb8aa3b, v23
	v_fma_f32 v27, v23, s2, -v25
	v_rndne_f32_e32 v29, v25
	v_fmac_f32_e32 v27, 0x32a5705f, v23
	v_sub_f32_e32 v25, v25, v29
	v_add_f32_e32 v25, v25, v27
	v_exp_f32_e32 v25, v25
	v_cvt_i32_f32_e32 v27, v29
	v_cmp_ngt_f32_e32 vcc, s3, v23
	v_ldexp_f32 v25, v25, v27
	s_nop 0
	v_cndmask_b32_e32 v25, 0, v25, vcc
	v_cmp_nlt_f32_e32 vcc, s10, v23
	s_nop 1
	v_cndmask_b32_e32 v23, v247, v25, vcc
	v_mul_f32_e32 v25, v92, v23
	v_mov_b32_e32 v23, v155
	v_lshl_add_u64 v[94:95], v[98:99], 0, v[22:23]
	global_store_dword v[94:95], v25, off
	v_mov_b32_e32 v25, v121
	v_mul_f32_e32 v25, v45, v25
	v_mul_f32_e32 v27, 0x3fb8aa3b, v25
	v_fma_f32 v29, v25, s2, -v27
	v_rndne_f32_e32 v31, v27
	v_fmac_f32_e32 v29, 0x32a5705f, v25
	v_sub_f32_e32 v27, v27, v31
	v_add_f32_e32 v27, v27, v29
	v_exp_f32_e32 v27, v27
	v_cvt_i32_f32_e32 v29, v31
	v_cmp_ngt_f32_e32 vcc, s3, v25
	v_ldexp_f32 v27, v27, v29
	s_nop 0
	v_cndmask_b32_e32 v27, 0, v27, vcc
	v_cmp_nlt_f32_e32 vcc, s10, v25
	s_nop 1
	v_cndmask_b32_e32 v25, v247, v27, vcc
	v_mul_f32_e32 v27, v93, v25
	v_mov_b32_e32 v25, v155
; __device__ __forceinline__ void hyena_raw4(const Args& a, int L, int t0, LAS float* scr, int lane) {
;     ...
;         for (int mth = 0; mth < 16; ++mth) { const int idx = lane + 64 * mth; raw[idx] = o[p][mth] * expf(-tl * dec[idx]); }
	v_lshl_add_u64 v[92:93], v[98:99], 0, v[24:25]
	global_store_dword v[92:93], v27, off
	v_mov_b32_e32 v27, v122
	v_mul_f32_e32 v27, v45, v27
	v_mul_f32_e32 v29, 0x3fb8aa3b, v27
	v_fma_f32 v31, v27, s2, -v29
	v_rndne_f32_e32 v33, v29
	v_fmac_f32_e32 v31, 0x32a5705f, v27
	v_sub_f32_e32 v29, v29, v33
	v_add_f32_e32 v29, v29, v31
	v_exp_f32_e32 v29, v29
	v_cvt_i32_f32_e32 v31, v33
	v_cmp_ngt_f32_e32 vcc, s3, v27
	v_ldexp_f32 v29, v29, v31
	s_nop 0
	v_cndmask_b32_e32 v29, 0, v29, vcc
	v_cmp_nlt_f32_e32 vcc, s10, v27
	s_nop 1
	v_cndmask_b32_e32 v27, v247, v29, vcc
	v_mul_f32_e32 v29, v90, v27
	v_mov_b32_e32 v27, v155
	v_lshl_add_u64 v[92:93], v[98:99], 0, v[26:27]
	global_store_dword v[92:93], v29, off
	v_mov_b32_e32 v29, v123
	v_mul_f32_e32 v29, v45, v29
	v_mul_f32_e32 v31, 0x3fb8aa3b, v29
	v_fma_f32 v33, v29, s2, -v31
	v_rndne_f32_e32 v35, v31
	v_fmac_f32_e32 v33, 0x32a5705f, v29
	v_sub_f32_e32 v31, v31, v35
	v_add_f32_e32 v31, v31, v33
	v_exp_f32_e32 v31, v31
	v_cvt_i32_f32_e32 v33, v35
	v_cmp_ngt_f32_e32 vcc, s3, v29
	v_ldexp_f32 v31, v31, v33
	s_nop 0
	v_cndmask_b32_e32 v31, 0, v31, vcc
	v_cmp_nlt_f32_e32 vcc, s10, v29
	s_nop 1
	v_cndmask_b32_e32 v29, v247, v31, vcc
	v_mul_f32_e32 v31, v91, v29
	v_mov_b32_e32 v29, v155
	v_lshl_add_u64 v[90:91], v[98:99], 0, v[28:29]
	global_store_dword v[90:91], v31, off
	v_mov_b32_e32 v31, v124
	v_mul_f32_e32 v31, v45, v31
	v_mul_f32_e32 v33, 0x3fb8aa3b, v31
	v_fma_f32 v35, v31, s2, -v33
	v_rndne_f32_e32 v37, v33
	v_fmac_f32_e32 v35, 0x32a5705f, v31
	v_sub_f32_e32 v33, v33, v37
	v_add_f32_e32 v33, v33, v35
	v_exp_f32_e32 v33, v33
	v_cvt_i32_f32_e32 v35, v37
	v_cmp_ngt_f32_e32 vcc, s3, v31
	v_ldexp_f32 v33, v33, v35
	s_nop 0
	v_cndmask_b32_e32 v33, 0, v33, vcc
	v_cmp_nlt_f32_e32 vcc, s10, v31
	s_nop 1
	v_cndmask_b32_e32 v31, v247, v33, vcc
	v_mul_f32_e32 v33, v88, v31
	v_mov_b32_e32 v31, v155
	v_lshl_add_u64 v[90:91], v[98:99], 0, v[30:31]
	global_store_dword v[90:91], v33, off
	v_mov_b32_e32 v33, v125
	v_mul_f32_e32 v33, v45, v33
	v_mul_f32_e32 v35, 0x3fb8aa3b, v33
	v_fma_f32 v37, v33, s2, -v35
	v_rndne_f32_e32 v39, v35
	v_fmac_f32_e32 v37, 0x32a5705f, v33
	v_sub_f32_e32 v35, v35, v39
	v_add_f32_e32 v35, v35, v37
	v_exp_f32_e32 v35, v35
	v_cvt_i32_f32_e32 v37, v39
	v_cmp_ngt_f32_e32 vcc, s3, v33
	v_ldexp_f32 v35, v35, v37
	s_nop 0
	v_cndmask_b32_e32 v35, 0, v35, vcc
	v_cmp_nlt_f32_e32 vcc, s10, v33
	s_nop 1
	v_cndmask_b32_e32 v33, v247, v35, vcc
	v_mul_f32_e32 v35, v89, v33
	v_mov_b32_e32 v33, v155
	v_lshl_add_u64 v[88:89], v[98:99], 0, v[32:33]
	global_store_dword v[88:89], v35, off
	v_mov_b32_e32 v35, v126
	v_mul_f32_e32 v35, v45, v35
	v_mul_f32_e32 v37, 0x3fb8aa3b, v35
	v_fma_f32 v39, v35, s2, -v37
	v_rndne_f32_e32 v41, v37
	v_fmac_f32_e32 v39, 0x32a5705f, v35
	v_sub_f32_e32 v37, v37, v41
	v_add_f32_e32 v37, v37, v39
	v_exp_f32_e32 v37, v37
	v_cvt_i32_f32_e32 v39, v41
	v_cmp_ngt_f32_e32 vcc, s3, v35
	v_ldexp_f32 v37, v37, v39
	s_nop 0
	v_cndmask_b32_e32 v37, 0, v37, vcc
	v_cmp_nlt_f32_e32 vcc, s10, v35
	s_nop 1
	v_cndmask_b32_e32 v35, v247, v37, vcc
	v_mul_f32_e32 v37, v84, v35
	v_mov_b32_e32 v35, v155
	v_lshl_add_u64 v[88:89], v[98:99], 0, v[34:35]
	global_store_dword v[88:89], v37, off
	v_mov_b32_e32 v37, v127
	v_mul_f32_e32 v37, v45, v37
	v_mul_f32_e32 v39, 0x3fb8aa3b, v37
	v_fma_f32 v41, v37, s2, -v39
	v_rndne_f32_e32 v43, v39
	v_fmac_f32_e32 v41, 0x32a5705f, v37
	v_sub_f32_e32 v39, v39, v43
	v_add_f32_e32 v39, v39, v41
	v_exp_f32_e32 v39, v39
	v_cvt_i32_f32_e32 v41, v43
	v_cmp_ngt_f32_e32 vcc, s3, v37
	v_ldexp_f32 v39, v39, v41
	s_nop 0
	v_cndmask_b32_e32 v39, 0, v39, vcc
	v_cmp_nlt_f32_e32 vcc, s10, v37
	s_nop 1
	v_cndmask_b32_e32 v37, v247, v39, vcc
	v_mul_f32_e32 v39, v85, v37
	v_mov_b32_e32 v37, v155
	v_lshl_add_u64 v[84:85], v[98:99], 0, v[36:37]
	global_store_dword v[84:85], v39, off
	v_mov_b32_e32 v39, v128
	v_mul_f32_e32 v39, v45, v39
	v_mul_f32_e32 v41, 0x3fb8aa3b, v39
	v_fma_f32 v43, v39, s2, -v41
	v_rndne_f32_e32 v84, v41
	v_fmac_f32_e32 v43, 0x32a5705f, v39
	v_sub_f32_e32 v41, v41, v84
	v_add_f32_e32 v41, v41, v43
	v_exp_f32_e32 v41, v41
	v_cvt_i32_f32_e32 v43, v84
	v_cmp_ngt_f32_e32 vcc, s3, v39
	v_ldexp_f32 v41, v41, v43
	s_nop 0
	v_cndmask_b32_e32 v41, 0, v41, vcc
	v_cmp_nlt_f32_e32 vcc, s10, v39
	s_nop 1
	v_cndmask_b32_e32 v39, v247, v41, vcc
	v_mul_f32_e32 v41, v82, v39
	v_mov_b32_e32 v39, v155
	v_lshl_add_u64 v[84:85], v[98:99], 0, v[38:39]
	global_store_dword v[84:85], v41, off
	v_mov_b32_e32 v41, v129
	v_mul_f32_e32 v41, v45, v41
	v_mul_f32_e32 v43, 0x3fb8aa3b, v41
	v_fma_f32 v82, v41, s2, -v43
	v_rndne_f32_e32 v84, v43
	v_fmac_f32_e32 v82, 0x32a5705f, v41
	v_sub_f32_e32 v43, v43, v84
	v_add_f32_e32 v43, v43, v82
	v_exp_f32_e32 v43, v43
	v_cvt_i32_f32_e32 v82, v84
	v_cmp_ngt_f32_e32 vcc, s3, v41
	v_ldexp_f32 v43, v43, v82
	s_nop 0
	v_cndmask_b32_e32 v43, 0, v43, vcc
	v_cmp_nlt_f32_e32 vcc, s10, v41
	s_nop 1
	v_cndmask_b32_e32 v41, v247, v43, vcc
	v_mul_f32_e32 v43, v83, v41
	v_mov_b32_e32 v41, v155
	v_lshl_add_u64 v[82:83], v[98:99], 0, v[40:41]
	global_store_dword v[82:83], v43, off
	v_mov_b32_e32 v43, v130
	v_mul_f32_e32 v43, v45, v43
	v_mul_f32_e32 v82, 0x3fb8aa3b, v43
	v_fma_f32 v83, v43, s2, -v82
	v_rndne_f32_e32 v84, v82
	v_fmac_f32_e32 v83, 0x32a5705f, v43
	v_sub_f32_e32 v82, v82, v84
	v_add_f32_e32 v82, v82, v83
	v_exp_f32_e32 v82, v82
	v_cvt_i32_f32_e32 v83, v84
	v_cmp_ngt_f32_e32 vcc, s3, v43
	v_ldexp_f32 v82, v82, v83
	s_nop 0
	v_cndmask_b32_e32 v82, 0, v82, vcc
	v_cmp_nlt_f32_e32 vcc, s10, v43
	s_nop 1
	v_cndmask_b32_e32 v43, v247, v82, vcc
	v_mul_f32_e32 v80, v80, v43
	v_mov_b32_e32 v43, v155
	v_lshl_add_u64 v[82:83], v[98:99], 0, v[42:43]
	global_store_dword v[82:83], v80, off
; __device__ __forceinline__ void hyena_raw4(const Args& a, int L, int t0, LAS float* scr, int lane) {
;     ...
;     for (int p = 0; p < 4; ++p) {
;         const float tl = (float)(t0 + p) * (1.0f / 2047.0f);
;         float* raw = (float*)(a.ws + WS_HRAW) + ((size_t)L * 2048 + t0 + p) * 1024;
; #pragma unroll
;         for (int mth = 0; mth < 16; ++mth) { const int idx = lane + 64 * mth; raw[idx] = o[p][mth] * expf(-tl * dec[idx]); }
	v_mov_b32_e32 v80, v131
	v_mul_f32_e32 v45, v45, v80
	v_mul_f32_e32 v80, 0x3fb8aa3b, v45
	v_fma_f32 v82, v45, s2, -v80
	v_rndne_f32_e32 v83, v80
	v_fmac_f32_e32 v82, 0x32a5705f, v45
	v_sub_f32_e32 v80, v80, v83
	v_add_f32_e32 v80, v80, v82
	v_exp_f32_e32 v80, v80
	v_cvt_i32_f32_e32 v82, v83
	v_cmp_ngt_f32_e32 vcc, s3, v45
	v_ldexp_f32 v80, v80, v82
	s_nop 0
	v_cndmask_b32_e32 v80, 0, v80, vcc
	v_cmp_nlt_f32_e32 vcc, s10, v45
	s_nop 1
	v_cndmask_b32_e32 v45, v247, v80, vcc
	v_mul_f32_e32 v82, v81, v45
	v_mov_b32_e32 v45, v155
	v_lshl_add_u64 v[80:81], v[98:99], 0, v[44:45]
	global_store_dword v[80:81], v82, off
	v_mov_b32_e32 v83, v116
	v_or_b32_e32 v80, 2, v206
	v_cvt_f32_u32_e32 v82, v80
	v_lshl_add_u64 v[80:81], v[86:87], 0, s[20:21]
	v_mul_f32_e32 v82, 0xba001002, v82
	v_mul_f32_e32 v83, v82, v83
	v_mul_f32_e32 v84, 0x3fb8aa3b, v83
	v_fma_f32 v85, v83, s2, -v84
	v_rndne_f32_e32 v88, v84
	v_fmac_f32_e32 v85, 0x32a5705f, v83
	v_sub_f32_e32 v84, v84, v88
	v_add_f32_e32 v84, v84, v85
	v_exp_f32_e32 v84, v84
	v_cvt_i32_f32_e32 v85, v88
	v_cmp_ngt_f32_e32 vcc, s3, v83
	v_ldexp_f32 v84, v84, v85
	s_nop 0
	v_cndmask_b32_e32 v84, 0, v84, vcc
	v_cmp_nlt_f32_e32 vcc, s10, v83
	s_nop 1
	v_cndmask_b32_e32 v83, v247, v84, vcc
	v_mul_f32_e32 v78, v78, v83
	v_lshl_add_u64 v[84:85], v[80:81], 0, v[14:15]
	global_store_dword v[84:85], v78, off
	v_mov_b32_e32 v78, v117
	v_mul_f32_e32 v78, v82, v78
	v_mul_f32_e32 v83, 0x3fb8aa3b, v78
	v_fma_f32 v84, v78, s2, -v83
	v_rndne_f32_e32 v85, v83
	v_fmac_f32_e32 v84, 0x32a5705f, v78
	v_sub_f32_e32 v83, v83, v85
	v_add_f32_e32 v83, v83, v84
	v_exp_f32_e32 v83, v83
	v_cvt_i32_f32_e32 v84, v85
	v_cmp_ngt_f32_e32 vcc, s3, v78
	v_ldexp_f32 v83, v83, v84
	s_nop 0
	v_cndmask_b32_e32 v83, 0, v83, vcc
	v_cmp_nlt_f32_e32 vcc, s10, v78
	s_nop 1
	v_cndmask_b32_e32 v78, v247, v83, vcc
	v_mul_f32_e32 v83, v79, v78
	v_lshl_add_u64 v[78:79], v[80:81], 0, v[16:17]
	global_store_dword v[78:79], v83, off
	v_mov_b32_e32 v78, v118
	v_mul_f32_e32 v78, v82, v78
	v_mul_f32_e32 v79, 0x3fb8aa3b, v78
	v_fma_f32 v83, v78, s2, -v79
	v_rndne_f32_e32 v84, v79
	v_fmac_f32_e32 v83, 0x32a5705f, v78
	v_sub_f32_e32 v79, v79, v84
	v_add_f32_e32 v79, v79, v83
	v_exp_f32_e32 v79, v79
	v_cvt_i32_f32_e32 v83, v84
	v_cmp_ngt_f32_e32 vcc, s3, v78
	v_ldexp_f32 v79, v79, v83
	s_nop 0
	v_cndmask_b32_e32 v79, 0, v79, vcc
	v_cmp_nlt_f32_e32 vcc, s10, v78
	s_nop 1
	v_cndmask_b32_e32 v78, v247, v79, vcc
	v_mul_f32_e32 v76, v76, v78
	v_lshl_add_u64 v[78:79], v[80:81], 0, v[18:19]
	global_store_dword v[78:79], v76, off
	v_mov_b32_e32 v76, v119
	v_mul_f32_e32 v76, v82, v76
	v_mul_f32_e32 v78, 0x3fb8aa3b, v76
	v_fma_f32 v79, v76, s2, -v78
	v_rndne_f32_e32 v83, v78
	v_fmac_f32_e32 v79, 0x32a5705f, v76
	v_sub_f32_e32 v78, v78, v83
	v_add_f32_e32 v78, v78, v79
	v_exp_f32_e32 v78, v78
	v_cvt_i32_f32_e32 v79, v83
	v_cmp_ngt_f32_e32 vcc, s3, v76
	v_ldexp_f32 v78, v78, v79
	s_nop 0
	v_cndmask_b32_e32 v78, 0, v78, vcc
	v_cmp_nlt_f32_e32 vcc, s10, v76
	s_nop 1
	v_cndmask_b32_e32 v76, v247, v78, vcc
	v_mul_f32_e32 v78, v77, v76
	v_lshl_add_u64 v[76:77], v[80:81], 0, v[20:21]
	global_store_dword v[76:77], v78, off
	v_mov_b32_e32 v76, v120
	v_mul_f32_e32 v76, v82, v76
	v_mul_f32_e32 v77, 0x3fb8aa3b, v76
	v_fma_f32 v78, v76, s2, -v77
	v_rndne_f32_e32 v79, v77
	v_fmac_f32_e32 v78, 0x32a5705f, v76
	v_sub_f32_e32 v77, v77, v79
	v_add_f32_e32 v77, v77, v78
	v_exp_f32_e32 v77, v77
	v_cvt_i32_f32_e32 v78, v79
	v_cmp_ngt_f32_e32 vcc, s3, v76
	v_ldexp_f32 v77, v77, v78
	s_nop 0
	v_cndmask_b32_e32 v77, 0, v77, vcc
	v_cmp_nlt_f32_e32 vcc, s10, v76
	s_nop 1
	v_cndmask_b32_e32 v76, v247, v77, vcc
	v_mul_f32_e32 v74, v74, v76
	v_lshl_add_u64 v[76:77], v[80:81], 0, v[22:23]
	global_store_dword v[76:77], v74, off
	v_mov_b32_e32 v74, v121
	v_mul_f32_e32 v74, v82, v74
	v_mul_f32_e32 v76, 0x3fb8aa3b, v74
	v_fma_f32 v77, v74, s2, -v76
	v_rndne_f32_e32 v78, v76
	v_fmac_f32_e32 v77, 0x32a5705f, v74
	v_sub_f32_e32 v76, v76, v78
	v_add_f32_e32 v76, v76, v77
	v_exp_f32_e32 v76, v76
	v_cvt_i32_f32_e32 v77, v78
	v_cmp_ngt_f32_e32 vcc, s3, v74
	v_ldexp_f32 v76, v76, v77
	s_nop 0
	v_cndmask_b32_e32 v76, 0, v76, vcc
	v_cmp_nlt_f32_e32 vcc, s10, v74
	s_nop 1
	v_cndmask_b32_e32 v74, v247, v76, vcc
	v_mul_f32_e32 v76, v75, v74
	v_lshl_add_u64 v[74:75], v[80:81], 0, v[24:25]
	global_store_dword v[74:75], v76, off
	v_mov_b32_e32 v74, v122
	v_mul_f32_e32 v74, v82, v74
	v_mul_f32_e32 v75, 0x3fb8aa3b, v74
	v_fma_f32 v76, v74, s2, -v75
	v_rndne_f32_e32 v77, v75
	v_fmac_f32_e32 v76, 0x32a5705f, v74
	v_sub_f32_e32 v75, v75, v77
	v_add_f32_e32 v75, v75, v76
	v_exp_f32_e32 v75, v75
	v_cvt_i32_f32_e32 v76, v77
	v_cmp_ngt_f32_e32 vcc, s3, v74
	v_ldexp_f32 v75, v75, v76
	s_nop 0
	v_cndmask_b32_e32 v75, 0, v75, vcc
	v_cmp_nlt_f32_e32 vcc, s10, v74
	s_nop 1
	v_cndmask_b32_e32 v74, v247, v75, vcc
	v_mul_f32_e32 v72, v72, v74
	v_lshl_add_u64 v[74:75], v[80:81], 0, v[26:27]
	global_store_dword v[74:75], v72, off
	v_mov_b32_e32 v72, v123
	v_mul_f32_e32 v72, v82, v72
	v_mul_f32_e32 v74, 0x3fb8aa3b, v72
	v_fma_f32 v75, v72, s2, -v74
	v_rndne_f32_e32 v76, v74
	v_fmac_f32_e32 v75, 0x32a5705f, v72
	v_sub_f32_e32 v74, v74, v76
	v_add_f32_e32 v74, v74, v75
	v_exp_f32_e32 v74, v74
	v_cvt_i32_f32_e32 v75, v76
	v_cmp_ngt_f32_e32 vcc, s3, v72
	v_ldexp_f32 v74, v74, v75
	s_nop 0
	v_cndmask_b32_e32 v74, 0, v74, vcc
	v_cmp_nlt_f32_e32 vcc, s10, v72
	s_nop 1
	v_cndmask_b32_e32 v72, v247, v74, vcc
	v_mul_f32_e32 v74, v73, v72
	v_lshl_add_u64 v[72:73], v[80:81], 0, v[28:29]
	global_store_dword v[72:73], v74, off
	v_mov_b32_e32 v72, v124
	v_mul_f32_e32 v72, v82, v72
	v_mul_f32_e32 v73, 0x3fb8aa3b, v72
	v_fma_f32 v74, v72, s2, -v73
; __device__ __forceinline__ void hyena_raw4(const Args& a, int L, int t0, LAS float* scr, int lane) {
;     ...
;     for (int p = 0; p < 4; ++p) {
;         const float tl = (float)(t0 + p) * (1.0f / 2047.0f);
;         float* raw = (float*)(a.ws + WS_HRAW) + ((size_t)L * 2048 + t0 + p) * 1024;
; #pragma unroll
;         for (int mth = 0; mth < 16; ++mth) { const int idx = lane + 64 * mth; raw[idx] = o[p][mth] * expf(-tl * dec[idx]); }
	v_rndne_f32_e32 v75, v73
	v_fmac_f32_e32 v74, 0x32a5705f, v72
	v_sub_f32_e32 v73, v73, v75
	v_add_f32_e32 v73, v73, v74
	v_exp_f32_e32 v73, v73
	v_cvt_i32_f32_e32 v74, v75
	v_cmp_ngt_f32_e32 vcc, s3, v72
	v_ldexp_f32 v73, v73, v74
	s_nop 0
	v_cndmask_b32_e32 v73, 0, v73, vcc
	v_cmp_nlt_f32_e32 vcc, s10, v72
	s_nop 1
	v_cndmask_b32_e32 v72, v247, v73, vcc
	v_mul_f32_e32 v68, v68, v72
	v_lshl_add_u64 v[72:73], v[80:81], 0, v[30:31]
	global_store_dword v[72:73], v68, off
	v_mov_b32_e32 v68, v125
	v_mul_f32_e32 v68, v82, v68
	v_mul_f32_e32 v72, 0x3fb8aa3b, v68
	v_fma_f32 v73, v68, s2, -v72
	v_rndne_f32_e32 v74, v72
	v_fmac_f32_e32 v73, 0x32a5705f, v68
	v_sub_f32_e32 v72, v72, v74
	v_add_f32_e32 v72, v72, v73
	v_exp_f32_e32 v72, v72
	v_cvt_i32_f32_e32 v73, v74
	v_cmp_ngt_f32_e32 vcc, s3, v68
	v_ldexp_f32 v72, v72, v73
	s_nop 0
	v_cndmask_b32_e32 v72, 0, v72, vcc
	v_cmp_nlt_f32_e32 vcc, s10, v68
	s_nop 1
	v_cndmask_b32_e32 v68, v247, v72, vcc
	v_mul_f32_e32 v72, v69, v68
	v_lshl_add_u64 v[68:69], v[80:81], 0, v[32:33]
	global_store_dword v[68:69], v72, off
	v_mov_b32_e32 v68, v126
	v_mul_f32_e32 v68, v82, v68
	v_mul_f32_e32 v69, 0x3fb8aa3b, v68
	v_fma_f32 v72, v68, s2, -v69
	v_rndne_f32_e32 v73, v69
	v_fmac_f32_e32 v72, 0x32a5705f, v68
	v_sub_f32_e32 v69, v69, v73
	v_add_f32_e32 v69, v69, v72
	v_exp_f32_e32 v69, v69
	v_cvt_i32_f32_e32 v72, v73
	v_cmp_ngt_f32_e32 vcc, s3, v68
	v_ldexp_f32 v69, v69, v72
	s_nop 0
	v_cndmask_b32_e32 v69, 0, v69, vcc
	v_cmp_nlt_f32_e32 vcc, s10, v68
	s_nop 1
	v_cndmask_b32_e32 v68, v247, v69, vcc
	v_mul_f32_e32 v66, v66, v68
	v_lshl_add_u64 v[68:69], v[80:81], 0, v[34:35]
	global_store_dword v[68:69], v66, off
	v_mov_b32_e32 v66, v127
	v_mul_f32_e32 v66, v82, v66
	v_mul_f32_e32 v68, 0x3fb8aa3b, v66
	v_fma_f32 v69, v66, s2, -v68
	v_rndne_f32_e32 v72, v68
	v_fmac_f32_e32 v69, 0x32a5705f, v66
	v_sub_f32_e32 v68, v68, v72
	v_add_f32_e32 v68, v68, v69
	v_exp_f32_e32 v68, v68
	v_cvt_i32_f32_e32 v69, v72
	v_cmp_ngt_f32_e32 vcc, s3, v66
	v_ldexp_f32 v68, v68, v69
	s_nop 0
	v_cndmask_b32_e32 v68, 0, v68, vcc
	v_cmp_nlt_f32_e32 vcc, s10, v66
	s_nop 1
	v_cndmask_b32_e32 v66, v247, v68, vcc
	v_mul_f32_e32 v68, v67, v66
	v_lshl_add_u64 v[66:67], v[80:81], 0, v[36:37]
	global_store_dword v[66:67], v68, off
	v_mov_b32_e32 v66, v128
	v_mul_f32_e32 v66, v82, v66
	v_mul_f32_e32 v67, 0x3fb8aa3b, v66
	v_fma_f32 v68, v66, s2, -v67
	v_rndne_f32_e32 v69, v67
	v_fmac_f32_e32 v68, 0x32a5705f, v66
	v_sub_f32_e32 v67, v67, v69
	v_add_f32_e32 v67, v67, v68
	v_exp_f32_e32 v67, v67
	v_cvt_i32_f32_e32 v68, v69
	v_cmp_ngt_f32_e32 vcc, s3, v66
	v_ldexp_f32 v67, v67, v68
	s_nop 0
	v_cndmask_b32_e32 v67, 0, v67, vcc
	v_cmp_nlt_f32_e32 vcc, s10, v66
	s_nop 1
	v_cndmask_b32_e32 v66, v247, v67, vcc
	v_mul_f32_e32 v64, v64, v66
	v_lshl_add_u64 v[66:67], v[80:81], 0, v[38:39]
	global_store_dword v[66:67], v64, off
	v_mov_b32_e32 v64, v129
	v_mul_f32_e32 v64, v82, v64
	v_mul_f32_e32 v66, 0x3fb8aa3b, v64
	v_fma_f32 v67, v64, s2, -v66
	v_rndne_f32_e32 v68, v66
	v_fmac_f32_e32 v67, 0x32a5705f, v64
	v_sub_f32_e32 v66, v66, v68
	v_add_f32_e32 v66, v66, v67
	v_exp_f32_e32 v66, v66
	v_cvt_i32_f32_e32 v67, v68
	v_cmp_ngt_f32_e32 vcc, s3, v64
	v_ldexp_f32 v66, v66, v67
	s_nop 0
	v_cndmask_b32_e32 v66, 0, v66, vcc
	v_cmp_nlt_f32_e32 vcc, s10, v64
	s_nop 1
	v_cndmask_b32_e32 v64, v247, v66, vcc
	v_mul_f32_e32 v66, v65, v64
	v_lshl_add_u64 v[64:65], v[80:81], 0, v[40:41]
	global_store_dword v[64:65], v66, off
	v_mov_b32_e32 v64, v130
	v_mul_f32_e32 v64, v82, v64
	v_mul_f32_e32 v65, 0x3fb8aa3b, v64
	v_fma_f32 v66, v64, s2, -v65
	v_rndne_f32_e32 v67, v65
	v_fmac_f32_e32 v66, 0x32a5705f, v64
	v_sub_f32_e32 v65, v65, v67
	v_add_f32_e32 v65, v65, v66
	v_exp_f32_e32 v65, v65
	v_cvt_i32_f32_e32 v66, v67
	v_cmp_ngt_f32_e32 vcc, s3, v64
	v_ldexp_f32 v65, v65, v66
	s_nop 0
	v_cndmask_b32_e32 v65, 0, v65, vcc
	v_cmp_nlt_f32_e32 vcc, s10, v64
	s_nop 1
	v_cndmask_b32_e32 v64, v247, v65, vcc
	v_mul_f32_e32 v62, v62, v64
	v_lshl_add_u64 v[64:65], v[80:81], 0, v[42:43]
	global_store_dword v[64:65], v62, off
	v_mov_b32_e32 v62, v131
	v_mul_f32_e32 v62, v82, v62
	v_mul_f32_e32 v64, 0x3fb8aa3b, v62
	v_fma_f32 v65, v62, s2, -v64
	v_rndne_f32_e32 v66, v64
	v_fmac_f32_e32 v65, 0x32a5705f, v62
	v_sub_f32_e32 v64, v64, v66
	v_add_f32_e32 v64, v64, v65
	v_exp_f32_e32 v64, v64
	v_cvt_i32_f32_e32 v65, v66
	v_cmp_ngt_f32_e32 vcc, s3, v62
	v_ldexp_f32 v64, v64, v65
	s_nop 0
	v_cndmask_b32_e32 v64, 0, v64, vcc
	v_cmp_nlt_f32_e32 vcc, s10, v62
	s_nop 1
	v_cndmask_b32_e32 v62, v247, v64, vcc
	v_mul_f32_e32 v64, v63, v62
	v_lshl_add_u64 v[62:63], v[80:81], 0, v[44:45]
	global_store_dword v[62:63], v64, off
	v_mov_b32_e32 v65, v116
	v_or_b32_e32 v62, 3, v206
	v_cvt_f32_u32_e32 v64, v62
	v_lshl_add_u64 v[62:63], v[86:87], 0, s[0:1]
	s_movk_i32 s0, 0x3ff
	v_mul_f32_e32 v64, 0xba001002, v64
	v_mul_f32_e32 v65, v64, v65
	v_mul_f32_e32 v66, 0x3fb8aa3b, v65
	v_fma_f32 v67, v65, s2, -v66
	v_rndne_f32_e32 v68, v66
	v_fmac_f32_e32 v67, 0x32a5705f, v65
	v_sub_f32_e32 v66, v66, v68
	v_add_f32_e32 v66, v66, v67
	v_exp_f32_e32 v66, v66
	v_cvt_i32_f32_e32 v67, v68
	v_cmp_ngt_f32_e32 vcc, s3, v65
	v_ldexp_f32 v66, v66, v67
	s_nop 0
	v_cndmask_b32_e32 v66, 0, v66, vcc
	v_cmp_nlt_f32_e32 vcc, s10, v65
	s_nop 1
	v_cndmask_b32_e32 v65, v247, v66, vcc
	v_mul_f32_e32 v60, v60, v65
	v_lshl_add_u64 v[66:67], v[62:63], 0, v[14:15]
	global_store_dword v[66:67], v60, off
	v_mov_b32_e32 v15, v117
	v_mul_f32_e32 v15, v64, v15
	v_mul_f32_e32 v60, 0x3fb8aa3b, v15
	v_fma_f32 v65, v15, s2, -v60
	v_rndne_f32_e32 v66, v60
	v_fmac_f32_e32 v65, 0x32a5705f, v15
	v_sub_f32_e32 v60, v60, v66
	v_add_f32_e32 v60, v60, v65
	v_exp_f32_e32 v60, v60
; __device__ __forceinline__ void hyena_raw4(const Args& a, int L, int t0, LAS float* scr, int lane) {
;     ...
;         for (int mth = 0; mth < 16; ++mth) { const int idx = lane + 64 * mth; raw[idx] = o[p][mth] * expf(-tl * dec[idx]); }
	v_cvt_i32_f32_e32 v65, v66
	v_cmp_ngt_f32_e32 vcc, s3, v15
	v_ldexp_f32 v60, v60, v65
	s_nop 0
	v_cndmask_b32_e32 v60, 0, v60, vcc
	v_cmp_nlt_f32_e32 vcc, s10, v15
	s_nop 1
	v_cndmask_b32_e32 v15, v247, v60, vcc
	v_mul_f32_e32 v15, v61, v15
	v_lshl_add_u64 v[60:61], v[62:63], 0, v[16:17]
	global_store_dword v[60:61], v15, off
	v_mov_b32_e32 v15, v118
	v_mul_f32_e32 v15, v64, v15
	v_mul_f32_e32 v17, 0x3fb8aa3b, v15
	v_fma_f32 v60, v15, s2, -v17
	v_rndne_f32_e32 v61, v17
	v_fmac_f32_e32 v60, 0x32a5705f, v15
	v_sub_f32_e32 v17, v17, v61
	v_add_f32_e32 v17, v17, v60
	v_exp_f32_e32 v17, v17
	v_cvt_i32_f32_e32 v60, v61
	v_cmp_ngt_f32_e32 vcc, s3, v15
	v_ldexp_f32 v17, v17, v60
	s_nop 0
	v_cndmask_b32_e32 v17, 0, v17, vcc
	v_cmp_nlt_f32_e32 vcc, s10, v15
	v_lshl_add_u64 v[60:61], v[62:63], 0, v[18:19]
	s_nop 0
	v_cndmask_b32_e32 v15, v247, v17, vcc
	v_mul_f32_e32 v15, v58, v15
	global_store_dword v[60:61], v15, off
	v_mov_b32_e32 v15, v119
	v_mul_f32_e32 v15, v64, v15
	v_mul_f32_e32 v17, 0x3fb8aa3b, v15
	v_fma_f32 v19, v15, s2, -v17
	v_rndne_f32_e32 v58, v17
	v_fmac_f32_e32 v19, 0x32a5705f, v15
	v_sub_f32_e32 v17, v17, v58
	v_add_f32_e32 v17, v17, v19
	v_exp_f32_e32 v17, v17
	v_cvt_i32_f32_e32 v19, v58
	v_cmp_ngt_f32_e32 vcc, s3, v15
	v_ldexp_f32 v17, v17, v19
	s_nop 0
	v_cndmask_b32_e32 v17, 0, v17, vcc
	v_cmp_nlt_f32_e32 vcc, s10, v15
	s_nop 1
	v_cndmask_b32_e32 v15, v247, v17, vcc
	v_mul_f32_e32 v15, v59, v15
	v_lshl_add_u64 v[58:59], v[62:63], 0, v[20:21]
	global_store_dword v[58:59], v15, off
	v_mov_b32_e32 v15, v120
	v_lshl_add_u64 v[58:59], v[62:63], 0, v[22:23]
	v_mul_f32_e32 v15, v64, v15
	v_mul_f32_e32 v17, 0x3fb8aa3b, v15
	v_fma_f32 v19, v15, s2, -v17
	v_rndne_f32_e32 v21, v17
	v_fmac_f32_e32 v19, 0x32a5705f, v15
	v_sub_f32_e32 v17, v17, v21
	v_add_f32_e32 v17, v17, v19
	v_exp_f32_e32 v17, v17
	v_cvt_i32_f32_e32 v19, v21
	v_cmp_ngt_f32_e32 vcc, s3, v15
	v_ldexp_f32 v17, v17, v19
	s_nop 0
	v_cndmask_b32_e32 v17, 0, v17, vcc
	v_cmp_nlt_f32_e32 vcc, s10, v15
	s_nop 1
	v_cndmask_b32_e32 v15, v247, v17, vcc
	v_mul_f32_e32 v15, v56, v15
	global_store_dword v[58:59], v15, off
	v_mov_b32_e32 v15, v121
	v_mul_f32_e32 v15, v64, v15
	v_mul_f32_e32 v17, 0x3fb8aa3b, v15
	v_fma_f32 v19, v15, s2, -v17
	v_rndne_f32_e32 v21, v17
	v_fmac_f32_e32 v19, 0x32a5705f, v15
	v_sub_f32_e32 v17, v17, v21
	v_add_f32_e32 v17, v17, v19
	v_exp_f32_e32 v17, v17
	v_cvt_i32_f32_e32 v19, v21
	v_cmp_ngt_f32_e32 vcc, s3, v15
	v_ldexp_f32 v17, v17, v19
	s_nop 0
	v_cndmask_b32_e32 v17, 0, v17, vcc
	v_cmp_nlt_f32_e32 vcc, s10, v15
	s_nop 1
	v_cndmask_b32_e32 v15, v247, v17, vcc
	v_mul_f32_e32 v15, v57, v15
	v_lshl_add_u64 v[56:57], v[62:63], 0, v[24:25]
	global_store_dword v[56:57], v15, off
	v_mov_b32_e32 v15, v122
	v_lshl_add_u64 v[56:57], v[62:63], 0, v[26:27]
	v_mul_f32_e32 v15, v64, v15
	v_mul_f32_e32 v17, 0x3fb8aa3b, v15
	v_fma_f32 v19, v15, s2, -v17
	v_rndne_f32_e32 v21, v17
	v_fmac_f32_e32 v19, 0x32a5705f, v15
	v_sub_f32_e32 v17, v17, v21
	v_add_f32_e32 v17, v17, v19
	v_exp_f32_e32 v17, v17
	v_cvt_i32_f32_e32 v19, v21
	v_cmp_ngt_f32_e32 vcc, s3, v15
	v_ldexp_f32 v17, v17, v19
	s_nop 0
	v_cndmask_b32_e32 v17, 0, v17, vcc
	v_cmp_nlt_f32_e32 vcc, s10, v15
	s_nop 1
	v_cndmask_b32_e32 v15, v247, v17, vcc
	v_mul_f32_e32 v15, v54, v15
	global_store_dword v[56:57], v15, off
	v_mov_b32_e32 v15, v123
	v_mul_f32_e32 v15, v64, v15
	v_mul_f32_e32 v17, 0x3fb8aa3b, v15
	v_fma_f32 v19, v15, s2, -v17
	v_rndne_f32_e32 v21, v17
	v_fmac_f32_e32 v19, 0x32a5705f, v15
	v_sub_f32_e32 v17, v17, v21
	v_add_f32_e32 v17, v17, v19
	v_exp_f32_e32 v17, v17
	v_cvt_i32_f32_e32 v19, v21
	v_cmp_ngt_f32_e32 vcc, s3, v15
	v_ldexp_f32 v17, v17, v19
	s_nop 0
	v_cndmask_b32_e32 v17, 0, v17, vcc
	v_cmp_nlt_f32_e32 vcc, s10, v15
	s_nop 1
	v_cndmask_b32_e32 v15, v247, v17, vcc
	v_mul_f32_e32 v15, v55, v15
	v_lshl_add_u64 v[54:55], v[62:63], 0, v[28:29]
	global_store_dword v[54:55], v15, off
	v_mov_b32_e32 v15, v124
	v_lshl_add_u64 v[54:55], v[62:63], 0, v[30:31]
	v_mul_f32_e32 v15, v64, v15
	v_mul_f32_e32 v17, 0x3fb8aa3b, v15
	v_fma_f32 v19, v15, s2, -v17
	v_rndne_f32_e32 v21, v17
	v_fmac_f32_e32 v19, 0x32a5705f, v15
	v_sub_f32_e32 v17, v17, v21
	v_add_f32_e32 v17, v17, v19
	v_exp_f32_e32 v17, v17
	v_cvt_i32_f32_e32 v19, v21
	v_cmp_ngt_f32_e32 vcc, s3, v15
	v_ldexp_f32 v17, v17, v19
	s_nop 0
	v_cndmask_b32_e32 v17, 0, v17, vcc
	v_cmp_nlt_f32_e32 vcc, s10, v15
	s_nop 1
; __device__ __forceinline__ void hyena_raw4(const Args& a, int L, int t0, LAS float* scr, int lane) {
;     ...
;         for (int mth = 0; mth < 16; ++mth) { const int idx = lane + 64 * mth; raw[idx] = o[p][mth] * expf(-tl * dec[idx]); }
; __device__ __forceinline__ void phase0(const Args& a, LAS unsigned char* lds) {
;     ...
;     for (int it = gw; it < 2 * 512; it += NGW) hyena_raw4(a, it >> 9, (it & 511) * 4, scr, lane);
	v_cndmask_b32_e32 v15, v247, v17, vcc
	v_mul_f32_e32 v15, v52, v15
	global_store_dword v[54:55], v15, off
	v_mov_b32_e32 v15, v125
	v_mul_f32_e32 v15, v64, v15
	v_mul_f32_e32 v17, 0x3fb8aa3b, v15
	v_fma_f32 v19, v15, s2, -v17
	v_rndne_f32_e32 v21, v17
	v_fmac_f32_e32 v19, 0x32a5705f, v15
	v_sub_f32_e32 v17, v17, v21
	v_add_f32_e32 v17, v17, v19
	v_exp_f32_e32 v17, v17
	v_cvt_i32_f32_e32 v19, v21
	v_cmp_ngt_f32_e32 vcc, s3, v15
	v_ldexp_f32 v17, v17, v19
	s_nop 0
	v_cndmask_b32_e32 v17, 0, v17, vcc
	v_cmp_nlt_f32_e32 vcc, s10, v15
	s_nop 1
	v_cndmask_b32_e32 v15, v247, v17, vcc
	v_mul_f32_e32 v15, v53, v15
	v_lshl_add_u64 v[52:53], v[62:63], 0, v[32:33]
	global_store_dword v[52:53], v15, off
	v_mov_b32_e32 v15, v126
	v_lshl_add_u64 v[52:53], v[62:63], 0, v[34:35]
	v_mul_f32_e32 v15, v64, v15
	v_mul_f32_e32 v17, 0x3fb8aa3b, v15
	v_fma_f32 v19, v15, s2, -v17
	v_rndne_f32_e32 v21, v17
	v_fmac_f32_e32 v19, 0x32a5705f, v15
	v_sub_f32_e32 v17, v17, v21
	v_add_f32_e32 v17, v17, v19
	v_exp_f32_e32 v17, v17
	v_cvt_i32_f32_e32 v19, v21
	v_cmp_ngt_f32_e32 vcc, s3, v15
	v_ldexp_f32 v17, v17, v19
	s_nop 0
	v_cndmask_b32_e32 v17, 0, v17, vcc
	v_cmp_nlt_f32_e32 vcc, s10, v15
	s_nop 1
	v_cndmask_b32_e32 v15, v247, v17, vcc
	v_mul_f32_e32 v15, v50, v15
	global_store_dword v[52:53], v15, off
	v_mov_b32_e32 v15, v127
	v_mul_f32_e32 v15, v64, v15
	v_mul_f32_e32 v17, 0x3fb8aa3b, v15
	v_fma_f32 v19, v15, s2, -v17
	v_rndne_f32_e32 v21, v17
	v_fmac_f32_e32 v19, 0x32a5705f, v15
	v_sub_f32_e32 v17, v17, v21
	v_add_f32_e32 v17, v17, v19
	v_exp_f32_e32 v17, v17
	v_cvt_i32_f32_e32 v19, v21
	v_cmp_ngt_f32_e32 vcc, s3, v15
	v_ldexp_f32 v17, v17, v19
	s_nop 0
	v_cndmask_b32_e32 v17, 0, v17, vcc
	v_cmp_nlt_f32_e32 vcc, s10, v15
	s_nop 1
	v_cndmask_b32_e32 v15, v247, v17, vcc
	v_mul_f32_e32 v15, v51, v15
	v_lshl_add_u64 v[50:51], v[62:63], 0, v[36:37]
	global_store_dword v[50:51], v15, off
	v_mov_b32_e32 v15, v128
	v_lshl_add_u64 v[50:51], v[62:63], 0, v[38:39]
	v_mul_f32_e32 v15, v64, v15
	v_mul_f32_e32 v17, 0x3fb8aa3b, v15
	v_fma_f32 v19, v15, s2, -v17
	v_rndne_f32_e32 v21, v17
	v_fmac_f32_e32 v19, 0x32a5705f, v15
	v_sub_f32_e32 v17, v17, v21
	v_add_f32_e32 v17, v17, v19
	v_exp_f32_e32 v17, v17
	v_cvt_i32_f32_e32 v19, v21
	v_cmp_ngt_f32_e32 vcc, s3, v15
	v_ldexp_f32 v17, v17, v19
	s_nop 0
	v_cndmask_b32_e32 v17, 0, v17, vcc
	v_cmp_nlt_f32_e32 vcc, s10, v15
	s_nop 1
	v_cndmask_b32_e32 v15, v247, v17, vcc
	v_mul_f32_e32 v15, v48, v15
	global_store_dword v[50:51], v15, off
	v_mov_b32_e32 v15, v129
	v_mul_f32_e32 v15, v64, v15
	v_mul_f32_e32 v17, 0x3fb8aa3b, v15
	v_fma_f32 v19, v15, s2, -v17
	v_rndne_f32_e32 v21, v17
	v_fmac_f32_e32 v19, 0x32a5705f, v15
	v_sub_f32_e32 v17, v17, v21
	v_add_f32_e32 v17, v17, v19
	v_exp_f32_e32 v17, v17
	v_cvt_i32_f32_e32 v19, v21
	v_cmp_ngt_f32_e32 vcc, s3, v15
	v_ldexp_f32 v17, v17, v19
	s_nop 0
	v_cndmask_b32_e32 v17, 0, v17, vcc
	v_cmp_nlt_f32_e32 vcc, s10, v15
	s_nop 1
	v_cndmask_b32_e32 v15, v247, v17, vcc
	v_mul_f32_e32 v15, v49, v15
	v_lshl_add_u64 v[48:49], v[62:63], 0, v[40:41]
	global_store_dword v[48:49], v15, off
	v_mov_b32_e32 v15, v130
	v_lshl_add_u64 v[48:49], v[62:63], 0, v[42:43]
	v_mul_f32_e32 v15, v64, v15
	v_mul_f32_e32 v17, 0x3fb8aa3b, v15
	v_fma_f32 v19, v15, s2, -v17
	v_rndne_f32_e32 v21, v17
	v_fmac_f32_e32 v19, 0x32a5705f, v15
	v_sub_f32_e32 v17, v17, v21
	v_add_f32_e32 v17, v17, v19
	v_exp_f32_e32 v17, v17
	v_cvt_i32_f32_e32 v19, v21
	v_cmp_ngt_f32_e32 vcc, s3, v15
	v_ldexp_f32 v17, v17, v19
	s_nop 0
	v_cndmask_b32_e32 v17, 0, v17, vcc
	v_cmp_nlt_f32_e32 vcc, s10, v15
	s_nop 1
	v_cndmask_b32_e32 v15, v247, v17, vcc
	v_mul_f32_e32 v15, v46, v15
	global_store_dword v[48:49], v15, off
	v_mov_b32_e32 v15, v131
	v_mul_f32_e32 v15, v64, v15
	v_mul_f32_e32 v17, 0x3fb8aa3b, v15
	v_fma_f32 v19, v15, s2, -v17
	v_rndne_f32_e32 v21, v17
	v_fmac_f32_e32 v19, 0x32a5705f, v15
	v_sub_f32_e32 v17, v17, v21
	v_add_f32_e32 v17, v17, v19
	v_exp_f32_e32 v17, v17
	v_cvt_i32_f32_e32 v19, v21
	v_cmp_ngt_f32_e32 vcc, s3, v15
	v_ldexp_f32 v17, v17, v19
	s_nop 0
	v_cndmask_b32_e32 v17, 0, v17, vcc
	v_cmp_nlt_f32_e32 vcc, s10, v15
	s_nop 1
	v_cndmask_b32_e32 v15, v247, v17, vcc
	v_mul_f32_e32 v15, v47, v15
	v_lshl_add_u64 v[46:47], v[62:63], 0, v[44:45]
	global_store_dword v[46:47], v15, off
	s_waitcnt lgkmcnt(0)
	v_cmp_lt_i32_e32 vcc, s0, v205
	s_or_b64 s[18:19], vcc, s[18:19]
	s_andn2_b64 exec, exec, s[18:19]
	s_cbranch_execnz .LBB0_385
